# v51 + loop-carried SALU rotated above the final K-loop barrier + m0 hazard pads replaced by reordering (exact loader-path trims)
# baseline (speedup 1.0000x reference)
.LBB0_142:
	ds_read_b128 v[168:171], v165
	ds_read_b128 v[172:175], v165 offset:1024
	ds_read_b128 v[176:179], v165 offset:2048
	ds_read_b128 v[180:183], v165 offset:3072
	ds_read_b128 v[184:187], v166
	ds_read_b128 v[188:191], v166 offset:1024
	ds_read_b128 v[192:195], v166 offset:2048
	ds_read_b128 v[196:199], v166 offset:3072
	s_add_i32 s54, s22, 2
	s_add_u32 s55, s20, 0x80
	s_addc_u32 s23, s21, 0
	s_cmp_eq_u32 s42, s22
	s_cselect_b32 s22, s4, s55
	s_cselect_b32 s23, s5, s23
	s_cselect_b32 s61, s19, s53
	s_cselect_b32 s60, s18, s52
	v_lshl_add_u64 v[234:235], s[20:21], 0, v[154:155]
	s_add_i32 m0, s31, 0xc000
	ds_read_b128 v[200:203], v167
	ds_read_b128 v[204:207], v167 offset:1024
	ds_read_b128 v[208:211], v167 offset:2048
	ds_read_b128 v[212:215], v167 offset:3072
	ds_read_b128 v[216:219], v167 offset:4096
	ds_read_b128 v[222:225], v167 offset:5120
	ds_read_b128 v[226:229], v167 offset:6144
	ds_read_b128 v[230:233], v167 offset:7168
	global_load_lds_dwordx4 v[234:235], off
	s_add_i32 m0, s31, 0xe000
	v_lshl_add_u64 v[234:235], s[20:21], 0, v[156:157]
	global_load_lds_dwordx4 v[234:235], off
	s_waitcnt vmcnt(8)
	s_waitcnt lgkmcnt(0)
	s_barrier
	s_waitcnt lgkmcnt(0)
	v_mfma_f32_16x16x32_bf16 v[120:123], v[168:171], v[200:203], v[120:123]
	v_mfma_f32_16x16x32_bf16 v[120:123], v[172:175], v[204:207], v[120:123]
	v_mfma_f32_16x16x32_bf16 v[116:119], v[180:183], v[204:207], v[116:119]
	v_mfma_f32_16x16x32_bf16 v[116:119], v[176:179], v[200:203], v[116:119]
	v_mfma_f32_16x16x32_bf16 v[124:127], v[184:187], v[200:203], v[124:127]
	v_mfma_f32_16x16x32_bf16 v[124:127], v[188:191], v[204:207], v[124:127]
	v_mfma_f32_16x16x32_bf16 v[112:115], v[196:199], v[204:207], v[112:115]
	v_mfma_f32_16x16x32_bf16 v[112:115], v[192:195], v[200:203], v[112:115]
	v_mfma_f32_16x16x32_bf16 v[96:99], v[192:195], v[208:211], v[96:99]
	v_mfma_f32_16x16x32_bf16 v[96:99], v[196:199], v[212:215], v[96:99]
	v_mfma_f32_16x16x32_bf16 v[104:107], v[188:191], v[212:215], v[104:107]
	v_mfma_f32_16x16x32_bf16 v[104:107], v[184:187], v[208:211], v[104:107]
	v_mfma_f32_16x16x32_bf16 v[100:103], v[176:179], v[208:211], v[100:103]
	v_mfma_f32_16x16x32_bf16 v[100:103], v[180:183], v[212:215], v[100:103]
	v_mfma_f32_16x16x32_bf16 v[108:111], v[172:175], v[212:215], v[108:111]
	v_mfma_f32_16x16x32_bf16 v[108:111], v[168:171], v[208:211], v[108:111]
	v_mfma_f32_16x16x32_bf16 v[92:95], v[168:171], v[216:219], v[92:95]
	v_mfma_f32_16x16x32_bf16 v[92:95], v[172:175], v[222:225], v[92:95]
	v_mfma_f32_16x16x32_bf16 v[84:87], v[180:183], v[222:225], v[84:87]
	v_mfma_f32_16x16x32_bf16 v[84:87], v[176:179], v[216:219], v[84:87]
	v_mfma_f32_16x16x32_bf16 v[88:91], v[184:187], v[216:219], v[88:91]
	v_mfma_f32_16x16x32_bf16 v[88:91], v[188:191], v[222:225], v[88:91]
	v_mfma_f32_16x16x32_bf16 v[80:83], v[196:199], v[222:225], v[80:83]
	v_mfma_f32_16x16x32_bf16 v[80:83], v[192:195], v[216:219], v[80:83]
	v_mfma_f32_16x16x32_bf16 v[64:67], v[192:195], v[226:229], v[64:67]
	v_mfma_f32_16x16x32_bf16 v[64:67], v[196:199], v[230:233], v[64:67]
	v_mfma_f32_16x16x32_bf16 v[72:75], v[188:191], v[230:233], v[72:75]
	v_mfma_f32_16x16x32_bf16 v[72:75], v[184:187], v[226:229], v[72:75]
	v_mfma_f32_16x16x32_bf16 v[68:71], v[176:179], v[226:229], v[68:71]
	v_mfma_f32_16x16x32_bf16 v[68:71], v[180:183], v[230:233], v[68:71]
	v_mfma_f32_16x16x32_bf16 v[76:79], v[172:175], v[230:233], v[76:79]
	v_mfma_f32_16x16x32_bf16 v[76:79], v[168:171], v[226:229], v[76:79]
	s_barrier
	s_add_i32 s55, s46, s28
	v_lshl_add_u64 v[234:235], s[60:61], 0, v[132:133]
	s_mov_b32 m0, s55
	ds_read_b128 v[200:203], v167 offset:16384
	ds_read_b128 v[204:207], v167 offset:17408
	ds_read_b128 v[208:211], v167 offset:18432
	ds_read_b128 v[212:215], v167 offset:19456
	ds_read_b128 v[216:219], v167 offset:20480
	ds_read_b128 v[222:225], v167 offset:21504
	ds_read_b128 v[226:229], v167 offset:22528
	ds_read_b128 v[230:233], v167 offset:23552
	global_load_lds_dwordx4 v[234:235], off
	s_add_i32 m0, s55, 0x2000
	v_lshl_add_u64 v[236:237], s[60:61], 0, v[128:129]
	s_add_u32 s60, s60, s10
	s_addc_u32 s61, s61, s11
	s_add_i32 s55, s47, s28
	global_load_lds_dwordx4 v[236:237], off
	v_lshl_add_u64 v[238:239], s[60:61], 0, v[132:133]
	s_mov_b32 m0, s55
	v_lshl_add_u64 v[240:241], s[60:61], 0, v[128:129]
	global_load_lds_dwordx4 v[238:239], off
	s_add_i32 m0, s55, 0x2000
	v_lshl_add_u64 v[242:243], s[22:23], 0, v[134:135]
	global_load_lds_dwordx4 v[240:241], off
	s_mov_b32 m0, s31
	v_lshl_add_u64 v[244:245], s[22:23], 0, v[130:131]
	global_load_lds_dwordx4 v[242:243], off
	s_mov_b32 m0, s33
	s_nop 0
	global_load_lds_dwordx4 v[244:245], off
	s_waitcnt vmcnt(8)
	s_waitcnt lgkmcnt(0)
	s_barrier
	s_waitcnt lgkmcnt(0)
	v_mfma_f32_16x16x32_bf16 v[60:63], v[168:171], v[200:203], v[60:63]
	v_mfma_f32_16x16x32_bf16 v[60:63], v[172:175], v[204:207], v[60:63]
	v_mfma_f32_16x16x32_bf16 v[52:55], v[180:183], v[204:207], v[52:55]
	v_mfma_f32_16x16x32_bf16 v[52:55], v[176:179], v[200:203], v[52:55]
	v_mfma_f32_16x16x32_bf16 v[56:59], v[184:187], v[200:203], v[56:59]
	v_mfma_f32_16x16x32_bf16 v[56:59], v[188:191], v[204:207], v[56:59]
	v_mfma_f32_16x16x32_bf16 v[48:51], v[196:199], v[204:207], v[48:51]
	v_mfma_f32_16x16x32_bf16 v[48:51], v[192:195], v[200:203], v[48:51]
	v_mfma_f32_16x16x32_bf16 v[32:35], v[192:195], v[208:211], v[32:35]
	v_mfma_f32_16x16x32_bf16 v[32:35], v[196:199], v[212:215], v[32:35]
	v_mfma_f32_16x16x32_bf16 v[40:43], v[188:191], v[212:215], v[40:43]
	v_mfma_f32_16x16x32_bf16 v[40:43], v[184:187], v[208:211], v[40:43]
	v_mfma_f32_16x16x32_bf16 v[36:39], v[176:179], v[208:211], v[36:39]
	v_mfma_f32_16x16x32_bf16 v[36:39], v[180:183], v[212:215], v[36:39]
	v_mfma_f32_16x16x32_bf16 v[44:47], v[172:175], v[212:215], v[44:47]
	v_mfma_f32_16x16x32_bf16 v[44:47], v[168:171], v[208:211], v[44:47]
	v_mfma_f32_16x16x32_bf16 v[28:31], v[168:171], v[216:219], v[28:31]
	v_mfma_f32_16x16x32_bf16 v[28:31], v[172:175], v[222:225], v[28:31]
	v_mfma_f32_16x16x32_bf16 v[20:23], v[180:183], v[222:225], v[20:23]
	v_mfma_f32_16x16x32_bf16 v[20:23], v[176:179], v[216:219], v[20:23]
	v_mfma_f32_16x16x32_bf16 v[24:27], v[184:187], v[216:219], v[24:27]
	v_mfma_f32_16x16x32_bf16 v[24:27], v[188:191], v[222:225], v[24:27]
	v_mfma_f32_16x16x32_bf16 v[16:19], v[196:199], v[222:225], v[16:19]
	v_mfma_f32_16x16x32_bf16 v[16:19], v[192:195], v[216:219], v[16:19]
	v_mfma_f32_16x16x32_bf16 v[0:3], v[192:195], v[226:229], v[0:3]
	v_mfma_f32_16x16x32_bf16 v[0:3], v[196:199], v[230:233], v[0:3]
	v_mfma_f32_16x16x32_bf16 v[8:11], v[188:191], v[230:233], v[8:11]
	v_mfma_f32_16x16x32_bf16 v[8:11], v[184:187], v[226:229], v[8:11]
	v_mfma_f32_16x16x32_bf16 v[4:7], v[176:179], v[226:229], v[4:7]
	v_mfma_f32_16x16x32_bf16 v[4:7], v[180:183], v[230:233], v[4:7]
	v_mfma_f32_16x16x32_bf16 v[12:15], v[172:175], v[230:233], v[12:15]
	v_mfma_f32_16x16x32_bf16 v[12:15], v[168:171], v[226:229], v[12:15]
	s_barrier
	s_add_i32 s55, 0, 0x18000
	s_add_i32 s60, 0, 0x1c000
	v_add_u32_e32 v180, s55, v164
	v_add_u32_e32 v196, s60, v164
	ds_read_b128 v[168:171], v180
	ds_read_b128 v[172:175], v180 offset:1024
	ds_read_b128 v[176:179], v180 offset:2048
	ds_read_b128 v[180:183], v180 offset:3072
	ds_read_b128 v[184:187], v196
	ds_read_b128 v[188:191], v196 offset:1024
	ds_read_b128 v[192:195], v196 offset:2048
	ds_read_b128 v[196:199], v196 offset:3072
	s_add_u32 s22, s22, s10
	s_addc_u32 s23, s23, s11
	s_mov_b32 m0, s34
	v_lshl_add_u64 v[246:247], s[22:23], 0, v[134:135]
	ds_read_b128 v[200:203], v167 offset:32768
	ds_read_b128 v[204:207], v167 offset:33792
	ds_read_b128 v[208:211], v167 offset:34816
	ds_read_b128 v[212:215], v167 offset:35840
	ds_read_b128 v[216:219], v167 offset:36864
	ds_read_b128 v[222:225], v167 offset:37888
	ds_read_b128 v[226:229], v167 offset:38912
	ds_read_b128 v[230:233], v167 offset:39936
	global_load_lds_dwordx4 v[246:247], off
	s_mov_b32 m0, s35
	v_lshl_add_u64 v[246:247], s[22:23], 0, v[130:131]
	global_load_lds_dwordx4 v[246:247], off
	s_waitcnt vmcnt(8)
	s_waitcnt lgkmcnt(0)
	s_barrier
	s_waitcnt lgkmcnt(0)
	v_mfma_f32_16x16x32_bf16 v[120:123], v[168:171], v[200:203], v[120:123]
	v_mfma_f32_16x16x32_bf16 v[120:123], v[172:175], v[204:207], v[120:123]
	v_mfma_f32_16x16x32_bf16 v[116:119], v[180:183], v[204:207], v[116:119]
	v_mfma_f32_16x16x32_bf16 v[116:119], v[176:179], v[200:203], v[116:119]
	v_mfma_f32_16x16x32_bf16 v[124:127], v[184:187], v[200:203], v[124:127]
	v_mfma_f32_16x16x32_bf16 v[124:127], v[188:191], v[204:207], v[124:127]
	v_mfma_f32_16x16x32_bf16 v[112:115], v[196:199], v[204:207], v[112:115]
	v_mfma_f32_16x16x32_bf16 v[112:115], v[192:195], v[200:203], v[112:115]
	v_mfma_f32_16x16x32_bf16 v[96:99], v[192:195], v[208:211], v[96:99]
	v_mfma_f32_16x16x32_bf16 v[96:99], v[196:199], v[212:215], v[96:99]
	v_mfma_f32_16x16x32_bf16 v[104:107], v[188:191], v[212:215], v[104:107]
	v_mfma_f32_16x16x32_bf16 v[104:107], v[184:187], v[208:211], v[104:107]
	v_mfma_f32_16x16x32_bf16 v[100:103], v[176:179], v[208:211], v[100:103]
	v_mfma_f32_16x16x32_bf16 v[100:103], v[180:183], v[212:215], v[100:103]
	v_mfma_f32_16x16x32_bf16 v[108:111], v[172:175], v[212:215], v[108:111]
	v_mfma_f32_16x16x32_bf16 v[108:111], v[168:171], v[208:211], v[108:111]
	v_mfma_f32_16x16x32_bf16 v[92:95], v[168:171], v[216:219], v[92:95]
	v_mfma_f32_16x16x32_bf16 v[92:95], v[172:175], v[222:225], v[92:95]
	v_mfma_f32_16x16x32_bf16 v[84:87], v[180:183], v[222:225], v[84:87]
	v_mfma_f32_16x16x32_bf16 v[84:87], v[176:179], v[216:219], v[84:87]
	v_mfma_f32_16x16x32_bf16 v[88:91], v[184:187], v[216:219], v[88:91]
	v_mfma_f32_16x16x32_bf16 v[88:91], v[188:191], v[222:225], v[88:91]
	v_mfma_f32_16x16x32_bf16 v[80:83], v[196:199], v[222:225], v[80:83]
	v_mfma_f32_16x16x32_bf16 v[80:83], v[192:195], v[216:219], v[80:83]
	v_mfma_f32_16x16x32_bf16 v[64:67], v[192:195], v[226:229], v[64:67]
	v_mfma_f32_16x16x32_bf16 v[64:67], v[196:199], v[230:233], v[64:67]
	v_mfma_f32_16x16x32_bf16 v[72:75], v[188:191], v[230:233], v[72:75]
	v_mfma_f32_16x16x32_bf16 v[72:75], v[184:187], v[226:229], v[72:75]
	v_mfma_f32_16x16x32_bf16 v[68:71], v[176:179], v[226:229], v[68:71]
	v_mfma_f32_16x16x32_bf16 v[68:71], v[180:183], v[230:233], v[68:71]
	v_mfma_f32_16x16x32_bf16 v[76:79], v[172:175], v[230:233], v[76:79]
	v_mfma_f32_16x16x32_bf16 v[76:79], v[168:171], v[226:229], v[76:79]
	s_barrier
	s_add_i32 s22, s55, s28
	v_lshl_add_u64 v[234:235], v[234:235], 0, s[14:15]
	s_mov_b32 m0, s22
	ds_read_b128 v[200:203], v167 offset:49152
	ds_read_b128 v[204:207], v167 offset:50176
	ds_read_b128 v[208:211], v167 offset:51200
	ds_read_b128 v[212:215], v167 offset:52224
	ds_read_b128 v[216:219], v167 offset:53248
	ds_read_b128 v[222:225], v167 offset:54272
	ds_read_b128 v[226:229], v167 offset:55296
	ds_read_b128 v[230:233], v167 offset:56320
	global_load_lds_dwordx4 v[234:235], off
	v_lshl_add_u64 v[234:235], v[236:237], 0, s[14:15]
	s_add_i32 m0, s22, 0x2000
	s_add_i32 s22, s60, s28
	global_load_lds_dwordx4 v[234:235], off
	s_mov_b32 m0, s22
	v_lshl_add_u64 v[234:235], v[238:239], 0, s[14:15]
	global_load_lds_dwordx4 v[234:235], off
	s_add_i32 m0, s22, 0x2000
	v_lshl_add_u64 v[234:235], v[240:241], 0, s[14:15]
	global_load_lds_dwordx4 v[234:235], off
	s_mov_b32 m0, s39
	v_lshl_add_u64 v[234:235], v[242:243], 0, s[14:15]
	global_load_lds_dwordx4 v[234:235], off
	s_mov_b32 m0, s40
	v_lshl_add_u64 v[234:235], v[244:245], 0, s[14:15]
	global_load_lds_dwordx4 v[234:235], off
	s_waitcnt vmcnt(8)
	s_waitcnt lgkmcnt(0)
	s_barrier
	s_waitcnt lgkmcnt(0)
	v_mfma_f32_16x16x32_bf16 v[60:63], v[168:171], v[200:203], v[60:63]
	v_mfma_f32_16x16x32_bf16 v[60:63], v[172:175], v[204:207], v[60:63]
	v_mfma_f32_16x16x32_bf16 v[52:55], v[180:183], v[204:207], v[52:55]
	v_mfma_f32_16x16x32_bf16 v[52:55], v[176:179], v[200:203], v[52:55]
	v_mfma_f32_16x16x32_bf16 v[56:59], v[184:187], v[200:203], v[56:59]
	v_mfma_f32_16x16x32_bf16 v[56:59], v[188:191], v[204:207], v[56:59]
	v_mfma_f32_16x16x32_bf16 v[48:51], v[196:199], v[204:207], v[48:51]
	v_mfma_f32_16x16x32_bf16 v[48:51], v[192:195], v[200:203], v[48:51]
	v_mfma_f32_16x16x32_bf16 v[32:35], v[192:195], v[208:211], v[32:35]
	v_mfma_f32_16x16x32_bf16 v[32:35], v[196:199], v[212:215], v[32:35]
	v_mfma_f32_16x16x32_bf16 v[40:43], v[188:191], v[212:215], v[40:43]
	v_mfma_f32_16x16x32_bf16 v[40:43], v[184:187], v[208:211], v[40:43]
	v_mfma_f32_16x16x32_bf16 v[36:39], v[176:179], v[208:211], v[36:39]
	v_mfma_f32_16x16x32_bf16 v[36:39], v[180:183], v[212:215], v[36:39]
	v_mfma_f32_16x16x32_bf16 v[44:47], v[172:175], v[212:215], v[44:47]
	v_mfma_f32_16x16x32_bf16 v[44:47], v[168:171], v[208:211], v[44:47]
	v_mfma_f32_16x16x32_bf16 v[28:31], v[168:171], v[216:219], v[28:31]
	v_mfma_f32_16x16x32_bf16 v[28:31], v[172:175], v[222:225], v[28:31]
	v_mfma_f32_16x16x32_bf16 v[20:23], v[180:183], v[222:225], v[20:23]
	v_mfma_f32_16x16x32_bf16 v[20:23], v[176:179], v[216:219], v[20:23]
	v_mfma_f32_16x16x32_bf16 v[24:27], v[184:187], v[216:219], v[24:27]
	v_mfma_f32_16x16x32_bf16 v[24:27], v[188:191], v[222:225], v[24:27]
	v_mfma_f32_16x16x32_bf16 v[16:19], v[196:199], v[222:225], v[16:19]
	v_mfma_f32_16x16x32_bf16 v[16:19], v[192:195], v[216:219], v[16:19]
	v_mfma_f32_16x16x32_bf16 v[0:3], v[192:195], v[226:229], v[0:3]
	v_mfma_f32_16x16x32_bf16 v[0:3], v[196:199], v[230:233], v[0:3]
	v_mfma_f32_16x16x32_bf16 v[8:11], v[188:191], v[230:233], v[8:11]
	v_mfma_f32_16x16x32_bf16 v[8:11], v[184:187], v[226:229], v[8:11]
	v_mfma_f32_16x16x32_bf16 v[4:7], v[176:179], v[226:229], v[4:7]
	v_mfma_f32_16x16x32_bf16 v[4:7], v[180:183], v[230:233], v[4:7]
	v_mfma_f32_16x16x32_bf16 v[12:15], v[172:175], v[230:233], v[12:15]
	v_mfma_f32_16x16x32_bf16 v[12:15], v[168:171], v[226:229], v[12:15]
	s_add_u32 s20, s20, 0x100
	s_addc_u32 s21, s21, 0
	s_add_u32 s52, s52, 0x100
	s_addc_u32 s53, s53, 0
	s_cmp_ge_i32 s54, s41
	s_mov_b32 s22, s54
	s_barrier
	s_cbranch_scc0 .LBB0_142

.LBB0_228:
	ds_read_b128 v[140:143], v219
	ds_read_b128 v[144:147], v219 offset:1024
	ds_read_b128 v[148:151], v219 offset:2048
	ds_read_b128 v[152:155], v219 offset:3072
	ds_read_b128 v[156:159], v221
	ds_read_b128 v[164:167], v221 offset:1024
	ds_read_b128 v[168:171], v221 offset:2048
	ds_read_b128 v[172:175], v221 offset:3072
	s_add_i32 s62, s26, 2
	s_add_u32 s27, s24, 0x4000
	s_addc_u32 s28, s25, 0
	s_cmp_eq_u32 s46, s26
	s_cselect_b32 s30, s0, s27
	s_cselect_b32 s31, s1, s28
	s_cselect_b32 s28, s22, s60
	s_cselect_b32 s29, s23, s61
	s_add_u32 s26, s30, 0x8000
	s_addc_u32 s27, s31, 0
	v_lshl_add_u64 v[160:161], s[24:25], 0, v[132:133]
	s_add_i32 m0, s38, 0xc000
	ds_read_b128 v[176:179], v222
	ds_read_b128 v[180:183], v222 offset:1024
	ds_read_b128 v[184:187], v222 offset:2048
	ds_read_b128 v[188:191], v222 offset:3072
	ds_read_b128 v[192:195], v222 offset:4096
	ds_read_b128 v[196:199], v222 offset:5120
	ds_read_b128 v[200:203], v222 offset:6144
	ds_read_b128 v[204:207], v222 offset:7168
	global_load_lds_dwordx4 v[160:161], off
	s_add_i32 m0, s38, 0xe000
	v_lshl_add_u64 v[160:161], s[24:25], 0, v[134:135]
	global_load_lds_dwordx4 v[160:161], off
	s_waitcnt vmcnt(8)
	s_waitcnt lgkmcnt(0)
	s_barrier
	s_waitcnt lgkmcnt(0)
	v_mfma_f32_16x16x32_bf16 v[124:127], v[140:143], v[176:179], v[124:127]
	v_mfma_f32_16x16x32_bf16 v[124:127], v[144:147], v[180:183], v[124:127]
	v_mfma_f32_16x16x32_bf16 v[120:123], v[152:155], v[180:183], v[120:123]
	v_mfma_f32_16x16x32_bf16 v[120:123], v[148:151], v[176:179], v[120:123]
	v_mfma_f32_16x16x32_bf16 v[108:111], v[156:159], v[176:179], v[108:111]
	v_mfma_f32_16x16x32_bf16 v[108:111], v[164:167], v[180:183], v[108:111]
	v_mfma_f32_16x16x32_bf16 v[100:103], v[172:175], v[180:183], v[100:103]
	v_mfma_f32_16x16x32_bf16 v[100:103], v[168:171], v[176:179], v[100:103]
	v_mfma_f32_16x16x32_bf16 v[84:87], v[168:171], v[184:187], v[84:87]
	v_mfma_f32_16x16x32_bf16 v[84:87], v[172:175], v[188:191], v[84:87]
	v_mfma_f32_16x16x32_bf16 v[92:95], v[164:167], v[188:191], v[92:95]
	v_mfma_f32_16x16x32_bf16 v[92:95], v[156:159], v[184:187], v[92:95]
	v_mfma_f32_16x16x32_bf16 v[112:115], v[148:151], v[184:187], v[112:115]
	v_mfma_f32_16x16x32_bf16 v[112:115], v[152:155], v[188:191], v[112:115]
	v_mfma_f32_16x16x32_bf16 v[116:119], v[144:147], v[188:191], v[116:119]
	v_mfma_f32_16x16x32_bf16 v[116:119], v[140:143], v[184:187], v[116:119]
	v_mfma_f32_16x16x32_bf16 v[104:107], v[140:143], v[192:195], v[104:107]
	v_mfma_f32_16x16x32_bf16 v[104:107], v[144:147], v[196:199], v[104:107]
	v_mfma_f32_16x16x32_bf16 v[96:99], v[152:155], v[196:199], v[96:99]
	v_mfma_f32_16x16x32_bf16 v[96:99], v[148:151], v[192:195], v[96:99]
	v_mfma_f32_16x16x32_bf16 v[76:79], v[156:159], v[192:195], v[76:79]
	v_mfma_f32_16x16x32_bf16 v[76:79], v[164:167], v[196:199], v[76:79]
	v_mfma_f32_16x16x32_bf16 v[72:75], v[172:175], v[196:199], v[72:75]
	v_mfma_f32_16x16x32_bf16 v[72:75], v[168:171], v[192:195], v[72:75]
	v_mfma_f32_16x16x32_bf16 v[64:67], v[168:171], v[200:203], v[64:67]
	v_mfma_f32_16x16x32_bf16 v[64:67], v[172:175], v[204:207], v[64:67]
	v_mfma_f32_16x16x32_bf16 v[68:71], v[164:167], v[204:207], v[68:71]
	v_mfma_f32_16x16x32_bf16 v[68:71], v[156:159], v[200:203], v[68:71]
	v_mfma_f32_16x16x32_bf16 v[80:83], v[148:151], v[200:203], v[80:83]
	v_mfma_f32_16x16x32_bf16 v[80:83], v[152:155], v[204:207], v[80:83]
	v_mfma_f32_16x16x32_bf16 v[88:91], v[144:147], v[204:207], v[88:91]
	v_mfma_f32_16x16x32_bf16 v[88:91], v[140:143], v[200:203], v[88:91]
	s_barrier
	s_add_i32 s63, s50, s37
	v_lshl_add_u64 v[160:161], s[28:29], 0, v[128:129]
	s_mov_b32 m0, s63
	ds_read_b128 v[176:179], v222 offset:16384
	ds_read_b128 v[180:183], v222 offset:17408
	ds_read_b128 v[184:187], v222 offset:18432
	ds_read_b128 v[188:191], v222 offset:19456
	ds_read_b128 v[192:195], v222 offset:20480
	ds_read_b128 v[196:199], v222 offset:21504
	ds_read_b128 v[200:203], v222 offset:22528
	ds_read_b128 v[204:207], v222 offset:23552
	global_load_lds_dwordx4 v[160:161], off
	s_add_i32 m0, s63, 0x2000
	s_add_u32 s64, s28, 0x4000
	v_lshl_add_u64 v[160:161], s[28:29], 0, v[130:131]
	s_addc_u32 s65, s29, 0
	s_add_i32 s63, s51, s37
	global_load_lds_dwordx4 v[160:161], off
	s_mov_b32 m0, s63
	v_lshl_add_u64 v[160:161], s[64:65], 0, v[128:129]
	global_load_lds_dwordx4 v[160:161], off
	s_add_i32 m0, s63, 0x2000
	v_lshl_add_u64 v[160:161], s[64:65], 0, v[130:131]
	global_load_lds_dwordx4 v[160:161], off
	s_mov_b32 m0, s38
	v_lshl_add_u64 v[160:161], s[30:31], 0, v[128:129]
	global_load_lds_dwordx4 v[160:161], off
	s_mov_b32 m0, s39
	v_lshl_add_u64 v[160:161], s[30:31], 0, v[130:131]
	global_load_lds_dwordx4 v[160:161], off
	s_waitcnt vmcnt(8)
	s_waitcnt lgkmcnt(0)
	s_barrier
	s_waitcnt lgkmcnt(0)
	v_mfma_f32_16x16x32_bf16 v[60:63], v[140:143], v[176:179], v[60:63]
	v_mfma_f32_16x16x32_bf16 v[60:63], v[144:147], v[180:183], v[60:63]
	v_mfma_f32_16x16x32_bf16 v[56:59], v[152:155], v[180:183], v[56:59]
	v_mfma_f32_16x16x32_bf16 v[56:59], v[148:151], v[176:179], v[56:59]
	v_mfma_f32_16x16x32_bf16 v[44:47], v[156:159], v[176:179], v[44:47]
	v_mfma_f32_16x16x32_bf16 v[44:47], v[164:167], v[180:183], v[44:47]
	v_mfma_f32_16x16x32_bf16 v[36:39], v[172:175], v[180:183], v[36:39]
	v_mfma_f32_16x16x32_bf16 v[36:39], v[168:171], v[176:179], v[36:39]
	v_mfma_f32_16x16x32_bf16 v[20:23], v[168:171], v[184:187], v[20:23]
	v_mfma_f32_16x16x32_bf16 v[20:23], v[172:175], v[188:191], v[20:23]
	v_mfma_f32_16x16x32_bf16 v[28:31], v[164:167], v[188:191], v[28:31]
	v_mfma_f32_16x16x32_bf16 v[28:31], v[156:159], v[184:187], v[28:31]
	v_mfma_f32_16x16x32_bf16 v[48:51], v[148:151], v[184:187], v[48:51]
	v_mfma_f32_16x16x32_bf16 v[48:51], v[152:155], v[188:191], v[48:51]
	v_mfma_f32_16x16x32_bf16 v[52:55], v[144:147], v[188:191], v[52:55]
	v_mfma_f32_16x16x32_bf16 v[52:55], v[140:143], v[184:187], v[52:55]
	v_mfma_f32_16x16x32_bf16 v[40:43], v[140:143], v[192:195], v[40:43]
	v_mfma_f32_16x16x32_bf16 v[40:43], v[144:147], v[196:199], v[40:43]
	v_mfma_f32_16x16x32_bf16 v[32:35], v[152:155], v[196:199], v[32:35]
	v_mfma_f32_16x16x32_bf16 v[32:35], v[148:151], v[192:195], v[32:35]
	v_mfma_f32_16x16x32_bf16 v[12:15], v[156:159], v[192:195], v[12:15]
	v_mfma_f32_16x16x32_bf16 v[12:15], v[164:167], v[196:199], v[12:15]
	v_mfma_f32_16x16x32_bf16 v[8:11], v[172:175], v[196:199], v[8:11]
	v_mfma_f32_16x16x32_bf16 v[8:11], v[168:171], v[192:195], v[8:11]
	v_mfma_f32_16x16x32_bf16 v[0:3], v[168:171], v[200:203], v[0:3]
	v_mfma_f32_16x16x32_bf16 v[0:3], v[172:175], v[204:207], v[0:3]
	v_mfma_f32_16x16x32_bf16 v[4:7], v[164:167], v[204:207], v[4:7]
	v_mfma_f32_16x16x32_bf16 v[4:7], v[156:159], v[200:203], v[4:7]
	v_mfma_f32_16x16x32_bf16 v[16:19], v[148:151], v[200:203], v[16:19]
	v_mfma_f32_16x16x32_bf16 v[16:19], v[152:155], v[204:207], v[16:19]
	v_mfma_f32_16x16x32_bf16 v[24:27], v[144:147], v[204:207], v[24:27]
	v_mfma_f32_16x16x32_bf16 v[24:27], v[140:143], v[200:203], v[24:27]
	s_barrier
	s_add_i32 s63, 0, 0x18000
	s_add_i32 s64, 0, 0x1c000
	v_add_u32_e32 v152, s63, v217
	v_add_u32_e32 v160, s64, v217
	ds_read_b128 v[140:143], v152
	ds_read_b128 v[144:147], v152 offset:1024
	ds_read_b128 v[148:151], v152 offset:2048
	ds_read_b128 v[152:155], v152 offset:3072
	ds_read_b128 v[156:159], v160
	ds_read_b128 v[164:167], v160 offset:1024
	ds_read_b128 v[168:171], v160 offset:2048
	ds_read_b128 v[172:175], v160 offset:3072
	s_add_u32 s30, s30, 0x4000
	s_addc_u32 s31, s31, 0
	s_mov_b32 m0, s40
	v_lshl_add_u64 v[160:161], s[30:31], 0, v[128:129]
	ds_read_b128 v[176:179], v222 offset:32768
	ds_read_b128 v[180:183], v222 offset:33792
	ds_read_b128 v[184:187], v222 offset:34816
	ds_read_b128 v[188:191], v222 offset:35840
	ds_read_b128 v[192:195], v222 offset:36864
	ds_read_b128 v[196:199], v222 offset:37888
	ds_read_b128 v[200:203], v222 offset:38912
	ds_read_b128 v[204:207], v222 offset:39936
	global_load_lds_dwordx4 v[160:161], off
	s_mov_b32 m0, s41
	v_lshl_add_u64 v[160:161], s[30:31], 0, v[130:131]
	global_load_lds_dwordx4 v[160:161], off
	s_waitcnt vmcnt(8)
	s_waitcnt lgkmcnt(0)
	s_barrier
	s_waitcnt lgkmcnt(0)
	v_mfma_f32_16x16x32_bf16 v[124:127], v[140:143], v[176:179], v[124:127]
	v_mfma_f32_16x16x32_bf16 v[124:127], v[144:147], v[180:183], v[124:127]
	v_mfma_f32_16x16x32_bf16 v[120:123], v[152:155], v[180:183], v[120:123]
	v_mfma_f32_16x16x32_bf16 v[120:123], v[148:151], v[176:179], v[120:123]
	v_mfma_f32_16x16x32_bf16 v[108:111], v[156:159], v[176:179], v[108:111]
	v_mfma_f32_16x16x32_bf16 v[108:111], v[164:167], v[180:183], v[108:111]
	v_mfma_f32_16x16x32_bf16 v[100:103], v[172:175], v[180:183], v[100:103]
	v_mfma_f32_16x16x32_bf16 v[100:103], v[168:171], v[176:179], v[100:103]
	v_mfma_f32_16x16x32_bf16 v[84:87], v[168:171], v[184:187], v[84:87]
	v_mfma_f32_16x16x32_bf16 v[84:87], v[172:175], v[188:191], v[84:87]
	v_mfma_f32_16x16x32_bf16 v[92:95], v[164:167], v[188:191], v[92:95]
	v_mfma_f32_16x16x32_bf16 v[92:95], v[156:159], v[184:187], v[92:95]
	v_mfma_f32_16x16x32_bf16 v[112:115], v[148:151], v[184:187], v[112:115]
	v_mfma_f32_16x16x32_bf16 v[112:115], v[152:155], v[188:191], v[112:115]
	v_mfma_f32_16x16x32_bf16 v[116:119], v[144:147], v[188:191], v[116:119]
	v_mfma_f32_16x16x32_bf16 v[116:119], v[140:143], v[184:187], v[116:119]
	v_mfma_f32_16x16x32_bf16 v[104:107], v[140:143], v[192:195], v[104:107]
	v_mfma_f32_16x16x32_bf16 v[104:107], v[144:147], v[196:199], v[104:107]
	v_mfma_f32_16x16x32_bf16 v[96:99], v[152:155], v[196:199], v[96:99]
	v_mfma_f32_16x16x32_bf16 v[96:99], v[148:151], v[192:195], v[96:99]
	v_mfma_f32_16x16x32_bf16 v[76:79], v[156:159], v[192:195], v[76:79]
	v_mfma_f32_16x16x32_bf16 v[76:79], v[164:167], v[196:199], v[76:79]
	v_mfma_f32_16x16x32_bf16 v[72:75], v[172:175], v[196:199], v[72:75]
	v_mfma_f32_16x16x32_bf16 v[72:75], v[168:171], v[192:195], v[72:75]
	v_mfma_f32_16x16x32_bf16 v[64:67], v[168:171], v[200:203], v[64:67]
	v_mfma_f32_16x16x32_bf16 v[64:67], v[172:175], v[204:207], v[64:67]
	v_mfma_f32_16x16x32_bf16 v[68:71], v[164:167], v[204:207], v[68:71]
	v_mfma_f32_16x16x32_bf16 v[68:71], v[156:159], v[200:203], v[68:71]
	v_mfma_f32_16x16x32_bf16 v[80:83], v[148:151], v[200:203], v[80:83]
	v_mfma_f32_16x16x32_bf16 v[80:83], v[152:155], v[204:207], v[80:83]
	v_mfma_f32_16x16x32_bf16 v[88:91], v[144:147], v[204:207], v[88:91]
	v_mfma_f32_16x16x32_bf16 v[88:91], v[140:143], v[200:203], v[88:91]
	s_barrier
	s_add_u32 s30, s28, 0x8000
	s_addc_u32 s31, s29, 0
	s_add_i32 s63, s63, s37
	v_lshl_add_u64 v[160:161], s[30:31], 0, v[128:129]
	s_mov_b32 m0, s63
	ds_read_b128 v[176:179], v222 offset:49152
	ds_read_b128 v[180:183], v222 offset:50176
	ds_read_b128 v[184:187], v222 offset:51200
	ds_read_b128 v[188:191], v222 offset:52224
	ds_read_b128 v[192:195], v222 offset:53248
	ds_read_b128 v[196:199], v222 offset:54272
	ds_read_b128 v[200:203], v222 offset:55296
	ds_read_b128 v[204:207], v222 offset:56320
	global_load_lds_dwordx4 v[160:161], off
	s_add_i32 m0, s63, 0x2000
	s_add_u32 s28, s28, 0xc000
	v_lshl_add_u64 v[160:161], s[30:31], 0, v[130:131]
	s_addc_u32 s29, s29, 0
	s_add_i32 s30, s64, s37
	global_load_lds_dwordx4 v[160:161], off
	s_mov_b32 m0, s30
	v_lshl_add_u64 v[160:161], s[28:29], 0, v[128:129]
	global_load_lds_dwordx4 v[160:161], off
	s_add_i32 m0, s30, 0x2000
	v_lshl_add_u64 v[160:161], s[28:29], 0, v[130:131]
	global_load_lds_dwordx4 v[160:161], off
	s_mov_b32 m0, s44
	v_lshl_add_u64 v[160:161], s[26:27], 0, v[128:129]
	global_load_lds_dwordx4 v[160:161], off
	s_mov_b32 m0, s45
	v_lshl_add_u64 v[160:161], s[26:27], 0, v[130:131]
	global_load_lds_dwordx4 v[160:161], off
	s_waitcnt vmcnt(8)
	s_waitcnt lgkmcnt(0)
	s_barrier
	s_waitcnt lgkmcnt(0)
	v_mfma_f32_16x16x32_bf16 v[60:63], v[140:143], v[176:179], v[60:63]
	v_mfma_f32_16x16x32_bf16 v[60:63], v[144:147], v[180:183], v[60:63]
	v_mfma_f32_16x16x32_bf16 v[56:59], v[152:155], v[180:183], v[56:59]
	v_mfma_f32_16x16x32_bf16 v[56:59], v[148:151], v[176:179], v[56:59]
	v_mfma_f32_16x16x32_bf16 v[44:47], v[156:159], v[176:179], v[44:47]
	v_mfma_f32_16x16x32_bf16 v[44:47], v[164:167], v[180:183], v[44:47]
	v_mfma_f32_16x16x32_bf16 v[36:39], v[172:175], v[180:183], v[36:39]
	v_mfma_f32_16x16x32_bf16 v[36:39], v[168:171], v[176:179], v[36:39]
	v_mfma_f32_16x16x32_bf16 v[20:23], v[168:171], v[184:187], v[20:23]
	v_mfma_f32_16x16x32_bf16 v[20:23], v[172:175], v[188:191], v[20:23]
	v_mfma_f32_16x16x32_bf16 v[28:31], v[164:167], v[188:191], v[28:31]
	v_mfma_f32_16x16x32_bf16 v[28:31], v[156:159], v[184:187], v[28:31]
	v_mfma_f32_16x16x32_bf16 v[48:51], v[148:151], v[184:187], v[48:51]
	v_mfma_f32_16x16x32_bf16 v[48:51], v[152:155], v[188:191], v[48:51]
	v_mfma_f32_16x16x32_bf16 v[52:55], v[144:147], v[188:191], v[52:55]
	v_mfma_f32_16x16x32_bf16 v[52:55], v[140:143], v[184:187], v[52:55]
	v_mfma_f32_16x16x32_bf16 v[40:43], v[140:143], v[192:195], v[40:43]
	v_mfma_f32_16x16x32_bf16 v[40:43], v[144:147], v[196:199], v[40:43]
	v_mfma_f32_16x16x32_bf16 v[32:35], v[152:155], v[196:199], v[32:35]
	v_mfma_f32_16x16x32_bf16 v[32:35], v[148:151], v[192:195], v[32:35]
	v_mfma_f32_16x16x32_bf16 v[12:15], v[156:159], v[192:195], v[12:15]
	v_mfma_f32_16x16x32_bf16 v[12:15], v[164:167], v[196:199], v[12:15]
	v_mfma_f32_16x16x32_bf16 v[8:11], v[172:175], v[196:199], v[8:11]
	v_mfma_f32_16x16x32_bf16 v[8:11], v[168:171], v[192:195], v[8:11]
	v_mfma_f32_16x16x32_bf16 v[0:3], v[168:171], v[200:203], v[0:3]
	v_mfma_f32_16x16x32_bf16 v[0:3], v[172:175], v[204:207], v[0:3]
	v_mfma_f32_16x16x32_bf16 v[4:7], v[164:167], v[204:207], v[4:7]
	v_mfma_f32_16x16x32_bf16 v[4:7], v[156:159], v[200:203], v[4:7]
	v_mfma_f32_16x16x32_bf16 v[16:19], v[148:151], v[200:203], v[16:19]
	v_mfma_f32_16x16x32_bf16 v[16:19], v[152:155], v[204:207], v[16:19]
	v_mfma_f32_16x16x32_bf16 v[24:27], v[144:147], v[204:207], v[24:27]
	v_mfma_f32_16x16x32_bf16 v[24:27], v[140:143], v[200:203], v[24:27]
	s_add_u32 s24, s24, 0x10000
	s_addc_u32 s25, s25, 0
	s_add_u32 s60, s60, 0x10000
	s_addc_u32 s61, s61, 0
	s_cmp_ge_i32 s62, s43
	s_mov_b32 s26, s62
	s_barrier
	s_cbranch_scc0 .LBB0_228
	v_pk_mul_f32 v[200:201], v[126:127], 0.5 op_sel_hi:[1,0]
	v_pk_mul_f32 v[202:203], v[124:125], 0.5 op_sel_hi:[1,0]
	v_pk_mul_f32 v[204:205], v[122:123], 0.5 op_sel_hi:[1,0]
	v_pk_mul_f32 v[206:207], v[120:121], 0.5 op_sel_hi:[1,0]
	v_pk_mul_f32 v[210:211], v[110:111], 0.5 op_sel_hi:[1,0]
	v_pk_mul_f32 v[208:209], v[108:109], 0.5 op_sel_hi:[1,0]
	v_pk_mul_f32 v[198:199], v[102:103], 0.5 op_sel_hi:[1,0]
	v_pk_mul_f32 v[196:197], v[100:101], 0.5 op_sel_hi:[1,0]
	v_pk_mul_f32 v[194:195], v[118:119], 0.5 op_sel_hi:[1,0]
	v_pk_mul_f32 v[192:193], v[116:117], 0.5 op_sel_hi:[1,0]
	v_pk_mul_f32 v[190:191], v[114:115], 0.5 op_sel_hi:[1,0]
	v_pk_mul_f32 v[188:189], v[112:113], 0.5 op_sel_hi:[1,0]
	v_pk_mul_f32 v[186:187], v[94:95], 0.5 op_sel_hi:[1,0]
	v_pk_mul_f32 v[184:185], v[92:93], 0.5 op_sel_hi:[1,0]
	v_pk_mul_f32 v[182:183], v[86:87], 0.5 op_sel_hi:[1,0]
	v_pk_mul_f32 v[180:181], v[84:85], 0.5 op_sel_hi:[1,0]
	v_pk_mul_f32 v[178:179], v[106:107], 0.5 op_sel_hi:[1,0]
	v_pk_mul_f32 v[176:177], v[104:105], 0.5 op_sel_hi:[1,0]
	v_pk_mul_f32 v[174:175], v[98:99], 0.5 op_sel_hi:[1,0]
	v_pk_mul_f32 v[172:173], v[96:97], 0.5 op_sel_hi:[1,0]
	v_pk_mul_f32 v[170:171], v[78:79], 0.5 op_sel_hi:[1,0]
	v_pk_mul_f32 v[168:169], v[76:77], 0.5 op_sel_hi:[1,0]
	v_pk_mul_f32 v[166:167], v[74:75], 0.5 op_sel_hi:[1,0]
	v_pk_mul_f32 v[164:165], v[72:73], 0.5 op_sel_hi:[1,0]
	v_pk_mul_f32 v[160:161], v[90:91], 0.5 op_sel_hi:[1,0]
	v_pk_mul_f32 v[158:159], v[88:89], 0.5 op_sel_hi:[1,0]
	v_pk_mul_f32 v[156:157], v[82:83], 0.5 op_sel_hi:[1,0]
	v_pk_mul_f32 v[154:155], v[80:81], 0.5 op_sel_hi:[1,0]
	v_pk_mul_f32 v[152:153], v[70:71], 0.5 op_sel_hi:[1,0]
	v_pk_mul_f32 v[150:151], v[68:69], 0.5 op_sel_hi:[1,0]
	v_pk_mul_f32 v[148:149], v[66:67], 0.5 op_sel_hi:[1,0]
	v_pk_mul_f32 v[146:147], v[64:65], 0.5 op_sel_hi:[1,0]
	v_pk_mul_f32 v[144:145], v[62:63], 0.5 op_sel_hi:[1,0]
	v_pk_mul_f32 v[142:143], v[60:61], 0.5 op_sel_hi:[1,0]
	v_pk_mul_f32 v[126:127], v[58:59], 0.5 op_sel_hi:[1,0]
	v_pk_mul_f32 v[124:125], v[56:57], 0.5 op_sel_hi:[1,0]
	v_pk_mul_f32 v[122:123], v[46:47], 0.5 op_sel_hi:[1,0]
	v_pk_mul_f32 v[120:121], v[44:45], 0.5 op_sel_hi:[1,0]
	v_pk_mul_f32 v[118:119], v[38:39], 0.5 op_sel_hi:[1,0]
	v_pk_mul_f32 v[116:117], v[36:37], 0.5 op_sel_hi:[1,0]
	v_pk_mul_f32 v[114:115], v[54:55], 0.5 op_sel_hi:[1,0]
	v_pk_mul_f32 v[112:113], v[52:53], 0.5 op_sel_hi:[1,0]
	v_pk_mul_f32 v[110:111], v[50:51], 0.5 op_sel_hi:[1,0]
	v_pk_mul_f32 v[108:109], v[48:49], 0.5 op_sel_hi:[1,0]
	v_pk_mul_f32 v[106:107], v[30:31], 0.5 op_sel_hi:[1,0]
	v_pk_mul_f32 v[104:105], v[28:29], 0.5 op_sel_hi:[1,0]
	v_pk_mul_f32 v[102:103], v[22:23], 0.5 op_sel_hi:[1,0]
	v_pk_mul_f32 v[100:101], v[20:21], 0.5 op_sel_hi:[1,0]
	v_pk_mul_f32 v[98:99], v[42:43], 0.5 op_sel_hi:[1,0]
	v_pk_mul_f32 v[96:97], v[40:41], 0.5 op_sel_hi:[1,0]
	v_pk_mul_f32 v[94:95], v[34:35], 0.5 op_sel_hi:[1,0]
	v_pk_mul_f32 v[92:93], v[32:33], 0.5 op_sel_hi:[1,0]
	v_pk_mul_f32 v[90:91], v[14:15], 0.5 op_sel_hi:[1,0]
	v_pk_mul_f32 v[88:89], v[12:13], 0.5 op_sel_hi:[1,0]
	v_pk_mul_f32 v[86:87], v[10:11], 0.5 op_sel_hi:[1,0]
	v_pk_mul_f32 v[84:85], v[8:9], 0.5 op_sel_hi:[1,0]
	v_pk_mul_f32 v[82:83], v[26:27], 0.5 op_sel_hi:[1,0]
	v_pk_mul_f32 v[80:81], v[24:25], 0.5 op_sel_hi:[1,0]
	v_pk_mul_f32 v[78:79], v[18:19], 0.5 op_sel_hi:[1,0]
	v_pk_mul_f32 v[76:77], v[16:17], 0.5 op_sel_hi:[1,0]
	v_pk_mul_f32 v[74:75], v[6:7], 0.5 op_sel_hi:[1,0]
	v_pk_mul_f32 v[72:73], v[4:5], 0.5 op_sel_hi:[1,0]
	v_pk_mul_f32 v[70:71], v[2:3], 0.5 op_sel_hi:[1,0]
	v_pk_mul_f32 v[68:69], v[0:1], 0.5 op_sel_hi:[1,0]

.LBB0_323:
	ds_read_b128 v[128:131], v222
	ds_read_b128 v[132:135], v222 offset:1024
	ds_read_b128 v[136:139], v222 offset:2048
	ds_read_b128 v[140:143], v222 offset:3072
	ds_read_b128 v[144:147], v223
	ds_read_b128 v[148:151], v223 offset:1024
	ds_read_b128 v[152:155], v223 offset:2048
	ds_read_b128 v[156:159], v223 offset:3072
	s_add_i32 s53, s50, 2
	s_add_u32 s54, s0, 0x80
	s_addc_u32 s51, s1, 0
	s_cmp_eq_u32 s78, s50
	s_cselect_b32 s50, s46, s54
	s_cselect_b32 s51, s47, s51
	s_cselect_b32 s55, s49, s52
	s_cselect_b32 s54, s48, s33
	v_lshl_add_u64 v[160:161], s[0:1], 0, v[176:177]
	s_add_i32 m0, s71, 0xc000
	ds_read_b128 v[184:187], v224
	ds_read_b128 v[188:191], v224 offset:1024
	ds_read_b128 v[192:195], v224 offset:2048
	ds_read_b128 v[196:199], v224 offset:3072
	ds_read_b128 v[200:203], v224 offset:4096
	ds_read_b128 v[204:207], v224 offset:5120
	ds_read_b128 v[208:211], v224 offset:6144
	ds_read_b128 v[212:215], v224 offset:7168
	global_load_lds_dwordx4 v[160:161], off
	s_add_i32 m0, s71, 0xe000
	v_lshl_add_u64 v[160:161], s[0:1], 0, v[178:179]
	global_load_lds_dwordx4 v[160:161], off
	s_waitcnt vmcnt(8)
	s_waitcnt lgkmcnt(0)
	s_barrier
	s_waitcnt lgkmcnt(0)
	v_mfma_f32_16x16x32_bf16 v[124:127], v[128:131], v[184:187], v[124:127]
	v_mfma_f32_16x16x32_bf16 v[124:127], v[132:135], v[188:191], v[124:127]
	v_mfma_f32_16x16x32_bf16 v[120:123], v[140:143], v[188:191], v[120:123]
	v_mfma_f32_16x16x32_bf16 v[120:123], v[136:139], v[184:187], v[120:123]
	v_mfma_f32_16x16x32_bf16 v[116:119], v[144:147], v[184:187], v[116:119]
	v_mfma_f32_16x16x32_bf16 v[116:119], v[148:151], v[188:191], v[116:119]
	v_mfma_f32_16x16x32_bf16 v[112:115], v[156:159], v[188:191], v[112:115]
	v_mfma_f32_16x16x32_bf16 v[112:115], v[152:155], v[184:187], v[112:115]
	v_mfma_f32_16x16x32_bf16 v[96:99], v[152:155], v[192:195], v[96:99]
	v_mfma_f32_16x16x32_bf16 v[96:99], v[156:159], v[196:199], v[96:99]
	v_mfma_f32_16x16x32_bf16 v[100:103], v[148:151], v[196:199], v[100:103]
	v_mfma_f32_16x16x32_bf16 v[100:103], v[144:147], v[192:195], v[100:103]
	v_mfma_f32_16x16x32_bf16 v[104:107], v[136:139], v[192:195], v[104:107]
	v_mfma_f32_16x16x32_bf16 v[104:107], v[140:143], v[196:199], v[104:107]
	v_mfma_f32_16x16x32_bf16 v[108:111], v[132:135], v[196:199], v[108:111]
	v_mfma_f32_16x16x32_bf16 v[108:111], v[128:131], v[192:195], v[108:111]
	v_mfma_f32_16x16x32_bf16 v[92:95], v[128:131], v[200:203], v[92:95]
	v_mfma_f32_16x16x32_bf16 v[92:95], v[132:135], v[204:207], v[92:95]
	v_mfma_f32_16x16x32_bf16 v[88:91], v[140:143], v[204:207], v[88:91]
	v_mfma_f32_16x16x32_bf16 v[88:91], v[136:139], v[200:203], v[88:91]
	v_mfma_f32_16x16x32_bf16 v[84:87], v[144:147], v[200:203], v[84:87]
	v_mfma_f32_16x16x32_bf16 v[84:87], v[148:151], v[204:207], v[84:87]
	v_mfma_f32_16x16x32_bf16 v[80:83], v[156:159], v[204:207], v[80:83]
	v_mfma_f32_16x16x32_bf16 v[80:83], v[152:155], v[200:203], v[80:83]
	v_mfma_f32_16x16x32_bf16 v[64:67], v[152:155], v[208:211], v[64:67]
	v_mfma_f32_16x16x32_bf16 v[64:67], v[156:159], v[212:215], v[64:67]
	v_mfma_f32_16x16x32_bf16 v[68:71], v[148:151], v[212:215], v[68:71]
	v_mfma_f32_16x16x32_bf16 v[68:71], v[144:147], v[208:211], v[68:71]
	v_mfma_f32_16x16x32_bf16 v[72:75], v[136:139], v[208:211], v[72:75]
	v_mfma_f32_16x16x32_bf16 v[72:75], v[140:143], v[212:215], v[72:75]
	v_mfma_f32_16x16x32_bf16 v[76:79], v[132:135], v[212:215], v[76:79]
	v_mfma_f32_16x16x32_bf16 v[76:79], v[128:131], v[208:211], v[76:79]
	s_barrier
	s_add_i32 s60, s82, s70
	v_lshl_add_u64 v[160:161], s[54:55], 0, v[166:167]
	s_mov_b32 m0, s60
	ds_read_b128 v[184:187], v224 offset:16384
	ds_read_b128 v[188:191], v224 offset:17408
	ds_read_b128 v[192:195], v224 offset:18432
	ds_read_b128 v[196:199], v224 offset:19456
	ds_read_b128 v[200:203], v224 offset:20480
	ds_read_b128 v[204:207], v224 offset:21504
	ds_read_b128 v[208:211], v224 offset:22528
	ds_read_b128 v[212:215], v224 offset:23552
	global_load_lds_dwordx4 v[160:161], off
	s_add_i32 m0, s60, 0x2000
	v_lshl_add_u64 v[216:217], s[54:55], 0, v[170:171]
	s_add_u32 s54, s54, s10
	s_addc_u32 s55, s55, s11
	s_add_i32 s60, s83, s70
	global_load_lds_dwordx4 v[216:217], off
	v_lshl_add_u64 v[218:219], s[54:55], 0, v[166:167]
	s_mov_b32 m0, s60
	v_lshl_add_u64 v[230:231], s[54:55], 0, v[170:171]
	global_load_lds_dwordx4 v[218:219], off
	s_add_i32 m0, s60, 0x2000
	v_lshl_add_u64 v[232:233], s[50:51], 0, v[164:165]
	global_load_lds_dwordx4 v[230:231], off
	s_mov_b32 m0, s71
	v_lshl_add_u64 v[234:235], s[50:51], 0, v[168:169]
	global_load_lds_dwordx4 v[232:233], off
	s_mov_b32 m0, s72
	s_nop 0
	global_load_lds_dwordx4 v[234:235], off
	s_waitcnt vmcnt(8)
	s_waitcnt lgkmcnt(0)
	s_barrier
	s_waitcnt lgkmcnt(0)
	v_mfma_f32_16x16x32_bf16 v[60:63], v[128:131], v[184:187], v[60:63]
	v_mfma_f32_16x16x32_bf16 v[60:63], v[132:135], v[188:191], v[60:63]
	v_mfma_f32_16x16x32_bf16 v[56:59], v[140:143], v[188:191], v[56:59]
	v_mfma_f32_16x16x32_bf16 v[56:59], v[136:139], v[184:187], v[56:59]
	v_mfma_f32_16x16x32_bf16 v[52:55], v[144:147], v[184:187], v[52:55]
	v_mfma_f32_16x16x32_bf16 v[52:55], v[148:151], v[188:191], v[52:55]
	v_mfma_f32_16x16x32_bf16 v[48:51], v[156:159], v[188:191], v[48:51]
	v_mfma_f32_16x16x32_bf16 v[48:51], v[152:155], v[184:187], v[48:51]
	v_mfma_f32_16x16x32_bf16 v[32:35], v[152:155], v[192:195], v[32:35]
	v_mfma_f32_16x16x32_bf16 v[32:35], v[156:159], v[196:199], v[32:35]
	v_mfma_f32_16x16x32_bf16 v[36:39], v[148:151], v[196:199], v[36:39]
	v_mfma_f32_16x16x32_bf16 v[36:39], v[144:147], v[192:195], v[36:39]
	v_mfma_f32_16x16x32_bf16 v[40:43], v[136:139], v[192:195], v[40:43]
	v_mfma_f32_16x16x32_bf16 v[40:43], v[140:143], v[196:199], v[40:43]
	v_mfma_f32_16x16x32_bf16 v[44:47], v[132:135], v[196:199], v[44:47]
	v_mfma_f32_16x16x32_bf16 v[44:47], v[128:131], v[192:195], v[44:47]
	v_mfma_f32_16x16x32_bf16 v[28:31], v[128:131], v[200:203], v[28:31]
	v_mfma_f32_16x16x32_bf16 v[28:31], v[132:135], v[204:207], v[28:31]
	v_mfma_f32_16x16x32_bf16 v[24:27], v[140:143], v[204:207], v[24:27]
	v_mfma_f32_16x16x32_bf16 v[24:27], v[136:139], v[200:203], v[24:27]
	v_mfma_f32_16x16x32_bf16 v[20:23], v[144:147], v[200:203], v[20:23]
	v_mfma_f32_16x16x32_bf16 v[20:23], v[148:151], v[204:207], v[20:23]
	v_mfma_f32_16x16x32_bf16 v[16:19], v[156:159], v[204:207], v[16:19]
	v_mfma_f32_16x16x32_bf16 v[16:19], v[152:155], v[200:203], v[16:19]
	v_mfma_f32_16x16x32_bf16 v[0:3], v[152:155], v[208:211], v[0:3]
	v_mfma_f32_16x16x32_bf16 v[0:3], v[156:159], v[212:215], v[0:3]
	v_mfma_f32_16x16x32_bf16 v[4:7], v[148:151], v[212:215], v[4:7]
	v_mfma_f32_16x16x32_bf16 v[4:7], v[144:147], v[208:211], v[4:7]
	v_mfma_f32_16x16x32_bf16 v[8:11], v[136:139], v[208:211], v[8:11]
	v_mfma_f32_16x16x32_bf16 v[8:11], v[140:143], v[212:215], v[8:11]
	v_mfma_f32_16x16x32_bf16 v[12:15], v[132:135], v[212:215], v[12:15]
	v_mfma_f32_16x16x32_bf16 v[12:15], v[128:131], v[208:211], v[12:15]
	s_barrier
	s_add_i32 s54, 0, 0x18000
	s_add_i32 s55, 0, 0x1c000
	v_add_u32_e32 v140, s54, v221
	v_add_u32_e32 v156, s55, v221
	ds_read_b128 v[128:131], v140
	ds_read_b128 v[132:135], v140 offset:1024
	ds_read_b128 v[136:139], v140 offset:2048
	ds_read_b128 v[140:143], v140 offset:3072
	ds_read_b128 v[144:147], v156
	ds_read_b128 v[148:151], v156 offset:1024
	ds_read_b128 v[152:155], v156 offset:2048
	ds_read_b128 v[156:159], v156 offset:3072
	s_add_u32 s50, s50, s10
	s_addc_u32 s51, s51, s11
	s_mov_b32 m0, s73
	v_lshl_add_u64 v[236:237], s[50:51], 0, v[164:165]
	ds_read_b128 v[184:187], v224 offset:32768
	ds_read_b128 v[188:191], v224 offset:33792
	ds_read_b128 v[192:195], v224 offset:34816
	ds_read_b128 v[196:199], v224 offset:35840
	ds_read_b128 v[200:203], v224 offset:36864
	ds_read_b128 v[204:207], v224 offset:37888
	ds_read_b128 v[208:211], v224 offset:38912
	ds_read_b128 v[212:215], v224 offset:39936
	global_load_lds_dwordx4 v[236:237], off
	s_mov_b32 m0, s74
	v_lshl_add_u64 v[236:237], s[50:51], 0, v[168:169]
	global_load_lds_dwordx4 v[236:237], off
	s_waitcnt vmcnt(8)
	s_waitcnt lgkmcnt(0)
	s_barrier
	s_waitcnt lgkmcnt(0)
	v_mfma_f32_16x16x32_bf16 v[124:127], v[128:131], v[184:187], v[124:127]
	v_mfma_f32_16x16x32_bf16 v[124:127], v[132:135], v[188:191], v[124:127]
	v_mfma_f32_16x16x32_bf16 v[120:123], v[140:143], v[188:191], v[120:123]
	v_mfma_f32_16x16x32_bf16 v[120:123], v[136:139], v[184:187], v[120:123]
	v_mfma_f32_16x16x32_bf16 v[116:119], v[144:147], v[184:187], v[116:119]
	v_mfma_f32_16x16x32_bf16 v[116:119], v[148:151], v[188:191], v[116:119]
	v_mfma_f32_16x16x32_bf16 v[112:115], v[156:159], v[188:191], v[112:115]
	v_mfma_f32_16x16x32_bf16 v[112:115], v[152:155], v[184:187], v[112:115]
	v_mfma_f32_16x16x32_bf16 v[96:99], v[152:155], v[192:195], v[96:99]
	v_mfma_f32_16x16x32_bf16 v[96:99], v[156:159], v[196:199], v[96:99]
	v_mfma_f32_16x16x32_bf16 v[100:103], v[148:151], v[196:199], v[100:103]
	v_mfma_f32_16x16x32_bf16 v[100:103], v[144:147], v[192:195], v[100:103]
	v_mfma_f32_16x16x32_bf16 v[104:107], v[136:139], v[192:195], v[104:107]
	v_mfma_f32_16x16x32_bf16 v[104:107], v[140:143], v[196:199], v[104:107]
	v_mfma_f32_16x16x32_bf16 v[108:111], v[132:135], v[196:199], v[108:111]
	v_mfma_f32_16x16x32_bf16 v[108:111], v[128:131], v[192:195], v[108:111]
	v_mfma_f32_16x16x32_bf16 v[92:95], v[128:131], v[200:203], v[92:95]
	v_mfma_f32_16x16x32_bf16 v[92:95], v[132:135], v[204:207], v[92:95]
	v_mfma_f32_16x16x32_bf16 v[88:91], v[140:143], v[204:207], v[88:91]
	v_mfma_f32_16x16x32_bf16 v[88:91], v[136:139], v[200:203], v[88:91]
	v_mfma_f32_16x16x32_bf16 v[84:87], v[144:147], v[200:203], v[84:87]
	v_mfma_f32_16x16x32_bf16 v[84:87], v[148:151], v[204:207], v[84:87]
	v_mfma_f32_16x16x32_bf16 v[80:83], v[156:159], v[204:207], v[80:83]
	v_mfma_f32_16x16x32_bf16 v[80:83], v[152:155], v[200:203], v[80:83]
	v_mfma_f32_16x16x32_bf16 v[64:67], v[152:155], v[208:211], v[64:67]
	v_mfma_f32_16x16x32_bf16 v[64:67], v[156:159], v[212:215], v[64:67]
	v_mfma_f32_16x16x32_bf16 v[68:71], v[148:151], v[212:215], v[68:71]
	v_mfma_f32_16x16x32_bf16 v[68:71], v[144:147], v[208:211], v[68:71]
	v_mfma_f32_16x16x32_bf16 v[72:75], v[136:139], v[208:211], v[72:75]
	v_mfma_f32_16x16x32_bf16 v[72:75], v[140:143], v[212:215], v[72:75]
	v_mfma_f32_16x16x32_bf16 v[76:79], v[132:135], v[212:215], v[76:79]
	v_mfma_f32_16x16x32_bf16 v[76:79], v[128:131], v[208:211], v[76:79]
	s_barrier
	s_add_i32 s50, s54, s70
	v_lshl_add_u64 v[160:161], v[160:161], 0, s[36:37]
	s_mov_b32 m0, s50
	ds_read_b128 v[184:187], v224 offset:49152
	ds_read_b128 v[188:191], v224 offset:50176
	ds_read_b128 v[192:195], v224 offset:51200
	ds_read_b128 v[196:199], v224 offset:52224
	ds_read_b128 v[200:203], v224 offset:53248
	ds_read_b128 v[204:207], v224 offset:54272
	ds_read_b128 v[208:211], v224 offset:55296
	ds_read_b128 v[212:215], v224 offset:56320
	global_load_lds_dwordx4 v[160:161], off
	v_lshl_add_u64 v[160:161], v[216:217], 0, s[36:37]
	s_add_i32 m0, s50, 0x2000
	s_add_i32 s50, s55, s70
	global_load_lds_dwordx4 v[160:161], off
	s_mov_b32 m0, s50
	v_lshl_add_u64 v[160:161], v[218:219], 0, s[36:37]
	global_load_lds_dwordx4 v[160:161], off
	s_add_i32 m0, s50, 0x2000
	v_lshl_add_u64 v[160:161], v[230:231], 0, s[36:37]
	global_load_lds_dwordx4 v[160:161], off
	s_mov_b32 m0, s76
	v_lshl_add_u64 v[160:161], v[232:233], 0, s[36:37]
	global_load_lds_dwordx4 v[160:161], off
	s_mov_b32 m0, s77
	v_lshl_add_u64 v[160:161], v[234:235], 0, s[36:37]
	global_load_lds_dwordx4 v[160:161], off
	s_waitcnt vmcnt(8)
	s_waitcnt lgkmcnt(0)
	s_barrier
	s_waitcnt lgkmcnt(0)
	v_mfma_f32_16x16x32_bf16 v[60:63], v[128:131], v[184:187], v[60:63]
	v_mfma_f32_16x16x32_bf16 v[60:63], v[132:135], v[188:191], v[60:63]
	v_mfma_f32_16x16x32_bf16 v[56:59], v[140:143], v[188:191], v[56:59]
	v_mfma_f32_16x16x32_bf16 v[56:59], v[136:139], v[184:187], v[56:59]
	v_mfma_f32_16x16x32_bf16 v[52:55], v[144:147], v[184:187], v[52:55]
	v_mfma_f32_16x16x32_bf16 v[52:55], v[148:151], v[188:191], v[52:55]
	v_mfma_f32_16x16x32_bf16 v[48:51], v[156:159], v[188:191], v[48:51]
	v_mfma_f32_16x16x32_bf16 v[48:51], v[152:155], v[184:187], v[48:51]
	v_mfma_f32_16x16x32_bf16 v[32:35], v[152:155], v[192:195], v[32:35]
	v_mfma_f32_16x16x32_bf16 v[32:35], v[156:159], v[196:199], v[32:35]
	v_mfma_f32_16x16x32_bf16 v[36:39], v[148:151], v[196:199], v[36:39]
	v_mfma_f32_16x16x32_bf16 v[36:39], v[144:147], v[192:195], v[36:39]
	v_mfma_f32_16x16x32_bf16 v[40:43], v[136:139], v[192:195], v[40:43]
	v_mfma_f32_16x16x32_bf16 v[40:43], v[140:143], v[196:199], v[40:43]
	v_mfma_f32_16x16x32_bf16 v[44:47], v[132:135], v[196:199], v[44:47]
	v_mfma_f32_16x16x32_bf16 v[44:47], v[128:131], v[192:195], v[44:47]
	v_mfma_f32_16x16x32_bf16 v[28:31], v[128:131], v[200:203], v[28:31]
	v_mfma_f32_16x16x32_bf16 v[28:31], v[132:135], v[204:207], v[28:31]
	v_mfma_f32_16x16x32_bf16 v[24:27], v[140:143], v[204:207], v[24:27]
	v_mfma_f32_16x16x32_bf16 v[24:27], v[136:139], v[200:203], v[24:27]
	v_mfma_f32_16x16x32_bf16 v[20:23], v[144:147], v[200:203], v[20:23]
	v_mfma_f32_16x16x32_bf16 v[20:23], v[148:151], v[204:207], v[20:23]
	v_mfma_f32_16x16x32_bf16 v[16:19], v[156:159], v[204:207], v[16:19]
	v_mfma_f32_16x16x32_bf16 v[16:19], v[152:155], v[200:203], v[16:19]
	v_mfma_f32_16x16x32_bf16 v[0:3], v[152:155], v[208:211], v[0:3]
	v_mfma_f32_16x16x32_bf16 v[0:3], v[156:159], v[212:215], v[0:3]
	v_mfma_f32_16x16x32_bf16 v[4:7], v[148:151], v[212:215], v[4:7]
	v_mfma_f32_16x16x32_bf16 v[4:7], v[144:147], v[208:211], v[4:7]
	v_mfma_f32_16x16x32_bf16 v[8:11], v[136:139], v[208:211], v[8:11]
	v_mfma_f32_16x16x32_bf16 v[8:11], v[140:143], v[212:215], v[8:11]
	v_mfma_f32_16x16x32_bf16 v[12:15], v[132:135], v[212:215], v[12:15]
	v_mfma_f32_16x16x32_bf16 v[12:15], v[128:131], v[208:211], v[12:15]
	s_add_u32 s0, s0, 0x100
	s_addc_u32 s1, s1, 0
	s_add_u32 s33, s33, 0x100
	s_addc_u32 s52, s52, 0
	s_cmp_ge_i32 s53, s75
	s_mov_b32 s50, s53
	s_barrier
	s_cbranch_scc0 .LBB0_323

.LBB0_592:
	ds_read_b128 v[144:147], v157
	ds_read_b128 v[148:151], v157 offset:1024
	ds_read_b128 v[164:167], v157 offset:2048
	ds_read_b128 v[168:171], v157 offset:3072
	ds_read_b128 v[172:175], v158
	ds_read_b128 v[176:179], v158 offset:1024
	ds_read_b128 v[180:183], v158 offset:2048
	ds_read_b128 v[184:187], v158 offset:3072
	s_add_i32 s64, s34, 2
	s_add_u32 s65, s30, 0x80
	s_addc_u32 s35, s31, 0
	s_cmp_eq_u32 s49, s34
	s_cselect_b32 s34, s2, s65
	s_cselect_b32 s35, s3, s35
	s_cselect_b32 s67, s29, s63
	s_cselect_b32 s66, s28, s62
	v_lshl_add_u64 v[152:153], s[30:31], 0, v[136:137]
	s_add_i32 m0, s41, 0xc000
	ds_read_b128 v[188:191], v159
	ds_read_b128 v[192:195], v159 offset:1024
	ds_read_b128 v[196:199], v159 offset:2048
	ds_read_b128 v[200:203], v159 offset:3072
	ds_read_b128 v[204:207], v159 offset:4096
	ds_read_b128 v[208:211], v159 offset:5120
	ds_read_b128 v[212:215], v159 offset:6144
	ds_read_b128 v[216:219], v159 offset:7168
	global_load_lds_dwordx4 v[152:153], off
	s_add_i32 m0, s41, 0xe000
	v_lshl_add_u64 v[152:153], s[30:31], 0, v[138:139]
	global_load_lds_dwordx4 v[152:153], off
	s_waitcnt vmcnt(8)
	s_waitcnt lgkmcnt(0)
	s_barrier
	s_waitcnt lgkmcnt(0)
	v_mfma_f32_16x16x32_bf16 v[120:123], v[144:147], v[188:191], v[120:123]
	v_mfma_f32_16x16x32_bf16 v[120:123], v[148:151], v[192:195], v[120:123]
	v_mfma_f32_16x16x32_bf16 v[124:127], v[168:171], v[192:195], v[124:127]
	v_mfma_f32_16x16x32_bf16 v[124:127], v[164:167], v[188:191], v[124:127]
	v_mfma_f32_16x16x32_bf16 v[116:119], v[172:175], v[188:191], v[116:119]
	v_mfma_f32_16x16x32_bf16 v[116:119], v[176:179], v[192:195], v[116:119]
	v_mfma_f32_16x16x32_bf16 v[112:115], v[184:187], v[192:195], v[112:115]
	v_mfma_f32_16x16x32_bf16 v[112:115], v[180:183], v[188:191], v[112:115]
	v_mfma_f32_16x16x32_bf16 v[96:99], v[180:183], v[196:199], v[96:99]
	v_mfma_f32_16x16x32_bf16 v[96:99], v[184:187], v[200:203], v[96:99]
	v_mfma_f32_16x16x32_bf16 v[100:103], v[176:179], v[200:203], v[100:103]
	v_mfma_f32_16x16x32_bf16 v[100:103], v[172:175], v[196:199], v[100:103]
	v_mfma_f32_16x16x32_bf16 v[104:107], v[164:167], v[196:199], v[104:107]
	v_mfma_f32_16x16x32_bf16 v[104:107], v[168:171], v[200:203], v[104:107]
	v_mfma_f32_16x16x32_bf16 v[108:111], v[148:151], v[200:203], v[108:111]
	v_mfma_f32_16x16x32_bf16 v[108:111], v[144:147], v[196:199], v[108:111]
	v_mfma_f32_16x16x32_bf16 v[92:95], v[144:147], v[204:207], v[92:95]
	v_mfma_f32_16x16x32_bf16 v[92:95], v[148:151], v[208:211], v[92:95]
	v_mfma_f32_16x16x32_bf16 v[88:91], v[168:171], v[208:211], v[88:91]
	v_mfma_f32_16x16x32_bf16 v[88:91], v[164:167], v[204:207], v[88:91]
	v_mfma_f32_16x16x32_bf16 v[84:87], v[172:175], v[204:207], v[84:87]
	v_mfma_f32_16x16x32_bf16 v[84:87], v[176:179], v[208:211], v[84:87]
	v_mfma_f32_16x16x32_bf16 v[80:83], v[184:187], v[208:211], v[80:83]
	v_mfma_f32_16x16x32_bf16 v[80:83], v[180:183], v[204:207], v[80:83]
	v_mfma_f32_16x16x32_bf16 v[64:67], v[180:183], v[212:215], v[64:67]
	v_mfma_f32_16x16x32_bf16 v[64:67], v[184:187], v[216:219], v[64:67]
	v_mfma_f32_16x16x32_bf16 v[68:71], v[176:179], v[216:219], v[68:71]
	v_mfma_f32_16x16x32_bf16 v[68:71], v[172:175], v[212:215], v[68:71]
	v_mfma_f32_16x16x32_bf16 v[72:75], v[164:167], v[212:215], v[72:75]
	v_mfma_f32_16x16x32_bf16 v[72:75], v[168:171], v[216:219], v[72:75]
	v_mfma_f32_16x16x32_bf16 v[76:79], v[148:151], v[216:219], v[76:79]
	v_mfma_f32_16x16x32_bf16 v[76:79], v[144:147], v[212:215], v[76:79]
	s_barrier
	s_add_i32 s65, s52, s40
	v_lshl_add_u64 v[152:153], s[66:67], 0, v[130:131]
	s_mov_b32 m0, s65
	ds_read_b128 v[188:191], v159 offset:16384
	ds_read_b128 v[192:195], v159 offset:17408
	ds_read_b128 v[196:199], v159 offset:18432
	ds_read_b128 v[200:203], v159 offset:19456
	ds_read_b128 v[204:207], v159 offset:20480
	ds_read_b128 v[208:211], v159 offset:21504
	ds_read_b128 v[212:215], v159 offset:22528
	ds_read_b128 v[216:219], v159 offset:23552
	global_load_lds_dwordx4 v[152:153], off
	s_add_i32 m0, s65, 0x2000
	v_lshl_add_u64 v[160:161], s[66:67], 0, v[134:135]
	s_add_u32 s66, s66, s8
	s_addc_u32 s67, s67, s9
	s_add_i32 s65, s53, s40
	global_load_lds_dwordx4 v[160:161], off
	v_lshl_add_u64 v[222:223], s[66:67], 0, v[130:131]
	s_mov_b32 m0, s65
	v_lshl_add_u64 v[224:225], s[66:67], 0, v[134:135]
	global_load_lds_dwordx4 v[222:223], off
	s_add_i32 m0, s65, 0x2000
	v_lshl_add_u64 v[226:227], s[34:35], 0, v[128:129]
	global_load_lds_dwordx4 v[224:225], off
	s_mov_b32 m0, s41
	v_lshl_add_u64 v[228:229], s[34:35], 0, v[132:133]
	global_load_lds_dwordx4 v[226:227], off
	s_mov_b32 m0, s42
	s_nop 0
	global_load_lds_dwordx4 v[228:229], off
	s_waitcnt vmcnt(8)
	s_waitcnt lgkmcnt(0)
	s_barrier
	s_waitcnt lgkmcnt(0)
	v_mfma_f32_16x16x32_bf16 v[60:63], v[144:147], v[188:191], v[60:63]
	v_mfma_f32_16x16x32_bf16 v[60:63], v[148:151], v[192:195], v[60:63]
	v_mfma_f32_16x16x32_bf16 v[56:59], v[168:171], v[192:195], v[56:59]
	v_mfma_f32_16x16x32_bf16 v[56:59], v[164:167], v[188:191], v[56:59]
	v_mfma_f32_16x16x32_bf16 v[52:55], v[172:175], v[188:191], v[52:55]
	v_mfma_f32_16x16x32_bf16 v[52:55], v[176:179], v[192:195], v[52:55]
	v_mfma_f32_16x16x32_bf16 v[48:51], v[184:187], v[192:195], v[48:51]
	v_mfma_f32_16x16x32_bf16 v[48:51], v[180:183], v[188:191], v[48:51]
	v_mfma_f32_16x16x32_bf16 v[32:35], v[180:183], v[196:199], v[32:35]
	v_mfma_f32_16x16x32_bf16 v[32:35], v[184:187], v[200:203], v[32:35]
	v_mfma_f32_16x16x32_bf16 v[36:39], v[176:179], v[200:203], v[36:39]
	v_mfma_f32_16x16x32_bf16 v[36:39], v[172:175], v[196:199], v[36:39]
	v_mfma_f32_16x16x32_bf16 v[40:43], v[164:167], v[196:199], v[40:43]
	v_mfma_f32_16x16x32_bf16 v[40:43], v[168:171], v[200:203], v[40:43]
	v_mfma_f32_16x16x32_bf16 v[44:47], v[148:151], v[200:203], v[44:47]
	v_mfma_f32_16x16x32_bf16 v[44:47], v[144:147], v[196:199], v[44:47]
	v_mfma_f32_16x16x32_bf16 v[28:31], v[144:147], v[204:207], v[28:31]
	v_mfma_f32_16x16x32_bf16 v[28:31], v[148:151], v[208:211], v[28:31]
	v_mfma_f32_16x16x32_bf16 v[24:27], v[168:171], v[208:211], v[24:27]
	v_mfma_f32_16x16x32_bf16 v[24:27], v[164:167], v[204:207], v[24:27]
	v_mfma_f32_16x16x32_bf16 v[20:23], v[172:175], v[204:207], v[20:23]
	v_mfma_f32_16x16x32_bf16 v[20:23], v[176:179], v[208:211], v[20:23]
	v_mfma_f32_16x16x32_bf16 v[16:19], v[184:187], v[208:211], v[16:19]
	v_mfma_f32_16x16x32_bf16 v[16:19], v[180:183], v[204:207], v[16:19]
	v_mfma_f32_16x16x32_bf16 v[0:3], v[180:183], v[212:215], v[0:3]
	v_mfma_f32_16x16x32_bf16 v[0:3], v[184:187], v[216:219], v[0:3]
	v_mfma_f32_16x16x32_bf16 v[4:7], v[176:179], v[216:219], v[4:7]
	v_mfma_f32_16x16x32_bf16 v[4:7], v[172:175], v[212:215], v[4:7]
	v_mfma_f32_16x16x32_bf16 v[8:11], v[164:167], v[212:215], v[8:11]
	v_mfma_f32_16x16x32_bf16 v[8:11], v[168:171], v[216:219], v[8:11]
	v_mfma_f32_16x16x32_bf16 v[12:15], v[148:151], v[216:219], v[12:15]
	v_mfma_f32_16x16x32_bf16 v[12:15], v[144:147], v[212:215], v[12:15]
	s_barrier
	s_add_i32 s65, 0, 0x18000
	s_add_i32 s66, 0, 0x1c000
	v_add_u32_e32 v168, s65, v155
	v_add_u32_e32 v184, s66, v155
	ds_read_b128 v[144:147], v168
	ds_read_b128 v[148:151], v168 offset:1024
	ds_read_b128 v[164:167], v168 offset:2048
	ds_read_b128 v[168:171], v168 offset:3072
	ds_read_b128 v[172:175], v184
	ds_read_b128 v[176:179], v184 offset:1024
	ds_read_b128 v[180:183], v184 offset:2048
	ds_read_b128 v[184:187], v184 offset:3072
	s_add_u32 s34, s34, s8
	s_addc_u32 s35, s35, s9
	s_mov_b32 m0, s43
	v_lshl_add_u64 v[230:231], s[34:35], 0, v[128:129]
	ds_read_b128 v[188:191], v159 offset:32768
	ds_read_b128 v[192:195], v159 offset:33792
	ds_read_b128 v[196:199], v159 offset:34816
	ds_read_b128 v[200:203], v159 offset:35840
	ds_read_b128 v[204:207], v159 offset:36864
	ds_read_b128 v[208:211], v159 offset:37888
	ds_read_b128 v[212:215], v159 offset:38912
	ds_read_b128 v[216:219], v159 offset:39936
	global_load_lds_dwordx4 v[230:231], off
	s_mov_b32 m0, s44
	v_lshl_add_u64 v[230:231], s[34:35], 0, v[132:133]
	global_load_lds_dwordx4 v[230:231], off
	s_waitcnt vmcnt(8)
	s_waitcnt lgkmcnt(0)
	s_barrier
	s_waitcnt lgkmcnt(0)
	v_mfma_f32_16x16x32_bf16 v[120:123], v[144:147], v[188:191], v[120:123]
	v_mfma_f32_16x16x32_bf16 v[120:123], v[148:151], v[192:195], v[120:123]
	v_mfma_f32_16x16x32_bf16 v[124:127], v[168:171], v[192:195], v[124:127]
	v_mfma_f32_16x16x32_bf16 v[124:127], v[164:167], v[188:191], v[124:127]
	v_mfma_f32_16x16x32_bf16 v[116:119], v[172:175], v[188:191], v[116:119]
	v_mfma_f32_16x16x32_bf16 v[116:119], v[176:179], v[192:195], v[116:119]
	v_mfma_f32_16x16x32_bf16 v[112:115], v[184:187], v[192:195], v[112:115]
	v_mfma_f32_16x16x32_bf16 v[112:115], v[180:183], v[188:191], v[112:115]
	v_mfma_f32_16x16x32_bf16 v[96:99], v[180:183], v[196:199], v[96:99]
	v_mfma_f32_16x16x32_bf16 v[96:99], v[184:187], v[200:203], v[96:99]
	v_mfma_f32_16x16x32_bf16 v[100:103], v[176:179], v[200:203], v[100:103]
	v_mfma_f32_16x16x32_bf16 v[100:103], v[172:175], v[196:199], v[100:103]
	v_mfma_f32_16x16x32_bf16 v[104:107], v[164:167], v[196:199], v[104:107]
	v_mfma_f32_16x16x32_bf16 v[104:107], v[168:171], v[200:203], v[104:107]
	v_mfma_f32_16x16x32_bf16 v[108:111], v[148:151], v[200:203], v[108:111]
	v_mfma_f32_16x16x32_bf16 v[108:111], v[144:147], v[196:199], v[108:111]
	v_mfma_f32_16x16x32_bf16 v[92:95], v[144:147], v[204:207], v[92:95]
	v_mfma_f32_16x16x32_bf16 v[92:95], v[148:151], v[208:211], v[92:95]
	v_mfma_f32_16x16x32_bf16 v[88:91], v[168:171], v[208:211], v[88:91]
	v_mfma_f32_16x16x32_bf16 v[88:91], v[164:167], v[204:207], v[88:91]
	v_mfma_f32_16x16x32_bf16 v[84:87], v[172:175], v[204:207], v[84:87]
	v_mfma_f32_16x16x32_bf16 v[84:87], v[176:179], v[208:211], v[84:87]
	v_mfma_f32_16x16x32_bf16 v[80:83], v[184:187], v[208:211], v[80:83]
	v_mfma_f32_16x16x32_bf16 v[80:83], v[180:183], v[204:207], v[80:83]
	v_mfma_f32_16x16x32_bf16 v[64:67], v[180:183], v[212:215], v[64:67]
	v_mfma_f32_16x16x32_bf16 v[64:67], v[184:187], v[216:219], v[64:67]
	v_mfma_f32_16x16x32_bf16 v[68:71], v[176:179], v[216:219], v[68:71]
	v_mfma_f32_16x16x32_bf16 v[68:71], v[172:175], v[212:215], v[68:71]
	v_mfma_f32_16x16x32_bf16 v[72:75], v[164:167], v[212:215], v[72:75]
	v_mfma_f32_16x16x32_bf16 v[72:75], v[168:171], v[216:219], v[72:75]
	v_mfma_f32_16x16x32_bf16 v[76:79], v[148:151], v[216:219], v[76:79]
	v_mfma_f32_16x16x32_bf16 v[76:79], v[144:147], v[212:215], v[76:79]
	s_barrier
	s_add_i32 s34, s65, s40
	v_lshl_add_u64 v[152:153], v[152:153], 0, s[14:15]
	s_mov_b32 m0, s34
	ds_read_b128 v[188:191], v159 offset:49152
	ds_read_b128 v[192:195], v159 offset:50176
	ds_read_b128 v[196:199], v159 offset:51200
	ds_read_b128 v[200:203], v159 offset:52224
	ds_read_b128 v[204:207], v159 offset:53248
	ds_read_b128 v[208:211], v159 offset:54272
	ds_read_b128 v[212:215], v159 offset:55296
	ds_read_b128 v[216:219], v159 offset:56320
	global_load_lds_dwordx4 v[152:153], off
	v_lshl_add_u64 v[152:153], v[160:161], 0, s[14:15]
	s_add_i32 m0, s34, 0x2000
	s_add_i32 s34, s66, s40
	global_load_lds_dwordx4 v[152:153], off
	s_mov_b32 m0, s34
	v_lshl_add_u64 v[152:153], v[222:223], 0, s[14:15]
	global_load_lds_dwordx4 v[152:153], off
	s_add_i32 m0, s34, 0x2000
	v_lshl_add_u64 v[152:153], v[224:225], 0, s[14:15]
	global_load_lds_dwordx4 v[152:153], off
	s_mov_b32 m0, s46
	v_lshl_add_u64 v[152:153], v[226:227], 0, s[14:15]
	global_load_lds_dwordx4 v[152:153], off
	s_mov_b32 m0, s47
	v_lshl_add_u64 v[152:153], v[228:229], 0, s[14:15]
	global_load_lds_dwordx4 v[152:153], off
	s_waitcnt vmcnt(8)
	s_waitcnt lgkmcnt(0)
	s_barrier
	s_waitcnt lgkmcnt(0)
	v_mfma_f32_16x16x32_bf16 v[60:63], v[144:147], v[188:191], v[60:63]
	v_mfma_f32_16x16x32_bf16 v[60:63], v[148:151], v[192:195], v[60:63]
	v_mfma_f32_16x16x32_bf16 v[56:59], v[168:171], v[192:195], v[56:59]
	v_mfma_f32_16x16x32_bf16 v[56:59], v[164:167], v[188:191], v[56:59]
	v_mfma_f32_16x16x32_bf16 v[52:55], v[172:175], v[188:191], v[52:55]
	v_mfma_f32_16x16x32_bf16 v[52:55], v[176:179], v[192:195], v[52:55]
	v_mfma_f32_16x16x32_bf16 v[48:51], v[184:187], v[192:195], v[48:51]
	v_mfma_f32_16x16x32_bf16 v[48:51], v[180:183], v[188:191], v[48:51]
	v_mfma_f32_16x16x32_bf16 v[32:35], v[180:183], v[196:199], v[32:35]
	v_mfma_f32_16x16x32_bf16 v[32:35], v[184:187], v[200:203], v[32:35]
	v_mfma_f32_16x16x32_bf16 v[36:39], v[176:179], v[200:203], v[36:39]
	v_mfma_f32_16x16x32_bf16 v[36:39], v[172:175], v[196:199], v[36:39]
	v_mfma_f32_16x16x32_bf16 v[40:43], v[164:167], v[196:199], v[40:43]
	v_mfma_f32_16x16x32_bf16 v[40:43], v[168:171], v[200:203], v[40:43]
	v_mfma_f32_16x16x32_bf16 v[44:47], v[148:151], v[200:203], v[44:47]
	v_mfma_f32_16x16x32_bf16 v[44:47], v[144:147], v[196:199], v[44:47]
	v_mfma_f32_16x16x32_bf16 v[28:31], v[144:147], v[204:207], v[28:31]
	v_mfma_f32_16x16x32_bf16 v[28:31], v[148:151], v[208:211], v[28:31]
	v_mfma_f32_16x16x32_bf16 v[24:27], v[168:171], v[208:211], v[24:27]
	v_mfma_f32_16x16x32_bf16 v[24:27], v[164:167], v[204:207], v[24:27]
	v_mfma_f32_16x16x32_bf16 v[20:23], v[172:175], v[204:207], v[20:23]
	v_mfma_f32_16x16x32_bf16 v[20:23], v[176:179], v[208:211], v[20:23]
	v_mfma_f32_16x16x32_bf16 v[16:19], v[184:187], v[208:211], v[16:19]
	v_mfma_f32_16x16x32_bf16 v[16:19], v[180:183], v[204:207], v[16:19]
	v_mfma_f32_16x16x32_bf16 v[0:3], v[180:183], v[212:215], v[0:3]
	v_mfma_f32_16x16x32_bf16 v[0:3], v[184:187], v[216:219], v[0:3]
	v_mfma_f32_16x16x32_bf16 v[4:7], v[176:179], v[216:219], v[4:7]
	v_mfma_f32_16x16x32_bf16 v[4:7], v[172:175], v[212:215], v[4:7]
	v_mfma_f32_16x16x32_bf16 v[8:11], v[164:167], v[212:215], v[8:11]
	v_mfma_f32_16x16x32_bf16 v[8:11], v[168:171], v[216:219], v[8:11]
	v_mfma_f32_16x16x32_bf16 v[12:15], v[148:151], v[216:219], v[12:15]
	v_mfma_f32_16x16x32_bf16 v[12:15], v[144:147], v[212:215], v[12:15]
	s_add_u32 s30, s30, 0x100
	s_addc_u32 s31, s31, 0
	s_add_u32 s62, s62, 0x100
	s_addc_u32 s63, s63, 0
	s_cmp_ge_i32 s64, s48
	s_mov_b32 s34, s64
	s_barrier
	s_cbranch_scc0 .LBB0_592

.LBB0_763:
	ds_read_b128 v[128:131], v181
	ds_read_b128 v[132:135], v181 offset:1024
	ds_read_b128 v[136:139], v181 offset:2048
	ds_read_b128 v[140:143], v181 offset:3072
	ds_read_b128 v[144:147], v182
	ds_read_b128 v[148:151], v182 offset:1024
	ds_read_b128 v[168:171], v182 offset:2048
	ds_read_b128 v[172:175], v182 offset:3072
	s_add_i32 s54, s26, 2
	s_add_u32 s55, s24, 0x80
	s_addc_u32 s27, s25, 0
	s_cmp_eq_u32 s43, s26
	s_cselect_b32 s26, s2, s55
	s_cselect_b32 s27, s3, s27
	s_cselect_b32 s61, s23, s53
	s_cselect_b32 s60, s22, s52
	v_lshl_add_u64 v[176:177], s[24:25], 0, v[160:161]
	s_add_i32 m0, s35, 0xc000
	ds_read_b128 v[184:187], v183
	ds_read_b128 v[188:191], v183 offset:1024
	ds_read_b128 v[192:195], v183 offset:2048
	ds_read_b128 v[196:199], v183 offset:3072
	ds_read_b128 v[200:203], v183 offset:4096
	ds_read_b128 v[204:207], v183 offset:5120
	ds_read_b128 v[208:211], v183 offset:6144
	ds_read_b128 v[212:215], v183 offset:7168
	global_load_lds_dwordx4 v[176:177], off
	s_add_i32 m0, s35, 0xe000
	v_lshl_add_u64 v[176:177], s[24:25], 0, v[162:163]
	global_load_lds_dwordx4 v[176:177], off
	s_waitcnt vmcnt(8)
	s_waitcnt lgkmcnt(0)
	s_barrier
	s_waitcnt lgkmcnt(0)
	v_mfma_f32_16x16x32_bf16 v[120:123], v[128:131], v[184:187], v[120:123]
	v_mfma_f32_16x16x32_bf16 v[120:123], v[132:135], v[188:191], v[120:123]
	v_mfma_f32_16x16x32_bf16 v[124:127], v[140:143], v[188:191], v[124:127]
	v_mfma_f32_16x16x32_bf16 v[124:127], v[136:139], v[184:187], v[124:127]
	v_mfma_f32_16x16x32_bf16 v[116:119], v[144:147], v[184:187], v[116:119]
	v_mfma_f32_16x16x32_bf16 v[116:119], v[148:151], v[188:191], v[116:119]
	v_mfma_f32_16x16x32_bf16 v[112:115], v[172:175], v[188:191], v[112:115]
	v_mfma_f32_16x16x32_bf16 v[112:115], v[168:171], v[184:187], v[112:115]
	v_mfma_f32_16x16x32_bf16 v[96:99], v[168:171], v[192:195], v[96:99]
	v_mfma_f32_16x16x32_bf16 v[96:99], v[172:175], v[196:199], v[96:99]
	v_mfma_f32_16x16x32_bf16 v[100:103], v[148:151], v[196:199], v[100:103]
	v_mfma_f32_16x16x32_bf16 v[100:103], v[144:147], v[192:195], v[100:103]
	v_mfma_f32_16x16x32_bf16 v[104:107], v[136:139], v[192:195], v[104:107]
	v_mfma_f32_16x16x32_bf16 v[104:107], v[140:143], v[196:199], v[104:107]
	v_mfma_f32_16x16x32_bf16 v[108:111], v[132:135], v[196:199], v[108:111]
	v_mfma_f32_16x16x32_bf16 v[108:111], v[128:131], v[192:195], v[108:111]
	v_mfma_f32_16x16x32_bf16 v[92:95], v[128:131], v[200:203], v[92:95]
	v_mfma_f32_16x16x32_bf16 v[92:95], v[132:135], v[204:207], v[92:95]
	v_mfma_f32_16x16x32_bf16 v[88:91], v[140:143], v[204:207], v[88:91]
	v_mfma_f32_16x16x32_bf16 v[88:91], v[136:139], v[200:203], v[88:91]
	v_mfma_f32_16x16x32_bf16 v[84:87], v[144:147], v[200:203], v[84:87]
	v_mfma_f32_16x16x32_bf16 v[84:87], v[148:151], v[204:207], v[84:87]
	v_mfma_f32_16x16x32_bf16 v[80:83], v[172:175], v[204:207], v[80:83]
	v_mfma_f32_16x16x32_bf16 v[80:83], v[168:171], v[200:203], v[80:83]
	v_mfma_f32_16x16x32_bf16 v[64:67], v[168:171], v[208:211], v[64:67]
	v_mfma_f32_16x16x32_bf16 v[64:67], v[172:175], v[212:215], v[64:67]
	v_mfma_f32_16x16x32_bf16 v[68:71], v[148:151], v[212:215], v[68:71]
	v_mfma_f32_16x16x32_bf16 v[68:71], v[144:147], v[208:211], v[68:71]
	v_mfma_f32_16x16x32_bf16 v[72:75], v[136:139], v[208:211], v[72:75]
	v_mfma_f32_16x16x32_bf16 v[72:75], v[140:143], v[212:215], v[72:75]
	v_mfma_f32_16x16x32_bf16 v[76:79], v[132:135], v[212:215], v[76:79]
	v_mfma_f32_16x16x32_bf16 v[76:79], v[128:131], v[208:211], v[76:79]
	s_barrier
	s_add_i32 s55, s46, s34
	v_lshl_add_u64 v[176:177], s[60:61], 0, v[154:155]
	s_mov_b32 m0, s55
	ds_read_b128 v[184:187], v183 offset:16384
	ds_read_b128 v[188:191], v183 offset:17408
	ds_read_b128 v[192:195], v183 offset:18432
	ds_read_b128 v[196:199], v183 offset:19456
	ds_read_b128 v[200:203], v183 offset:20480
	ds_read_b128 v[204:207], v183 offset:21504
	ds_read_b128 v[208:211], v183 offset:22528
	ds_read_b128 v[212:215], v183 offset:23552
	global_load_lds_dwordx4 v[176:177], off
	s_add_i32 m0, s55, 0x2000
	v_lshl_add_u64 v[216:217], s[60:61], 0, v[158:159]
	s_add_u32 s60, s60, s8
	s_addc_u32 s61, s61, s9
	s_add_i32 s55, s47, s34
	global_load_lds_dwordx4 v[216:217], off
	v_lshl_add_u64 v[218:219], s[60:61], 0, v[154:155]
	s_mov_b32 m0, s55
	v_lshl_add_u64 v[222:223], s[60:61], 0, v[158:159]
	global_load_lds_dwordx4 v[218:219], off
	s_add_i32 m0, s55, 0x2000
	v_lshl_add_u64 v[224:225], s[26:27], 0, v[152:153]
	global_load_lds_dwordx4 v[222:223], off
	s_mov_b32 m0, s35
	v_lshl_add_u64 v[226:227], s[26:27], 0, v[156:157]
	global_load_lds_dwordx4 v[224:225], off
	s_mov_b32 m0, s36
	s_nop 0
	global_load_lds_dwordx4 v[226:227], off
	s_waitcnt vmcnt(8)
	s_waitcnt lgkmcnt(0)
	s_barrier
	s_waitcnt lgkmcnt(0)
	v_mfma_f32_16x16x32_bf16 v[60:63], v[128:131], v[184:187], v[60:63]
	v_mfma_f32_16x16x32_bf16 v[60:63], v[132:135], v[188:191], v[60:63]
	v_mfma_f32_16x16x32_bf16 v[56:59], v[140:143], v[188:191], v[56:59]
	v_mfma_f32_16x16x32_bf16 v[56:59], v[136:139], v[184:187], v[56:59]
	v_mfma_f32_16x16x32_bf16 v[52:55], v[144:147], v[184:187], v[52:55]
	v_mfma_f32_16x16x32_bf16 v[52:55], v[148:151], v[188:191], v[52:55]
	v_mfma_f32_16x16x32_bf16 v[48:51], v[172:175], v[188:191], v[48:51]
	v_mfma_f32_16x16x32_bf16 v[48:51], v[168:171], v[184:187], v[48:51]
	v_mfma_f32_16x16x32_bf16 v[32:35], v[168:171], v[192:195], v[32:35]
	v_mfma_f32_16x16x32_bf16 v[32:35], v[172:175], v[196:199], v[32:35]
	v_mfma_f32_16x16x32_bf16 v[36:39], v[148:151], v[196:199], v[36:39]
	v_mfma_f32_16x16x32_bf16 v[36:39], v[144:147], v[192:195], v[36:39]
	v_mfma_f32_16x16x32_bf16 v[40:43], v[136:139], v[192:195], v[40:43]
	v_mfma_f32_16x16x32_bf16 v[40:43], v[140:143], v[196:199], v[40:43]
	v_mfma_f32_16x16x32_bf16 v[44:47], v[132:135], v[196:199], v[44:47]
	v_mfma_f32_16x16x32_bf16 v[44:47], v[128:131], v[192:195], v[44:47]
	v_mfma_f32_16x16x32_bf16 v[28:31], v[128:131], v[200:203], v[28:31]
	v_mfma_f32_16x16x32_bf16 v[28:31], v[132:135], v[204:207], v[28:31]
	v_mfma_f32_16x16x32_bf16 v[24:27], v[140:143], v[204:207], v[24:27]
	v_mfma_f32_16x16x32_bf16 v[24:27], v[136:139], v[200:203], v[24:27]
	v_mfma_f32_16x16x32_bf16 v[20:23], v[144:147], v[200:203], v[20:23]
	v_mfma_f32_16x16x32_bf16 v[20:23], v[148:151], v[204:207], v[20:23]
	v_mfma_f32_16x16x32_bf16 v[16:19], v[172:175], v[204:207], v[16:19]
	v_mfma_f32_16x16x32_bf16 v[16:19], v[168:171], v[200:203], v[16:19]
	v_mfma_f32_16x16x32_bf16 v[0:3], v[168:171], v[208:211], v[0:3]
	v_mfma_f32_16x16x32_bf16 v[0:3], v[172:175], v[212:215], v[0:3]
	v_mfma_f32_16x16x32_bf16 v[4:7], v[148:151], v[212:215], v[4:7]
	v_mfma_f32_16x16x32_bf16 v[4:7], v[144:147], v[208:211], v[4:7]
	v_mfma_f32_16x16x32_bf16 v[8:11], v[136:139], v[208:211], v[8:11]
	v_mfma_f32_16x16x32_bf16 v[8:11], v[140:143], v[212:215], v[8:11]
	v_mfma_f32_16x16x32_bf16 v[12:15], v[132:135], v[212:215], v[12:15]
	v_mfma_f32_16x16x32_bf16 v[12:15], v[128:131], v[208:211], v[12:15]
	s_barrier
	s_add_i32 s55, 0, 0x18000
	s_add_i32 s60, 0, 0x1c000
	v_add_u32_e32 v140, s55, v179
	v_add_u32_e32 v172, s60, v179
	ds_read_b128 v[128:131], v140
	ds_read_b128 v[132:135], v140 offset:1024
	ds_read_b128 v[136:139], v140 offset:2048
	ds_read_b128 v[140:143], v140 offset:3072
	ds_read_b128 v[144:147], v172
	ds_read_b128 v[148:151], v172 offset:1024
	ds_read_b128 v[168:171], v172 offset:2048
	ds_read_b128 v[172:175], v172 offset:3072
	s_add_u32 s26, s26, s8
	s_addc_u32 s27, s27, s9
	s_mov_b32 m0, s37
	v_lshl_add_u64 v[228:229], s[26:27], 0, v[152:153]
	ds_read_b128 v[184:187], v183 offset:32768
	ds_read_b128 v[188:191], v183 offset:33792
	ds_read_b128 v[192:195], v183 offset:34816
	ds_read_b128 v[196:199], v183 offset:35840
	ds_read_b128 v[200:203], v183 offset:36864
	ds_read_b128 v[204:207], v183 offset:37888
	ds_read_b128 v[208:211], v183 offset:38912
	ds_read_b128 v[212:215], v183 offset:39936
	global_load_lds_dwordx4 v[228:229], off
	s_mov_b32 m0, s38
	v_lshl_add_u64 v[228:229], s[26:27], 0, v[156:157]
	global_load_lds_dwordx4 v[228:229], off
	s_waitcnt vmcnt(8)
	s_waitcnt lgkmcnt(0)
	s_barrier
	s_waitcnt lgkmcnt(0)
	v_mfma_f32_16x16x32_bf16 v[120:123], v[128:131], v[184:187], v[120:123]
	v_mfma_f32_16x16x32_bf16 v[120:123], v[132:135], v[188:191], v[120:123]
	v_mfma_f32_16x16x32_bf16 v[124:127], v[140:143], v[188:191], v[124:127]
	v_mfma_f32_16x16x32_bf16 v[124:127], v[136:139], v[184:187], v[124:127]
	v_mfma_f32_16x16x32_bf16 v[116:119], v[144:147], v[184:187], v[116:119]
	v_mfma_f32_16x16x32_bf16 v[116:119], v[148:151], v[188:191], v[116:119]
	v_mfma_f32_16x16x32_bf16 v[112:115], v[172:175], v[188:191], v[112:115]
	v_mfma_f32_16x16x32_bf16 v[112:115], v[168:171], v[184:187], v[112:115]
	v_mfma_f32_16x16x32_bf16 v[96:99], v[168:171], v[192:195], v[96:99]
	v_mfma_f32_16x16x32_bf16 v[96:99], v[172:175], v[196:199], v[96:99]
	v_mfma_f32_16x16x32_bf16 v[100:103], v[148:151], v[196:199], v[100:103]
	v_mfma_f32_16x16x32_bf16 v[100:103], v[144:147], v[192:195], v[100:103]
	v_mfma_f32_16x16x32_bf16 v[104:107], v[136:139], v[192:195], v[104:107]
	v_mfma_f32_16x16x32_bf16 v[104:107], v[140:143], v[196:199], v[104:107]
	v_mfma_f32_16x16x32_bf16 v[108:111], v[132:135], v[196:199], v[108:111]
	v_mfma_f32_16x16x32_bf16 v[108:111], v[128:131], v[192:195], v[108:111]
	v_mfma_f32_16x16x32_bf16 v[92:95], v[128:131], v[200:203], v[92:95]
	v_mfma_f32_16x16x32_bf16 v[92:95], v[132:135], v[204:207], v[92:95]
	v_mfma_f32_16x16x32_bf16 v[88:91], v[140:143], v[204:207], v[88:91]
	v_mfma_f32_16x16x32_bf16 v[88:91], v[136:139], v[200:203], v[88:91]
	v_mfma_f32_16x16x32_bf16 v[84:87], v[144:147], v[200:203], v[84:87]
	v_mfma_f32_16x16x32_bf16 v[84:87], v[148:151], v[204:207], v[84:87]
	v_mfma_f32_16x16x32_bf16 v[80:83], v[172:175], v[204:207], v[80:83]
	v_mfma_f32_16x16x32_bf16 v[80:83], v[168:171], v[200:203], v[80:83]
	v_mfma_f32_16x16x32_bf16 v[64:67], v[168:171], v[208:211], v[64:67]
	v_mfma_f32_16x16x32_bf16 v[64:67], v[172:175], v[212:215], v[64:67]
	v_mfma_f32_16x16x32_bf16 v[68:71], v[148:151], v[212:215], v[68:71]
	v_mfma_f32_16x16x32_bf16 v[68:71], v[144:147], v[208:211], v[68:71]
	v_mfma_f32_16x16x32_bf16 v[72:75], v[136:139], v[208:211], v[72:75]
	v_mfma_f32_16x16x32_bf16 v[72:75], v[140:143], v[212:215], v[72:75]
	v_mfma_f32_16x16x32_bf16 v[76:79], v[132:135], v[212:215], v[76:79]
	v_mfma_f32_16x16x32_bf16 v[76:79], v[128:131], v[208:211], v[76:79]
	s_barrier
	s_add_i32 s26, s55, s34
	v_lshl_add_u64 v[176:177], v[176:177], 0, s[16:17]
	s_mov_b32 m0, s26
	ds_read_b128 v[184:187], v183 offset:49152
	ds_read_b128 v[188:191], v183 offset:50176
	ds_read_b128 v[192:195], v183 offset:51200
	ds_read_b128 v[196:199], v183 offset:52224
	ds_read_b128 v[200:203], v183 offset:53248
	ds_read_b128 v[204:207], v183 offset:54272
	ds_read_b128 v[208:211], v183 offset:55296
	ds_read_b128 v[212:215], v183 offset:56320
	global_load_lds_dwordx4 v[176:177], off
	v_lshl_add_u64 v[176:177], v[216:217], 0, s[16:17]
	s_add_i32 m0, s26, 0x2000
	s_add_i32 s26, s60, s34
	global_load_lds_dwordx4 v[176:177], off
	s_mov_b32 m0, s26
	v_lshl_add_u64 v[176:177], v[218:219], 0, s[16:17]
	global_load_lds_dwordx4 v[176:177], off
	s_add_i32 m0, s26, 0x2000
	v_lshl_add_u64 v[176:177], v[222:223], 0, s[16:17]
	global_load_lds_dwordx4 v[176:177], off
	s_mov_b32 m0, s40
	v_lshl_add_u64 v[176:177], v[224:225], 0, s[16:17]
	global_load_lds_dwordx4 v[176:177], off
	s_mov_b32 m0, s41
	v_lshl_add_u64 v[176:177], v[226:227], 0, s[16:17]
	global_load_lds_dwordx4 v[176:177], off
	s_waitcnt vmcnt(8)
	s_waitcnt lgkmcnt(0)
	s_barrier
	s_waitcnt lgkmcnt(0)
	v_mfma_f32_16x16x32_bf16 v[60:63], v[128:131], v[184:187], v[60:63]
	v_mfma_f32_16x16x32_bf16 v[60:63], v[132:135], v[188:191], v[60:63]
	v_mfma_f32_16x16x32_bf16 v[56:59], v[140:143], v[188:191], v[56:59]
	v_mfma_f32_16x16x32_bf16 v[56:59], v[136:139], v[184:187], v[56:59]
	v_mfma_f32_16x16x32_bf16 v[52:55], v[144:147], v[184:187], v[52:55]
	v_mfma_f32_16x16x32_bf16 v[52:55], v[148:151], v[188:191], v[52:55]
	v_mfma_f32_16x16x32_bf16 v[48:51], v[172:175], v[188:191], v[48:51]
	v_mfma_f32_16x16x32_bf16 v[48:51], v[168:171], v[184:187], v[48:51]
	v_mfma_f32_16x16x32_bf16 v[32:35], v[168:171], v[192:195], v[32:35]
	v_mfma_f32_16x16x32_bf16 v[32:35], v[172:175], v[196:199], v[32:35]
	v_mfma_f32_16x16x32_bf16 v[36:39], v[148:151], v[196:199], v[36:39]
	v_mfma_f32_16x16x32_bf16 v[36:39], v[144:147], v[192:195], v[36:39]
	v_mfma_f32_16x16x32_bf16 v[40:43], v[136:139], v[192:195], v[40:43]
	v_mfma_f32_16x16x32_bf16 v[40:43], v[140:143], v[196:199], v[40:43]
	v_mfma_f32_16x16x32_bf16 v[44:47], v[132:135], v[196:199], v[44:47]
	v_mfma_f32_16x16x32_bf16 v[44:47], v[128:131], v[192:195], v[44:47]
	v_mfma_f32_16x16x32_bf16 v[28:31], v[128:131], v[200:203], v[28:31]
	v_mfma_f32_16x16x32_bf16 v[28:31], v[132:135], v[204:207], v[28:31]
	v_mfma_f32_16x16x32_bf16 v[24:27], v[140:143], v[204:207], v[24:27]
	v_mfma_f32_16x16x32_bf16 v[24:27], v[136:139], v[200:203], v[24:27]
	v_mfma_f32_16x16x32_bf16 v[20:23], v[144:147], v[200:203], v[20:23]
	v_mfma_f32_16x16x32_bf16 v[20:23], v[148:151], v[204:207], v[20:23]
	v_mfma_f32_16x16x32_bf16 v[16:19], v[172:175], v[204:207], v[16:19]
	v_mfma_f32_16x16x32_bf16 v[16:19], v[168:171], v[200:203], v[16:19]
	v_mfma_f32_16x16x32_bf16 v[0:3], v[168:171], v[208:211], v[0:3]
	v_mfma_f32_16x16x32_bf16 v[0:3], v[172:175], v[212:215], v[0:3]
	v_mfma_f32_16x16x32_bf16 v[4:7], v[148:151], v[212:215], v[4:7]
	v_mfma_f32_16x16x32_bf16 v[4:7], v[144:147], v[208:211], v[4:7]
	v_mfma_f32_16x16x32_bf16 v[8:11], v[136:139], v[208:211], v[8:11]
	v_mfma_f32_16x16x32_bf16 v[8:11], v[140:143], v[212:215], v[8:11]
	v_mfma_f32_16x16x32_bf16 v[12:15], v[132:135], v[212:215], v[12:15]
	v_mfma_f32_16x16x32_bf16 v[12:15], v[128:131], v[208:211], v[12:15]
	s_add_u32 s24, s24, 0x100
	s_addc_u32 s25, s25, 0
	s_add_u32 s52, s52, 0x100
	s_addc_u32 s53, s53, 0
	s_cmp_ge_i32 s54, s42
	s_mov_b32 s26, s54
	s_barrier
	s_cbranch_scc0 .LBB0_763

.LBB0_849:
	ds_read_b128 v[112:115], v209
	ds_read_b128 v[116:119], v209 offset:1024
	ds_read_b128 v[120:123], v209 offset:2048
	ds_read_b128 v[128:131], v209 offset:3072
	ds_read_b128 v[144:147], v210
	ds_read_b128 v[148:151], v210 offset:1024
	ds_read_b128 v[152:155], v210 offset:2048
	ds_read_b128 v[156:159], v210 offset:3072
	s_add_i32 s62, s30, 2
	s_add_u32 s63, s28, 0x80
	s_addc_u32 s31, s29, 0
	s_cmp_eq_u32 s46, s30
	s_cselect_b32 s30, s4, s63
	s_cselect_b32 s31, s5, s31
	s_cselect_b32 s65, s27, s61
	s_cselect_b32 s64, s26, s60
	v_lshl_add_u64 v[204:205], s[28:29], 0, v[180:181]
	s_add_i32 m0, s38, 0xc000
	ds_read_b128 v[160:163], v211
	ds_read_b128 v[164:167], v211 offset:1024
	ds_read_b128 v[168:171], v211 offset:2048
	ds_read_b128 v[172:175], v211 offset:3072
	ds_read_b128 v[188:191], v211 offset:4096
	ds_read_b128 v[192:195], v211 offset:5120
	ds_read_b128 v[196:199], v211 offset:6144
	ds_read_b128 v[200:203], v211 offset:7168
	global_load_lds_dwordx4 v[204:205], off
	s_add_i32 m0, s38, 0xe000
	v_lshl_add_u64 v[204:205], s[28:29], 0, v[182:183]
	global_load_lds_dwordx4 v[204:205], off
	s_waitcnt vmcnt(8)
	s_waitcnt lgkmcnt(0)
	s_barrier
	s_waitcnt lgkmcnt(0)
	v_mfma_f32_16x16x32_bf16 v[136:139], v[112:115], v[160:163], v[136:139]
	v_mfma_f32_16x16x32_bf16 v[136:139], v[116:119], v[164:167], v[136:139]
	v_mfma_f32_16x16x32_bf16 v[140:143], v[128:131], v[164:167], v[140:143]
	v_mfma_f32_16x16x32_bf16 v[140:143], v[120:123], v[160:163], v[140:143]
	v_mfma_f32_16x16x32_bf16 v[132:135], v[144:147], v[160:163], v[132:135]
	v_mfma_f32_16x16x32_bf16 v[132:135], v[148:151], v[164:167], v[132:135]
	v_mfma_f32_16x16x32_bf16 v[124:127], v[156:159], v[164:167], v[124:127]
	v_mfma_f32_16x16x32_bf16 v[124:127], v[152:155], v[160:163], v[124:127]
	v_mfma_f32_16x16x32_bf16 v[96:99], v[152:155], v[168:171], v[96:99]
	v_mfma_f32_16x16x32_bf16 v[96:99], v[156:159], v[172:175], v[96:99]
	v_mfma_f32_16x16x32_bf16 v[100:103], v[148:151], v[172:175], v[100:103]
	v_mfma_f32_16x16x32_bf16 v[100:103], v[144:147], v[168:171], v[100:103]
	v_mfma_f32_16x16x32_bf16 v[104:107], v[120:123], v[168:171], v[104:107]
	v_mfma_f32_16x16x32_bf16 v[104:107], v[128:131], v[172:175], v[104:107]
	v_mfma_f32_16x16x32_bf16 v[108:111], v[116:119], v[172:175], v[108:111]
	v_mfma_f32_16x16x32_bf16 v[108:111], v[112:115], v[168:171], v[108:111]
	v_mfma_f32_16x16x32_bf16 v[92:95], v[112:115], v[188:191], v[92:95]
	v_mfma_f32_16x16x32_bf16 v[92:95], v[116:119], v[192:195], v[92:95]
	v_mfma_f32_16x16x32_bf16 v[88:91], v[128:131], v[192:195], v[88:91]
	v_mfma_f32_16x16x32_bf16 v[88:91], v[120:123], v[188:191], v[88:91]
	v_mfma_f32_16x16x32_bf16 v[84:87], v[144:147], v[188:191], v[84:87]
	v_mfma_f32_16x16x32_bf16 v[84:87], v[148:151], v[192:195], v[84:87]
	v_mfma_f32_16x16x32_bf16 v[80:83], v[156:159], v[192:195], v[80:83]
	v_mfma_f32_16x16x32_bf16 v[80:83], v[152:155], v[188:191], v[80:83]
	v_mfma_f32_16x16x32_bf16 v[64:67], v[152:155], v[196:199], v[64:67]
	v_mfma_f32_16x16x32_bf16 v[64:67], v[156:159], v[200:203], v[64:67]
	v_mfma_f32_16x16x32_bf16 v[68:71], v[148:151], v[200:203], v[68:71]
	v_mfma_f32_16x16x32_bf16 v[68:71], v[144:147], v[196:199], v[68:71]
	v_mfma_f32_16x16x32_bf16 v[72:75], v[120:123], v[196:199], v[72:75]
	v_mfma_f32_16x16x32_bf16 v[72:75], v[128:131], v[200:203], v[72:75]
	v_mfma_f32_16x16x32_bf16 v[76:79], v[116:119], v[200:203], v[76:79]
	v_mfma_f32_16x16x32_bf16 v[76:79], v[112:115], v[196:199], v[76:79]
	s_barrier
	s_add_i32 s63, s50, s37
	v_lshl_add_u64 v[204:205], s[64:65], 0, v[176:177]
	s_mov_b32 m0, s63
	ds_read_b128 v[160:163], v211 offset:16384
	ds_read_b128 v[164:167], v211 offset:17408
	ds_read_b128 v[168:171], v211 offset:18432
	ds_read_b128 v[172:175], v211 offset:19456
	ds_read_b128 v[188:191], v211 offset:20480
	ds_read_b128 v[192:195], v211 offset:21504
	ds_read_b128 v[196:199], v211 offset:22528
	ds_read_b128 v[200:203], v211 offset:23552
	global_load_lds_dwordx4 v[204:205], off
	s_add_i32 m0, s63, 0x2000
	v_lshl_add_u64 v[214:215], s[64:65], 0, v[178:179]
	s_add_u32 s64, s64, s10
	s_addc_u32 s65, s65, s11
	s_add_i32 s63, s51, s37
	global_load_lds_dwordx4 v[214:215], off
	v_lshl_add_u64 v[216:217], s[64:65], 0, v[176:177]
	s_mov_b32 m0, s63
	v_lshl_add_u64 v[218:219], s[64:65], 0, v[178:179]
	global_load_lds_dwordx4 v[216:217], off
	s_add_i32 m0, s63, 0x2000
	v_lshl_add_u64 v[222:223], s[30:31], 0, v[176:177]
	global_load_lds_dwordx4 v[218:219], off
	s_mov_b32 m0, s38
	v_lshl_add_u64 v[224:225], s[30:31], 0, v[178:179]
	global_load_lds_dwordx4 v[222:223], off
	s_mov_b32 m0, s39
	s_nop 0
	global_load_lds_dwordx4 v[224:225], off
	s_waitcnt vmcnt(8)
	s_waitcnt lgkmcnt(0)
	s_barrier
	s_waitcnt lgkmcnt(0)
	v_mfma_f32_16x16x32_bf16 v[60:63], v[112:115], v[160:163], v[60:63]
	v_mfma_f32_16x16x32_bf16 v[60:63], v[116:119], v[164:167], v[60:63]
	v_mfma_f32_16x16x32_bf16 v[56:59], v[128:131], v[164:167], v[56:59]
	v_mfma_f32_16x16x32_bf16 v[56:59], v[120:123], v[160:163], v[56:59]
	v_mfma_f32_16x16x32_bf16 v[52:55], v[144:147], v[160:163], v[52:55]
	v_mfma_f32_16x16x32_bf16 v[52:55], v[148:151], v[164:167], v[52:55]
	v_mfma_f32_16x16x32_bf16 v[48:51], v[156:159], v[164:167], v[48:51]
	v_mfma_f32_16x16x32_bf16 v[48:51], v[152:155], v[160:163], v[48:51]
	v_mfma_f32_16x16x32_bf16 v[32:35], v[152:155], v[168:171], v[32:35]
	v_mfma_f32_16x16x32_bf16 v[32:35], v[156:159], v[172:175], v[32:35]
	v_mfma_f32_16x16x32_bf16 v[36:39], v[148:151], v[172:175], v[36:39]
	v_mfma_f32_16x16x32_bf16 v[36:39], v[144:147], v[168:171], v[36:39]
	v_mfma_f32_16x16x32_bf16 v[40:43], v[120:123], v[168:171], v[40:43]
	v_mfma_f32_16x16x32_bf16 v[40:43], v[128:131], v[172:175], v[40:43]
	v_mfma_f32_16x16x32_bf16 v[44:47], v[116:119], v[172:175], v[44:47]
	v_mfma_f32_16x16x32_bf16 v[44:47], v[112:115], v[168:171], v[44:47]
	v_mfma_f32_16x16x32_bf16 v[28:31], v[112:115], v[188:191], v[28:31]
	v_mfma_f32_16x16x32_bf16 v[28:31], v[116:119], v[192:195], v[28:31]
	v_mfma_f32_16x16x32_bf16 v[24:27], v[128:131], v[192:195], v[24:27]
	v_mfma_f32_16x16x32_bf16 v[24:27], v[120:123], v[188:191], v[24:27]
	v_mfma_f32_16x16x32_bf16 v[20:23], v[144:147], v[188:191], v[20:23]
	v_mfma_f32_16x16x32_bf16 v[20:23], v[148:151], v[192:195], v[20:23]
	v_mfma_f32_16x16x32_bf16 v[16:19], v[156:159], v[192:195], v[16:19]
	v_mfma_f32_16x16x32_bf16 v[16:19], v[152:155], v[188:191], v[16:19]
	v_mfma_f32_16x16x32_bf16 v[0:3], v[152:155], v[196:199], v[0:3]
	v_mfma_f32_16x16x32_bf16 v[0:3], v[156:159], v[200:203], v[0:3]
	v_mfma_f32_16x16x32_bf16 v[4:7], v[148:151], v[200:203], v[4:7]
	v_mfma_f32_16x16x32_bf16 v[4:7], v[144:147], v[196:199], v[4:7]
	v_mfma_f32_16x16x32_bf16 v[8:11], v[120:123], v[196:199], v[8:11]
	v_mfma_f32_16x16x32_bf16 v[8:11], v[128:131], v[200:203], v[8:11]
	v_mfma_f32_16x16x32_bf16 v[12:15], v[116:119], v[200:203], v[12:15]
	v_mfma_f32_16x16x32_bf16 v[12:15], v[112:115], v[196:199], v[12:15]
	s_barrier
	s_add_i32 s63, 0, 0x18000
	s_add_i32 s64, 0, 0x1c000
	v_add_u32_e32 v128, s63, v207
	v_add_u32_e32 v156, s64, v207
	ds_read_b128 v[112:115], v128
	ds_read_b128 v[116:119], v128 offset:1024
	ds_read_b128 v[120:123], v128 offset:2048
	ds_read_b128 v[128:131], v128 offset:3072
	ds_read_b128 v[144:147], v156
	ds_read_b128 v[148:151], v156 offset:1024
	ds_read_b128 v[152:155], v156 offset:2048
	ds_read_b128 v[156:159], v156 offset:3072
	s_add_u32 s30, s30, s10
	s_addc_u32 s31, s31, s11
	s_mov_b32 m0, s40
	v_lshl_add_u64 v[226:227], s[30:31], 0, v[176:177]
	ds_read_b128 v[160:163], v211 offset:32768
	ds_read_b128 v[164:167], v211 offset:33792
	ds_read_b128 v[168:171], v211 offset:34816
	ds_read_b128 v[172:175], v211 offset:35840
	ds_read_b128 v[188:191], v211 offset:36864
	ds_read_b128 v[192:195], v211 offset:37888
	ds_read_b128 v[196:199], v211 offset:38912
	ds_read_b128 v[200:203], v211 offset:39936
	global_load_lds_dwordx4 v[226:227], off
	s_mov_b32 m0, s41
	v_lshl_add_u64 v[226:227], s[30:31], 0, v[178:179]
	global_load_lds_dwordx4 v[226:227], off
	s_waitcnt vmcnt(8)
	s_waitcnt lgkmcnt(0)
	s_barrier
	s_waitcnt lgkmcnt(0)
	v_mfma_f32_16x16x32_bf16 v[136:139], v[112:115], v[160:163], v[136:139]
	v_mfma_f32_16x16x32_bf16 v[136:139], v[116:119], v[164:167], v[136:139]
	v_mfma_f32_16x16x32_bf16 v[140:143], v[128:131], v[164:167], v[140:143]
	v_mfma_f32_16x16x32_bf16 v[140:143], v[120:123], v[160:163], v[140:143]
	v_mfma_f32_16x16x32_bf16 v[132:135], v[144:147], v[160:163], v[132:135]
	v_mfma_f32_16x16x32_bf16 v[132:135], v[148:151], v[164:167], v[132:135]
	v_mfma_f32_16x16x32_bf16 v[124:127], v[156:159], v[164:167], v[124:127]
	v_mfma_f32_16x16x32_bf16 v[124:127], v[152:155], v[160:163], v[124:127]
	v_mfma_f32_16x16x32_bf16 v[96:99], v[152:155], v[168:171], v[96:99]
	v_mfma_f32_16x16x32_bf16 v[96:99], v[156:159], v[172:175], v[96:99]
	v_mfma_f32_16x16x32_bf16 v[100:103], v[148:151], v[172:175], v[100:103]
	v_mfma_f32_16x16x32_bf16 v[100:103], v[144:147], v[168:171], v[100:103]
	v_mfma_f32_16x16x32_bf16 v[104:107], v[120:123], v[168:171], v[104:107]
	v_mfma_f32_16x16x32_bf16 v[104:107], v[128:131], v[172:175], v[104:107]
	v_mfma_f32_16x16x32_bf16 v[108:111], v[116:119], v[172:175], v[108:111]
	v_mfma_f32_16x16x32_bf16 v[108:111], v[112:115], v[168:171], v[108:111]
	v_mfma_f32_16x16x32_bf16 v[92:95], v[112:115], v[188:191], v[92:95]
	v_mfma_f32_16x16x32_bf16 v[92:95], v[116:119], v[192:195], v[92:95]
	v_mfma_f32_16x16x32_bf16 v[88:91], v[128:131], v[192:195], v[88:91]
	v_mfma_f32_16x16x32_bf16 v[88:91], v[120:123], v[188:191], v[88:91]
	v_mfma_f32_16x16x32_bf16 v[84:87], v[144:147], v[188:191], v[84:87]
	v_mfma_f32_16x16x32_bf16 v[84:87], v[148:151], v[192:195], v[84:87]
	v_mfma_f32_16x16x32_bf16 v[80:83], v[156:159], v[192:195], v[80:83]
	v_mfma_f32_16x16x32_bf16 v[80:83], v[152:155], v[188:191], v[80:83]
	v_mfma_f32_16x16x32_bf16 v[64:67], v[152:155], v[196:199], v[64:67]
	v_mfma_f32_16x16x32_bf16 v[64:67], v[156:159], v[200:203], v[64:67]
	v_mfma_f32_16x16x32_bf16 v[68:71], v[148:151], v[200:203], v[68:71]
	v_mfma_f32_16x16x32_bf16 v[68:71], v[144:147], v[196:199], v[68:71]
	v_mfma_f32_16x16x32_bf16 v[72:75], v[120:123], v[196:199], v[72:75]
	v_mfma_f32_16x16x32_bf16 v[72:75], v[128:131], v[200:203], v[72:75]
	v_mfma_f32_16x16x32_bf16 v[76:79], v[116:119], v[200:203], v[76:79]
	v_mfma_f32_16x16x32_bf16 v[76:79], v[112:115], v[196:199], v[76:79]
	s_barrier
	s_add_i32 s30, s63, s37
	v_lshl_add_u64 v[204:205], v[204:205], 0, s[18:19]
	s_mov_b32 m0, s30
	ds_read_b128 v[160:163], v211 offset:49152
	ds_read_b128 v[164:167], v211 offset:50176
	ds_read_b128 v[168:171], v211 offset:51200
	ds_read_b128 v[172:175], v211 offset:52224
	ds_read_b128 v[188:191], v211 offset:53248
	ds_read_b128 v[192:195], v211 offset:54272
	ds_read_b128 v[196:199], v211 offset:55296
	ds_read_b128 v[200:203], v211 offset:56320
	global_load_lds_dwordx4 v[204:205], off
	v_lshl_add_u64 v[204:205], v[214:215], 0, s[18:19]
	s_add_i32 m0, s30, 0x2000
	s_add_i32 s30, s64, s37
	global_load_lds_dwordx4 v[204:205], off
	s_mov_b32 m0, s30
	v_lshl_add_u64 v[204:205], v[216:217], 0, s[18:19]
	global_load_lds_dwordx4 v[204:205], off
	s_add_i32 m0, s30, 0x2000
	v_lshl_add_u64 v[204:205], v[218:219], 0, s[18:19]
	global_load_lds_dwordx4 v[204:205], off
	s_mov_b32 m0, s43
	v_lshl_add_u64 v[204:205], v[222:223], 0, s[18:19]
	global_load_lds_dwordx4 v[204:205], off
	s_mov_b32 m0, s44
	v_lshl_add_u64 v[204:205], v[224:225], 0, s[18:19]
	global_load_lds_dwordx4 v[204:205], off
	s_waitcnt vmcnt(8)
	s_waitcnt lgkmcnt(0)
	s_barrier
	s_waitcnt lgkmcnt(0)
	v_mfma_f32_16x16x32_bf16 v[60:63], v[112:115], v[160:163], v[60:63]
	v_mfma_f32_16x16x32_bf16 v[60:63], v[116:119], v[164:167], v[60:63]
	v_mfma_f32_16x16x32_bf16 v[56:59], v[128:131], v[164:167], v[56:59]
	v_mfma_f32_16x16x32_bf16 v[56:59], v[120:123], v[160:163], v[56:59]
	v_mfma_f32_16x16x32_bf16 v[52:55], v[144:147], v[160:163], v[52:55]
	v_mfma_f32_16x16x32_bf16 v[52:55], v[148:151], v[164:167], v[52:55]
	v_mfma_f32_16x16x32_bf16 v[48:51], v[156:159], v[164:167], v[48:51]
	v_mfma_f32_16x16x32_bf16 v[48:51], v[152:155], v[160:163], v[48:51]
	v_mfma_f32_16x16x32_bf16 v[32:35], v[152:155], v[168:171], v[32:35]
	v_mfma_f32_16x16x32_bf16 v[32:35], v[156:159], v[172:175], v[32:35]
	v_mfma_f32_16x16x32_bf16 v[36:39], v[148:151], v[172:175], v[36:39]
	v_mfma_f32_16x16x32_bf16 v[36:39], v[144:147], v[168:171], v[36:39]
	v_mfma_f32_16x16x32_bf16 v[40:43], v[120:123], v[168:171], v[40:43]
	v_mfma_f32_16x16x32_bf16 v[40:43], v[128:131], v[172:175], v[40:43]
	v_mfma_f32_16x16x32_bf16 v[44:47], v[116:119], v[172:175], v[44:47]
	v_mfma_f32_16x16x32_bf16 v[44:47], v[112:115], v[168:171], v[44:47]
	v_mfma_f32_16x16x32_bf16 v[28:31], v[112:115], v[188:191], v[28:31]
	v_mfma_f32_16x16x32_bf16 v[28:31], v[116:119], v[192:195], v[28:31]
	v_mfma_f32_16x16x32_bf16 v[24:27], v[128:131], v[192:195], v[24:27]
	v_mfma_f32_16x16x32_bf16 v[24:27], v[120:123], v[188:191], v[24:27]
	v_mfma_f32_16x16x32_bf16 v[20:23], v[144:147], v[188:191], v[20:23]
	v_mfma_f32_16x16x32_bf16 v[20:23], v[148:151], v[192:195], v[20:23]
	v_mfma_f32_16x16x32_bf16 v[16:19], v[156:159], v[192:195], v[16:19]
	v_mfma_f32_16x16x32_bf16 v[16:19], v[152:155], v[188:191], v[16:19]
	v_mfma_f32_16x16x32_bf16 v[0:3], v[152:155], v[196:199], v[0:3]
	v_mfma_f32_16x16x32_bf16 v[0:3], v[156:159], v[200:203], v[0:3]
	v_mfma_f32_16x16x32_bf16 v[4:7], v[148:151], v[200:203], v[4:7]
	v_mfma_f32_16x16x32_bf16 v[4:7], v[144:147], v[196:199], v[4:7]
	v_mfma_f32_16x16x32_bf16 v[8:11], v[120:123], v[196:199], v[8:11]
	v_mfma_f32_16x16x32_bf16 v[8:11], v[128:131], v[200:203], v[8:11]
	v_mfma_f32_16x16x32_bf16 v[12:15], v[116:119], v[200:203], v[12:15]
	v_mfma_f32_16x16x32_bf16 v[12:15], v[112:115], v[196:199], v[12:15]
	s_add_u32 s28, s28, 0x100
	s_addc_u32 s29, s29, 0
	s_add_u32 s60, s60, 0x100
	s_addc_u32 s61, s61, 0
	s_cmp_ge_i32 s62, s45
	s_mov_b32 s30, s62
	s_barrier
	s_cbranch_scc0 .LBB0_849

.LBB0_949:
	ds_read_b128 v[164:167], v157
	ds_read_b128 v[168:171], v157 offset:1024
	ds_read_b128 v[172:175], v157 offset:2048
	ds_read_b128 v[176:179], v157 offset:3072
	ds_read_b128 v[180:183], v162
	ds_read_b128 v[184:187], v162 offset:1024
	ds_read_b128 v[188:191], v162 offset:2048
	ds_read_b128 v[192:195], v162 offset:3072
	s_add_i32 s68, s34, 2
	s_add_u32 s69, s30, 0x80
	s_addc_u32 s35, s31, 0
	s_cmp_eq_u32 s49, s34
	s_cselect_b32 s34, s2, s69
	s_cselect_b32 s35, s3, s35
	s_cselect_b32 s71, s29, s67
	s_cselect_b32 s70, s28, s66
	v_lshl_add_u64 v[230:231], s[30:31], 0, v[136:137]
	s_add_i32 m0, s41, 0xc000
	ds_read_b128 v[196:199], v163
	ds_read_b128 v[200:203], v163 offset:1024
	ds_read_b128 v[204:207], v163 offset:2048
	ds_read_b128 v[208:211], v163 offset:3072
	ds_read_b128 v[212:215], v163 offset:4096
	ds_read_b128 v[216:219], v163 offset:5120
	ds_read_b128 v[222:225], v163 offset:6144
	ds_read_b128 v[226:229], v163 offset:7168
	global_load_lds_dwordx4 v[230:231], off
	s_add_i32 m0, s41, 0xe000
	v_lshl_add_u64 v[230:231], s[30:31], 0, v[138:139]
	global_load_lds_dwordx4 v[230:231], off
	s_waitcnt vmcnt(8)
	s_waitcnt lgkmcnt(0)
	s_barrier
	s_waitcnt lgkmcnt(0)
	v_mfma_f32_16x16x32_bf16 v[120:123], v[164:167], v[196:199], v[120:123]
	v_mfma_f32_16x16x32_bf16 v[120:123], v[168:171], v[200:203], v[120:123]
	v_mfma_f32_16x16x32_bf16 v[124:127], v[176:179], v[200:203], v[124:127]
	v_mfma_f32_16x16x32_bf16 v[124:127], v[172:175], v[196:199], v[124:127]
	v_mfma_f32_16x16x32_bf16 v[116:119], v[180:183], v[196:199], v[116:119]
	v_mfma_f32_16x16x32_bf16 v[116:119], v[184:187], v[200:203], v[116:119]
	v_mfma_f32_16x16x32_bf16 v[112:115], v[192:195], v[200:203], v[112:115]
	v_mfma_f32_16x16x32_bf16 v[112:115], v[188:191], v[196:199], v[112:115]
	v_mfma_f32_16x16x32_bf16 v[96:99], v[188:191], v[204:207], v[96:99]
	v_mfma_f32_16x16x32_bf16 v[96:99], v[192:195], v[208:211], v[96:99]
	v_mfma_f32_16x16x32_bf16 v[100:103], v[184:187], v[208:211], v[100:103]
	v_mfma_f32_16x16x32_bf16 v[100:103], v[180:183], v[204:207], v[100:103]
	v_mfma_f32_16x16x32_bf16 v[104:107], v[172:175], v[204:207], v[104:107]
	v_mfma_f32_16x16x32_bf16 v[104:107], v[176:179], v[208:211], v[104:107]
	v_mfma_f32_16x16x32_bf16 v[108:111], v[168:171], v[208:211], v[108:111]
	v_mfma_f32_16x16x32_bf16 v[108:111], v[164:167], v[204:207], v[108:111]
	v_mfma_f32_16x16x32_bf16 v[92:95], v[164:167], v[212:215], v[92:95]
	v_mfma_f32_16x16x32_bf16 v[92:95], v[168:171], v[216:219], v[92:95]
	v_mfma_f32_16x16x32_bf16 v[88:91], v[176:179], v[216:219], v[88:91]
	v_mfma_f32_16x16x32_bf16 v[88:91], v[172:175], v[212:215], v[88:91]
	v_mfma_f32_16x16x32_bf16 v[84:87], v[180:183], v[212:215], v[84:87]
	v_mfma_f32_16x16x32_bf16 v[84:87], v[184:187], v[216:219], v[84:87]
	v_mfma_f32_16x16x32_bf16 v[80:83], v[192:195], v[216:219], v[80:83]
	v_mfma_f32_16x16x32_bf16 v[80:83], v[188:191], v[212:215], v[80:83]
	v_mfma_f32_16x16x32_bf16 v[64:67], v[188:191], v[222:225], v[64:67]
	v_mfma_f32_16x16x32_bf16 v[64:67], v[192:195], v[226:229], v[64:67]
	v_mfma_f32_16x16x32_bf16 v[68:71], v[184:187], v[226:229], v[68:71]
	v_mfma_f32_16x16x32_bf16 v[68:71], v[180:183], v[222:225], v[68:71]
	v_mfma_f32_16x16x32_bf16 v[72:75], v[172:175], v[222:225], v[72:75]
	v_mfma_f32_16x16x32_bf16 v[72:75], v[176:179], v[226:229], v[72:75]
	v_mfma_f32_16x16x32_bf16 v[76:79], v[168:171], v[226:229], v[76:79]
	v_mfma_f32_16x16x32_bf16 v[76:79], v[164:167], v[222:225], v[76:79]
	s_barrier
	s_add_i32 s69, s52, s40
	v_lshl_add_u64 v[230:231], s[70:71], 0, v[130:131]
	s_mov_b32 m0, s69
	ds_read_b128 v[196:199], v163 offset:16384
	ds_read_b128 v[200:203], v163 offset:17408
	ds_read_b128 v[204:207], v163 offset:18432
	ds_read_b128 v[208:211], v163 offset:19456
	ds_read_b128 v[212:215], v163 offset:20480
	ds_read_b128 v[216:219], v163 offset:21504
	ds_read_b128 v[222:225], v163 offset:22528
	ds_read_b128 v[226:229], v163 offset:23552
	global_load_lds_dwordx4 v[230:231], off
	s_add_i32 m0, s69, 0x2000
	v_lshl_add_u64 v[232:233], s[70:71], 0, v[134:135]
	s_add_u32 s70, s70, s6
	s_addc_u32 s71, s71, s7
	s_add_i32 s69, s53, s40
	global_load_lds_dwordx4 v[232:233], off
	v_lshl_add_u64 v[234:235], s[70:71], 0, v[130:131]
	s_mov_b32 m0, s69
	v_lshl_add_u64 v[236:237], s[70:71], 0, v[134:135]
	global_load_lds_dwordx4 v[234:235], off
	s_add_i32 m0, s69, 0x2000
	v_lshl_add_u64 v[238:239], s[34:35], 0, v[128:129]
	global_load_lds_dwordx4 v[236:237], off
	s_mov_b32 m0, s41
	v_lshl_add_u64 v[240:241], s[34:35], 0, v[132:133]
	global_load_lds_dwordx4 v[238:239], off
	s_mov_b32 m0, s42
	s_nop 0
	global_load_lds_dwordx4 v[240:241], off
	s_waitcnt vmcnt(8)
	s_waitcnt lgkmcnt(0)
	s_barrier
	s_waitcnt lgkmcnt(0)
	v_mfma_f32_16x16x32_bf16 v[60:63], v[164:167], v[196:199], v[60:63]
	v_mfma_f32_16x16x32_bf16 v[60:63], v[168:171], v[200:203], v[60:63]
	v_mfma_f32_16x16x32_bf16 v[56:59], v[176:179], v[200:203], v[56:59]
	v_mfma_f32_16x16x32_bf16 v[56:59], v[172:175], v[196:199], v[56:59]
	v_mfma_f32_16x16x32_bf16 v[52:55], v[180:183], v[196:199], v[52:55]
	v_mfma_f32_16x16x32_bf16 v[52:55], v[184:187], v[200:203], v[52:55]
	v_mfma_f32_16x16x32_bf16 v[48:51], v[192:195], v[200:203], v[48:51]
	v_mfma_f32_16x16x32_bf16 v[48:51], v[188:191], v[196:199], v[48:51]
	v_mfma_f32_16x16x32_bf16 v[32:35], v[188:191], v[204:207], v[32:35]
	v_mfma_f32_16x16x32_bf16 v[32:35], v[192:195], v[208:211], v[32:35]
	v_mfma_f32_16x16x32_bf16 v[36:39], v[184:187], v[208:211], v[36:39]
	v_mfma_f32_16x16x32_bf16 v[36:39], v[180:183], v[204:207], v[36:39]
	v_mfma_f32_16x16x32_bf16 v[40:43], v[172:175], v[204:207], v[40:43]
	v_mfma_f32_16x16x32_bf16 v[40:43], v[176:179], v[208:211], v[40:43]
	v_mfma_f32_16x16x32_bf16 v[44:47], v[168:171], v[208:211], v[44:47]
	v_mfma_f32_16x16x32_bf16 v[44:47], v[164:167], v[204:207], v[44:47]
	v_mfma_f32_16x16x32_bf16 v[28:31], v[164:167], v[212:215], v[28:31]
	v_mfma_f32_16x16x32_bf16 v[28:31], v[168:171], v[216:219], v[28:31]
	v_mfma_f32_16x16x32_bf16 v[24:27], v[176:179], v[216:219], v[24:27]
	v_mfma_f32_16x16x32_bf16 v[24:27], v[172:175], v[212:215], v[24:27]
	v_mfma_f32_16x16x32_bf16 v[20:23], v[180:183], v[212:215], v[20:23]
	v_mfma_f32_16x16x32_bf16 v[20:23], v[184:187], v[216:219], v[20:23]
	v_mfma_f32_16x16x32_bf16 v[16:19], v[192:195], v[216:219], v[16:19]
	v_mfma_f32_16x16x32_bf16 v[16:19], v[188:191], v[212:215], v[16:19]
	v_mfma_f32_16x16x32_bf16 v[0:3], v[188:191], v[222:225], v[0:3]
	v_mfma_f32_16x16x32_bf16 v[0:3], v[192:195], v[226:229], v[0:3]
	v_mfma_f32_16x16x32_bf16 v[4:7], v[184:187], v[226:229], v[4:7]
	v_mfma_f32_16x16x32_bf16 v[4:7], v[180:183], v[222:225], v[4:7]
	v_mfma_f32_16x16x32_bf16 v[8:11], v[172:175], v[222:225], v[8:11]
	v_mfma_f32_16x16x32_bf16 v[8:11], v[176:179], v[226:229], v[8:11]
	v_mfma_f32_16x16x32_bf16 v[12:15], v[168:171], v[226:229], v[12:15]
	v_mfma_f32_16x16x32_bf16 v[12:15], v[164:167], v[222:225], v[12:15]
	s_barrier
	s_add_i32 s69, 0, 0x18000
	s_add_i32 s70, 0, 0x1c000
	v_add_u32_e32 v176, s69, v154
	v_add_u32_e32 v192, s70, v154
	ds_read_b128 v[164:167], v176
	ds_read_b128 v[168:171], v176 offset:1024
	ds_read_b128 v[172:175], v176 offset:2048
	ds_read_b128 v[176:179], v176 offset:3072
	ds_read_b128 v[180:183], v192
	ds_read_b128 v[184:187], v192 offset:1024
	ds_read_b128 v[188:191], v192 offset:2048
	ds_read_b128 v[192:195], v192 offset:3072
	s_add_u32 s34, s34, s6
	s_addc_u32 s35, s35, s7
	s_mov_b32 m0, s43
	v_lshl_add_u64 v[242:243], s[34:35], 0, v[128:129]
	ds_read_b128 v[196:199], v163 offset:32768
	ds_read_b128 v[200:203], v163 offset:33792
	ds_read_b128 v[204:207], v163 offset:34816
	ds_read_b128 v[208:211], v163 offset:35840
	ds_read_b128 v[212:215], v163 offset:36864
	ds_read_b128 v[216:219], v163 offset:37888
	ds_read_b128 v[222:225], v163 offset:38912
	ds_read_b128 v[226:229], v163 offset:39936
	global_load_lds_dwordx4 v[242:243], off
	s_mov_b32 m0, s44
	v_lshl_add_u64 v[242:243], s[34:35], 0, v[132:133]
	global_load_lds_dwordx4 v[242:243], off
	s_waitcnt vmcnt(8)
	s_waitcnt lgkmcnt(0)
	s_barrier
	s_waitcnt lgkmcnt(0)
	v_mfma_f32_16x16x32_bf16 v[120:123], v[164:167], v[196:199], v[120:123]
	v_mfma_f32_16x16x32_bf16 v[120:123], v[168:171], v[200:203], v[120:123]
	v_mfma_f32_16x16x32_bf16 v[124:127], v[176:179], v[200:203], v[124:127]
	v_mfma_f32_16x16x32_bf16 v[124:127], v[172:175], v[196:199], v[124:127]
	v_mfma_f32_16x16x32_bf16 v[116:119], v[180:183], v[196:199], v[116:119]
	v_mfma_f32_16x16x32_bf16 v[116:119], v[184:187], v[200:203], v[116:119]
	v_mfma_f32_16x16x32_bf16 v[112:115], v[192:195], v[200:203], v[112:115]
	v_mfma_f32_16x16x32_bf16 v[112:115], v[188:191], v[196:199], v[112:115]
	v_mfma_f32_16x16x32_bf16 v[96:99], v[188:191], v[204:207], v[96:99]
	v_mfma_f32_16x16x32_bf16 v[96:99], v[192:195], v[208:211], v[96:99]
	v_mfma_f32_16x16x32_bf16 v[100:103], v[184:187], v[208:211], v[100:103]
	v_mfma_f32_16x16x32_bf16 v[100:103], v[180:183], v[204:207], v[100:103]
	v_mfma_f32_16x16x32_bf16 v[104:107], v[172:175], v[204:207], v[104:107]
	v_mfma_f32_16x16x32_bf16 v[104:107], v[176:179], v[208:211], v[104:107]
	v_mfma_f32_16x16x32_bf16 v[108:111], v[168:171], v[208:211], v[108:111]
	v_mfma_f32_16x16x32_bf16 v[108:111], v[164:167], v[204:207], v[108:111]
	v_mfma_f32_16x16x32_bf16 v[92:95], v[164:167], v[212:215], v[92:95]
	v_mfma_f32_16x16x32_bf16 v[92:95], v[168:171], v[216:219], v[92:95]
	v_mfma_f32_16x16x32_bf16 v[88:91], v[176:179], v[216:219], v[88:91]
	v_mfma_f32_16x16x32_bf16 v[88:91], v[172:175], v[212:215], v[88:91]
	v_mfma_f32_16x16x32_bf16 v[84:87], v[180:183], v[212:215], v[84:87]
	v_mfma_f32_16x16x32_bf16 v[84:87], v[184:187], v[216:219], v[84:87]
	v_mfma_f32_16x16x32_bf16 v[80:83], v[192:195], v[216:219], v[80:83]
	v_mfma_f32_16x16x32_bf16 v[80:83], v[188:191], v[212:215], v[80:83]
	v_mfma_f32_16x16x32_bf16 v[64:67], v[188:191], v[222:225], v[64:67]
	v_mfma_f32_16x16x32_bf16 v[64:67], v[192:195], v[226:229], v[64:67]
	v_mfma_f32_16x16x32_bf16 v[68:71], v[184:187], v[226:229], v[68:71]
	v_mfma_f32_16x16x32_bf16 v[68:71], v[180:183], v[222:225], v[68:71]
	v_mfma_f32_16x16x32_bf16 v[72:75], v[172:175], v[222:225], v[72:75]
	v_mfma_f32_16x16x32_bf16 v[72:75], v[176:179], v[226:229], v[72:75]
	v_mfma_f32_16x16x32_bf16 v[76:79], v[168:171], v[226:229], v[76:79]
	v_mfma_f32_16x16x32_bf16 v[76:79], v[164:167], v[222:225], v[76:79]
	s_barrier
	s_add_i32 s34, s69, s40
	v_lshl_add_u64 v[230:231], v[230:231], 0, s[12:13]
	s_mov_b32 m0, s34
	ds_read_b128 v[196:199], v163 offset:49152
	ds_read_b128 v[200:203], v163 offset:50176
	ds_read_b128 v[204:207], v163 offset:51200
	ds_read_b128 v[208:211], v163 offset:52224
	ds_read_b128 v[212:215], v163 offset:53248
	ds_read_b128 v[216:219], v163 offset:54272
	ds_read_b128 v[222:225], v163 offset:55296
	ds_read_b128 v[226:229], v163 offset:56320
	global_load_lds_dwordx4 v[230:231], off
	v_lshl_add_u64 v[230:231], v[232:233], 0, s[12:13]
	s_add_i32 m0, s34, 0x2000
	s_add_i32 s34, s70, s40
	global_load_lds_dwordx4 v[230:231], off
	s_mov_b32 m0, s34
	v_lshl_add_u64 v[230:231], v[234:235], 0, s[12:13]
	global_load_lds_dwordx4 v[230:231], off
	s_add_i32 m0, s34, 0x2000
	v_lshl_add_u64 v[230:231], v[236:237], 0, s[12:13]
	global_load_lds_dwordx4 v[230:231], off
	s_mov_b32 m0, s46
	v_lshl_add_u64 v[230:231], v[238:239], 0, s[12:13]
	global_load_lds_dwordx4 v[230:231], off
	s_mov_b32 m0, s47
	v_lshl_add_u64 v[230:231], v[240:241], 0, s[12:13]
	global_load_lds_dwordx4 v[230:231], off
	s_waitcnt vmcnt(8)
	s_waitcnt lgkmcnt(0)
	s_barrier
	s_waitcnt lgkmcnt(0)
	v_mfma_f32_16x16x32_bf16 v[60:63], v[164:167], v[196:199], v[60:63]
	v_mfma_f32_16x16x32_bf16 v[60:63], v[168:171], v[200:203], v[60:63]
	v_mfma_f32_16x16x32_bf16 v[56:59], v[176:179], v[200:203], v[56:59]
	v_mfma_f32_16x16x32_bf16 v[56:59], v[172:175], v[196:199], v[56:59]
	v_mfma_f32_16x16x32_bf16 v[52:55], v[180:183], v[196:199], v[52:55]
	v_mfma_f32_16x16x32_bf16 v[52:55], v[184:187], v[200:203], v[52:55]
	v_mfma_f32_16x16x32_bf16 v[48:51], v[192:195], v[200:203], v[48:51]
	v_mfma_f32_16x16x32_bf16 v[48:51], v[188:191], v[196:199], v[48:51]
	v_mfma_f32_16x16x32_bf16 v[32:35], v[188:191], v[204:207], v[32:35]
	v_mfma_f32_16x16x32_bf16 v[32:35], v[192:195], v[208:211], v[32:35]
	v_mfma_f32_16x16x32_bf16 v[36:39], v[184:187], v[208:211], v[36:39]
	v_mfma_f32_16x16x32_bf16 v[36:39], v[180:183], v[204:207], v[36:39]
	v_mfma_f32_16x16x32_bf16 v[40:43], v[172:175], v[204:207], v[40:43]
	v_mfma_f32_16x16x32_bf16 v[40:43], v[176:179], v[208:211], v[40:43]
	v_mfma_f32_16x16x32_bf16 v[44:47], v[168:171], v[208:211], v[44:47]
	v_mfma_f32_16x16x32_bf16 v[44:47], v[164:167], v[204:207], v[44:47]
	v_mfma_f32_16x16x32_bf16 v[28:31], v[164:167], v[212:215], v[28:31]
	v_mfma_f32_16x16x32_bf16 v[28:31], v[168:171], v[216:219], v[28:31]
	v_mfma_f32_16x16x32_bf16 v[24:27], v[176:179], v[216:219], v[24:27]
	v_mfma_f32_16x16x32_bf16 v[24:27], v[172:175], v[212:215], v[24:27]
	v_mfma_f32_16x16x32_bf16 v[20:23], v[180:183], v[212:215], v[20:23]
	v_mfma_f32_16x16x32_bf16 v[20:23], v[184:187], v[216:219], v[20:23]
	v_mfma_f32_16x16x32_bf16 v[16:19], v[192:195], v[216:219], v[16:19]
	v_mfma_f32_16x16x32_bf16 v[16:19], v[188:191], v[212:215], v[16:19]
	v_mfma_f32_16x16x32_bf16 v[0:3], v[188:191], v[222:225], v[0:3]
	v_mfma_f32_16x16x32_bf16 v[0:3], v[192:195], v[226:229], v[0:3]
	v_mfma_f32_16x16x32_bf16 v[4:7], v[184:187], v[226:229], v[4:7]
	v_mfma_f32_16x16x32_bf16 v[4:7], v[180:183], v[222:225], v[4:7]
	v_mfma_f32_16x16x32_bf16 v[8:11], v[172:175], v[222:225], v[8:11]
	v_mfma_f32_16x16x32_bf16 v[8:11], v[176:179], v[226:229], v[8:11]
	v_mfma_f32_16x16x32_bf16 v[12:15], v[168:171], v[226:229], v[12:15]
	v_mfma_f32_16x16x32_bf16 v[12:15], v[164:167], v[222:225], v[12:15]
	s_add_u32 s30, s30, 0x100
	s_addc_u32 s31, s31, 0
	s_add_u32 s66, s66, 0x100
	s_addc_u32 s67, s67, 0
	s_cmp_ge_i32 s68, s48
	s_mov_b32 s34, s68
	s_barrier
	s_cbranch_scc0 .LBB0_949

.LBB0_970:
	ds_read_b128 v[170:173], v139
	ds_read_b128 v[174:177], v139 offset:1024
	ds_read_b128 v[178:181], v139 offset:2048
	ds_read_b128 v[182:185], v139 offset:3072
	ds_read_b128 v[186:189], v165
	ds_read_b128 v[190:193], v165 offset:1024
	ds_read_b128 v[194:197], v165 offset:2048
	ds_read_b128 v[198:201], v165 offset:3072
	s_add_i32 s8, s4, 2
	s_add_u32 s9, s2, 0x80
	s_addc_u32 s5, s3, 0
	s_cmp_eq_u32 s52, s4
	s_cselect_b32 s4, s30, s9
	s_cselect_b32 s5, s31, s5
	s_cselect_b32 s11, s35, s7
	s_cselect_b32 s10, s34, s6
	v_lshl_add_u64 v[218:219], s[2:3], 0, v[156:157]
	s_add_i32 m0, s42, 0xc000
	ds_read_b128 v[202:205], v166
	ds_read_b128 v[206:209], v166 offset:1024
	ds_read_b128 v[210:213], v166 offset:2048
	ds_read_b128 v[214:217], v166 offset:3072
	ds_read_b128 v[222:225], v166 offset:4096
	ds_read_b128 v[226:229], v166 offset:5120
	ds_read_b128 v[230:233], v166 offset:6144
	ds_read_b128 v[234:237], v166 offset:7168
	global_load_lds_dwordx4 v[218:219], off
	s_add_i32 m0, s42, 0xe000
	v_lshl_add_u64 v[218:219], s[2:3], 0, v[158:159]
	global_load_lds_dwordx4 v[218:219], off
	s_waitcnt vmcnt(8)
	s_waitcnt lgkmcnt(0)
	s_barrier
	s_waitcnt lgkmcnt(0)
	v_mfma_f32_16x16x32_bf16 v[124:127], v[170:173], v[202:205], v[124:127]
	v_mfma_f32_16x16x32_bf16 v[124:127], v[174:177], v[206:209], v[124:127]
	v_mfma_f32_16x16x32_bf16 v[120:123], v[182:185], v[206:209], v[120:123]
	v_mfma_f32_16x16x32_bf16 v[120:123], v[178:181], v[202:205], v[120:123]
	v_mfma_f32_16x16x32_bf16 v[116:119], v[186:189], v[202:205], v[116:119]
	v_mfma_f32_16x16x32_bf16 v[116:119], v[190:193], v[206:209], v[116:119]
	v_mfma_f32_16x16x32_bf16 v[112:115], v[198:201], v[206:209], v[112:115]
	v_mfma_f32_16x16x32_bf16 v[112:115], v[194:197], v[202:205], v[112:115]
	v_mfma_f32_16x16x32_bf16 v[96:99], v[194:197], v[210:213], v[96:99]
	v_mfma_f32_16x16x32_bf16 v[96:99], v[198:201], v[214:217], v[96:99]
	v_mfma_f32_16x16x32_bf16 v[100:103], v[190:193], v[214:217], v[100:103]
	v_mfma_f32_16x16x32_bf16 v[100:103], v[186:189], v[210:213], v[100:103]
	v_mfma_f32_16x16x32_bf16 v[104:107], v[178:181], v[210:213], v[104:107]
	v_mfma_f32_16x16x32_bf16 v[104:107], v[182:185], v[214:217], v[104:107]
	v_mfma_f32_16x16x32_bf16 v[108:111], v[174:177], v[214:217], v[108:111]
	v_mfma_f32_16x16x32_bf16 v[108:111], v[170:173], v[210:213], v[108:111]
	v_mfma_f32_16x16x32_bf16 v[92:95], v[170:173], v[222:225], v[92:95]
	v_mfma_f32_16x16x32_bf16 v[92:95], v[174:177], v[226:229], v[92:95]
	v_mfma_f32_16x16x32_bf16 v[88:91], v[182:185], v[226:229], v[88:91]
	v_mfma_f32_16x16x32_bf16 v[88:91], v[178:181], v[222:225], v[88:91]
	v_mfma_f32_16x16x32_bf16 v[84:87], v[186:189], v[222:225], v[84:87]
	v_mfma_f32_16x16x32_bf16 v[84:87], v[190:193], v[226:229], v[84:87]
	v_mfma_f32_16x16x32_bf16 v[80:83], v[198:201], v[226:229], v[80:83]
	v_mfma_f32_16x16x32_bf16 v[80:83], v[194:197], v[222:225], v[80:83]
	v_mfma_f32_16x16x32_bf16 v[64:67], v[194:197], v[230:233], v[64:67]
	v_mfma_f32_16x16x32_bf16 v[64:67], v[198:201], v[234:237], v[64:67]
	v_mfma_f32_16x16x32_bf16 v[68:71], v[190:193], v[234:237], v[68:71]
	v_mfma_f32_16x16x32_bf16 v[68:71], v[186:189], v[230:233], v[68:71]
	v_mfma_f32_16x16x32_bf16 v[72:75], v[178:181], v[230:233], v[72:75]
	v_mfma_f32_16x16x32_bf16 v[72:75], v[182:185], v[234:237], v[72:75]
	v_mfma_f32_16x16x32_bf16 v[76:79], v[174:177], v[234:237], v[76:79]
	v_mfma_f32_16x16x32_bf16 v[76:79], v[170:173], v[230:233], v[76:79]
	s_barrier
	s_add_i32 s9, s60, s39
	v_lshl_add_u64 v[218:219], s[10:11], 0, v[132:133]
	s_mov_b32 m0, s9
	ds_read_b128 v[202:205], v166 offset:16384
	ds_read_b128 v[206:209], v166 offset:17408
	ds_read_b128 v[210:213], v166 offset:18432
	ds_read_b128 v[214:217], v166 offset:19456
	ds_read_b128 v[222:225], v166 offset:20480
	ds_read_b128 v[226:229], v166 offset:21504
	ds_read_b128 v[230:233], v166 offset:22528
	ds_read_b128 v[234:237], v166 offset:23552
	global_load_lds_dwordx4 v[218:219], off
	s_add_i32 m0, s9, 0x2000
	v_lshl_add_u64 v[238:239], s[10:11], 0, v[128:129]
	s_add_u32 s10, s10, s18
	s_addc_u32 s11, s11, s19
	s_add_i32 s9, s61, s39
	global_load_lds_dwordx4 v[238:239], off
	v_lshl_add_u64 v[240:241], s[10:11], 0, v[132:133]
	s_mov_b32 m0, s9
	v_lshl_add_u64 v[242:243], s[10:11], 0, v[128:129]
	global_load_lds_dwordx4 v[240:241], off
	s_add_i32 m0, s9, 0x2000
	v_lshl_add_u64 v[244:245], s[4:5], 0, v[134:135]
	global_load_lds_dwordx4 v[242:243], off
	s_mov_b32 m0, s42
	v_lshl_add_u64 v[246:247], s[4:5], 0, v[130:131]
	global_load_lds_dwordx4 v[244:245], off
	s_mov_b32 m0, s43
	s_nop 0
	global_load_lds_dwordx4 v[246:247], off
	s_waitcnt vmcnt(8)
	s_waitcnt lgkmcnt(0)
	s_barrier
	s_waitcnt lgkmcnt(0)
	v_mfma_f32_16x16x32_bf16 v[60:63], v[170:173], v[202:205], v[60:63]
	v_mfma_f32_16x16x32_bf16 v[60:63], v[174:177], v[206:209], v[60:63]
	v_mfma_f32_16x16x32_bf16 v[56:59], v[182:185], v[206:209], v[56:59]
	v_mfma_f32_16x16x32_bf16 v[56:59], v[178:181], v[202:205], v[56:59]
	v_mfma_f32_16x16x32_bf16 v[52:55], v[186:189], v[202:205], v[52:55]
	v_mfma_f32_16x16x32_bf16 v[52:55], v[190:193], v[206:209], v[52:55]
	v_mfma_f32_16x16x32_bf16 v[48:51], v[198:201], v[206:209], v[48:51]
	v_mfma_f32_16x16x32_bf16 v[48:51], v[194:197], v[202:205], v[48:51]
	v_mfma_f32_16x16x32_bf16 v[32:35], v[194:197], v[210:213], v[32:35]
	v_mfma_f32_16x16x32_bf16 v[32:35], v[198:201], v[214:217], v[32:35]
	v_mfma_f32_16x16x32_bf16 v[36:39], v[190:193], v[214:217], v[36:39]
	v_mfma_f32_16x16x32_bf16 v[36:39], v[186:189], v[210:213], v[36:39]
	v_mfma_f32_16x16x32_bf16 v[40:43], v[178:181], v[210:213], v[40:43]
	v_mfma_f32_16x16x32_bf16 v[40:43], v[182:185], v[214:217], v[40:43]
	v_mfma_f32_16x16x32_bf16 v[44:47], v[174:177], v[214:217], v[44:47]
	v_mfma_f32_16x16x32_bf16 v[44:47], v[170:173], v[210:213], v[44:47]
	v_mfma_f32_16x16x32_bf16 v[28:31], v[170:173], v[222:225], v[28:31]
	v_mfma_f32_16x16x32_bf16 v[28:31], v[174:177], v[226:229], v[28:31]
	v_mfma_f32_16x16x32_bf16 v[24:27], v[182:185], v[226:229], v[24:27]
	v_mfma_f32_16x16x32_bf16 v[24:27], v[178:181], v[222:225], v[24:27]
	v_mfma_f32_16x16x32_bf16 v[20:23], v[186:189], v[222:225], v[20:23]
	v_mfma_f32_16x16x32_bf16 v[20:23], v[190:193], v[226:229], v[20:23]
	v_mfma_f32_16x16x32_bf16 v[16:19], v[198:201], v[226:229], v[16:19]
	v_mfma_f32_16x16x32_bf16 v[16:19], v[194:197], v[222:225], v[16:19]
	v_mfma_f32_16x16x32_bf16 v[0:3], v[194:197], v[230:233], v[0:3]
	v_mfma_f32_16x16x32_bf16 v[0:3], v[198:201], v[234:237], v[0:3]
	v_mfma_f32_16x16x32_bf16 v[4:7], v[190:193], v[234:237], v[4:7]
	v_mfma_f32_16x16x32_bf16 v[4:7], v[186:189], v[230:233], v[4:7]
	v_mfma_f32_16x16x32_bf16 v[8:11], v[178:181], v[230:233], v[8:11]
	v_mfma_f32_16x16x32_bf16 v[8:11], v[182:185], v[234:237], v[8:11]
	v_mfma_f32_16x16x32_bf16 v[12:15], v[174:177], v[234:237], v[12:15]
	v_mfma_f32_16x16x32_bf16 v[12:15], v[170:173], v[230:233], v[12:15]
	s_barrier
	s_add_i32 s9, 0, 0x18000
	v_add_u32_e32 v169, s9, v164
	s_add_i32 s10, 0, 0x1c000
	ds_read_b128 v[170:173], v169
	ds_read_b128 v[174:177], v169 offset:1024
	ds_read_b128 v[178:181], v169 offset:2048
	ds_read_b128 v[182:185], v169 offset:3072
	v_add_u32_e32 v169, s10, v164
	ds_read_b128 v[186:189], v169
	ds_read_b128 v[190:193], v169 offset:1024
	ds_read_b128 v[194:197], v169 offset:2048
	ds_read_b128 v[198:201], v169 offset:3072
	s_add_u32 s4, s4, s18
	s_addc_u32 s5, s5, s19
	s_mov_b32 m0, s44
	v_lshl_add_u64 v[248:249], s[4:5], 0, v[134:135]
	ds_read_b128 v[202:205], v166 offset:32768
	ds_read_b128 v[206:209], v166 offset:33792
	ds_read_b128 v[210:213], v166 offset:34816
	ds_read_b128 v[214:217], v166 offset:35840
	ds_read_b128 v[222:225], v166 offset:36864
	ds_read_b128 v[226:229], v166 offset:37888
	ds_read_b128 v[230:233], v166 offset:38912
	ds_read_b128 v[234:237], v166 offset:39936
	global_load_lds_dwordx4 v[248:249], off
	s_mov_b32 m0, s45
	v_lshl_add_u64 v[248:249], s[4:5], 0, v[130:131]
	global_load_lds_dwordx4 v[248:249], off
	s_waitcnt vmcnt(8)
	s_waitcnt lgkmcnt(0)
	s_barrier
	s_waitcnt lgkmcnt(0)
	v_mfma_f32_16x16x32_bf16 v[124:127], v[170:173], v[202:205], v[124:127]
	v_mfma_f32_16x16x32_bf16 v[124:127], v[174:177], v[206:209], v[124:127]
	v_mfma_f32_16x16x32_bf16 v[120:123], v[182:185], v[206:209], v[120:123]
	v_mfma_f32_16x16x32_bf16 v[120:123], v[178:181], v[202:205], v[120:123]
	v_mfma_f32_16x16x32_bf16 v[116:119], v[186:189], v[202:205], v[116:119]
	v_mfma_f32_16x16x32_bf16 v[116:119], v[190:193], v[206:209], v[116:119]
	v_mfma_f32_16x16x32_bf16 v[112:115], v[198:201], v[206:209], v[112:115]
	v_mfma_f32_16x16x32_bf16 v[112:115], v[194:197], v[202:205], v[112:115]
	v_mfma_f32_16x16x32_bf16 v[96:99], v[194:197], v[210:213], v[96:99]
	v_mfma_f32_16x16x32_bf16 v[96:99], v[198:201], v[214:217], v[96:99]
	v_mfma_f32_16x16x32_bf16 v[100:103], v[190:193], v[214:217], v[100:103]
	v_mfma_f32_16x16x32_bf16 v[100:103], v[186:189], v[210:213], v[100:103]
	v_mfma_f32_16x16x32_bf16 v[104:107], v[178:181], v[210:213], v[104:107]
	v_mfma_f32_16x16x32_bf16 v[104:107], v[182:185], v[214:217], v[104:107]
	v_mfma_f32_16x16x32_bf16 v[108:111], v[174:177], v[214:217], v[108:111]
	v_mfma_f32_16x16x32_bf16 v[108:111], v[170:173], v[210:213], v[108:111]
	v_mfma_f32_16x16x32_bf16 v[92:95], v[170:173], v[222:225], v[92:95]
	v_mfma_f32_16x16x32_bf16 v[92:95], v[174:177], v[226:229], v[92:95]
	v_mfma_f32_16x16x32_bf16 v[88:91], v[182:185], v[226:229], v[88:91]
	v_mfma_f32_16x16x32_bf16 v[88:91], v[178:181], v[222:225], v[88:91]
	v_mfma_f32_16x16x32_bf16 v[84:87], v[186:189], v[222:225], v[84:87]
	v_mfma_f32_16x16x32_bf16 v[84:87], v[190:193], v[226:229], v[84:87]
	v_mfma_f32_16x16x32_bf16 v[80:83], v[198:201], v[226:229], v[80:83]
	v_mfma_f32_16x16x32_bf16 v[80:83], v[194:197], v[222:225], v[80:83]
	v_mfma_f32_16x16x32_bf16 v[64:67], v[194:197], v[230:233], v[64:67]
	v_mfma_f32_16x16x32_bf16 v[64:67], v[198:201], v[234:237], v[64:67]
	v_mfma_f32_16x16x32_bf16 v[68:71], v[190:193], v[234:237], v[68:71]
	v_mfma_f32_16x16x32_bf16 v[68:71], v[186:189], v[230:233], v[68:71]
	v_mfma_f32_16x16x32_bf16 v[72:75], v[178:181], v[230:233], v[72:75]
	v_mfma_f32_16x16x32_bf16 v[72:75], v[182:185], v[234:237], v[72:75]
	v_mfma_f32_16x16x32_bf16 v[76:79], v[174:177], v[234:237], v[76:79]
	v_mfma_f32_16x16x32_bf16 v[76:79], v[170:173], v[230:233], v[76:79]
	s_barrier
	s_add_i32 s4, s9, s39
	v_lshl_add_u64 v[218:219], v[218:219], 0, s[24:25]
	s_mov_b32 m0, s4
	ds_read_b128 v[202:205], v166 offset:49152
	ds_read_b128 v[206:209], v166 offset:50176
	ds_read_b128 v[210:213], v166 offset:51200
	ds_read_b128 v[214:217], v166 offset:52224
	ds_read_b128 v[222:225], v166 offset:53248
	ds_read_b128 v[226:229], v166 offset:54272
	ds_read_b128 v[230:233], v166 offset:55296
	ds_read_b128 v[234:237], v166 offset:56320
	global_load_lds_dwordx4 v[218:219], off
	v_lshl_add_u64 v[218:219], v[238:239], 0, s[24:25]
	s_add_i32 m0, s4, 0x2000
	s_add_i32 s4, s10, s39
	global_load_lds_dwordx4 v[218:219], off
	s_mov_b32 m0, s4
	v_lshl_add_u64 v[218:219], v[240:241], 0, s[24:25]
	global_load_lds_dwordx4 v[218:219], off
	s_add_i32 m0, s4, 0x2000
	v_lshl_add_u64 v[218:219], v[242:243], 0, s[24:25]
	global_load_lds_dwordx4 v[218:219], off
	s_mov_b32 m0, s49
	v_lshl_add_u64 v[218:219], v[244:245], 0, s[24:25]
	global_load_lds_dwordx4 v[218:219], off
	s_mov_b32 m0, s50
	v_lshl_add_u64 v[218:219], v[246:247], 0, s[24:25]
	global_load_lds_dwordx4 v[218:219], off
	s_waitcnt vmcnt(8)
	s_waitcnt lgkmcnt(0)
	s_barrier
	s_waitcnt lgkmcnt(0)
	v_mfma_f32_16x16x32_bf16 v[60:63], v[170:173], v[202:205], v[60:63]
	v_mfma_f32_16x16x32_bf16 v[60:63], v[174:177], v[206:209], v[60:63]
	v_mfma_f32_16x16x32_bf16 v[56:59], v[182:185], v[206:209], v[56:59]
	v_mfma_f32_16x16x32_bf16 v[56:59], v[178:181], v[202:205], v[56:59]
	v_mfma_f32_16x16x32_bf16 v[52:55], v[186:189], v[202:205], v[52:55]
	v_mfma_f32_16x16x32_bf16 v[52:55], v[190:193], v[206:209], v[52:55]
	v_mfma_f32_16x16x32_bf16 v[48:51], v[198:201], v[206:209], v[48:51]
	v_mfma_f32_16x16x32_bf16 v[48:51], v[194:197], v[202:205], v[48:51]
	v_mfma_f32_16x16x32_bf16 v[32:35], v[194:197], v[210:213], v[32:35]
	v_mfma_f32_16x16x32_bf16 v[32:35], v[198:201], v[214:217], v[32:35]
	v_mfma_f32_16x16x32_bf16 v[36:39], v[190:193], v[214:217], v[36:39]
	v_mfma_f32_16x16x32_bf16 v[36:39], v[186:189], v[210:213], v[36:39]
	v_mfma_f32_16x16x32_bf16 v[40:43], v[178:181], v[210:213], v[40:43]
	v_mfma_f32_16x16x32_bf16 v[40:43], v[182:185], v[214:217], v[40:43]
	v_mfma_f32_16x16x32_bf16 v[44:47], v[174:177], v[214:217], v[44:47]
	v_mfma_f32_16x16x32_bf16 v[44:47], v[170:173], v[210:213], v[44:47]
	v_mfma_f32_16x16x32_bf16 v[28:31], v[170:173], v[222:225], v[28:31]
	v_mfma_f32_16x16x32_bf16 v[28:31], v[174:177], v[226:229], v[28:31]
	v_mfma_f32_16x16x32_bf16 v[24:27], v[182:185], v[226:229], v[24:27]
	v_mfma_f32_16x16x32_bf16 v[24:27], v[178:181], v[222:225], v[24:27]
	v_mfma_f32_16x16x32_bf16 v[20:23], v[186:189], v[222:225], v[20:23]
	v_mfma_f32_16x16x32_bf16 v[20:23], v[190:193], v[226:229], v[20:23]
	v_mfma_f32_16x16x32_bf16 v[16:19], v[198:201], v[226:229], v[16:19]
	v_mfma_f32_16x16x32_bf16 v[16:19], v[194:197], v[222:225], v[16:19]
	v_mfma_f32_16x16x32_bf16 v[0:3], v[194:197], v[230:233], v[0:3]
	v_mfma_f32_16x16x32_bf16 v[0:3], v[198:201], v[234:237], v[0:3]
	v_mfma_f32_16x16x32_bf16 v[4:7], v[190:193], v[234:237], v[4:7]
	v_mfma_f32_16x16x32_bf16 v[4:7], v[186:189], v[230:233], v[4:7]
	v_mfma_f32_16x16x32_bf16 v[8:11], v[178:181], v[230:233], v[8:11]
	v_mfma_f32_16x16x32_bf16 v[8:11], v[182:185], v[234:237], v[8:11]
	v_mfma_f32_16x16x32_bf16 v[12:15], v[174:177], v[234:237], v[12:15]
	v_mfma_f32_16x16x32_bf16 v[12:15], v[170:173], v[230:233], v[12:15]
	s_add_u32 s2, s2, 0x100
	s_addc_u32 s3, s3, 0
	s_add_u32 s6, s6, 0x100
	s_addc_u32 s7, s7, 0
	s_cmp_ge_i32 s8, s51
	s_mov_b32 s4, s8
	s_barrier
	s_cbranch_scc0 .LBB0_970

.LBB0_1056:
	ds_read_b128 v[140:143], v222
	ds_read_b128 v[144:147], v222 offset:1024
	ds_read_b128 v[148:151], v222 offset:2048
	ds_read_b128 v[152:155], v222 offset:3072
	ds_read_b128 v[156:159], v223
	ds_read_b128 v[160:163], v223 offset:1024
	ds_read_b128 v[164:167], v223 offset:2048
	ds_read_b128 v[168:171], v223 offset:3072
	s_add_i32 s62, s26, 2
	s_add_u32 s27, s24, 0x4000
	s_addc_u32 s28, s25, 0
	s_cmp_eq_u32 s46, s26
	s_cselect_b32 s30, s0, s27
	s_cselect_b32 s31, s1, s28
	s_cselect_b32 s28, s22, s60
	s_cselect_b32 s29, s23, s61
	s_add_u32 s26, s30, 0x8000
	s_addc_u32 s27, s31, 0
	v_lshl_add_u64 v[204:205], s[24:25], 0, v[132:133]
	s_add_i32 m0, s38, 0xc000
	ds_read_b128 v[172:175], v224
	ds_read_b128 v[176:179], v224 offset:1024
	ds_read_b128 v[180:183], v224 offset:2048
	ds_read_b128 v[184:187], v224 offset:3072
	ds_read_b128 v[188:191], v224 offset:4096
	ds_read_b128 v[192:195], v224 offset:5120
	ds_read_b128 v[196:199], v224 offset:6144
	ds_read_b128 v[200:203], v224 offset:7168
	global_load_lds_dwordx4 v[204:205], off
	s_add_i32 m0, s38, 0xe000
	v_lshl_add_u64 v[204:205], s[24:25], 0, v[134:135]
	global_load_lds_dwordx4 v[204:205], off
	s_waitcnt vmcnt(8)
	s_waitcnt lgkmcnt(0)
	s_barrier
	s_waitcnt lgkmcnt(0)
	v_mfma_f32_16x16x32_bf16 v[124:127], v[140:143], v[172:175], v[124:127]
	v_mfma_f32_16x16x32_bf16 v[124:127], v[144:147], v[176:179], v[124:127]
	v_mfma_f32_16x16x32_bf16 v[120:123], v[152:155], v[176:179], v[120:123]
	v_mfma_f32_16x16x32_bf16 v[120:123], v[148:151], v[172:175], v[120:123]
	v_mfma_f32_16x16x32_bf16 v[108:111], v[156:159], v[172:175], v[108:111]
	v_mfma_f32_16x16x32_bf16 v[108:111], v[160:163], v[176:179], v[108:111]
	v_mfma_f32_16x16x32_bf16 v[100:103], v[168:171], v[176:179], v[100:103]
	v_mfma_f32_16x16x32_bf16 v[100:103], v[164:167], v[172:175], v[100:103]
	v_mfma_f32_16x16x32_bf16 v[84:87], v[164:167], v[180:183], v[84:87]
	v_mfma_f32_16x16x32_bf16 v[84:87], v[168:171], v[184:187], v[84:87]
	v_mfma_f32_16x16x32_bf16 v[92:95], v[160:163], v[184:187], v[92:95]
	v_mfma_f32_16x16x32_bf16 v[92:95], v[156:159], v[180:183], v[92:95]
	v_mfma_f32_16x16x32_bf16 v[112:115], v[148:151], v[180:183], v[112:115]
	v_mfma_f32_16x16x32_bf16 v[112:115], v[152:155], v[184:187], v[112:115]
	v_mfma_f32_16x16x32_bf16 v[116:119], v[144:147], v[184:187], v[116:119]
	v_mfma_f32_16x16x32_bf16 v[116:119], v[140:143], v[180:183], v[116:119]
	v_mfma_f32_16x16x32_bf16 v[104:107], v[140:143], v[188:191], v[104:107]
	v_mfma_f32_16x16x32_bf16 v[104:107], v[144:147], v[192:195], v[104:107]
	v_mfma_f32_16x16x32_bf16 v[96:99], v[152:155], v[192:195], v[96:99]
	v_mfma_f32_16x16x32_bf16 v[96:99], v[148:151], v[188:191], v[96:99]
	v_mfma_f32_16x16x32_bf16 v[76:79], v[156:159], v[188:191], v[76:79]
	v_mfma_f32_16x16x32_bf16 v[76:79], v[160:163], v[192:195], v[76:79]
	v_mfma_f32_16x16x32_bf16 v[72:75], v[168:171], v[192:195], v[72:75]
	v_mfma_f32_16x16x32_bf16 v[72:75], v[164:167], v[188:191], v[72:75]
	v_mfma_f32_16x16x32_bf16 v[64:67], v[164:167], v[196:199], v[64:67]
	v_mfma_f32_16x16x32_bf16 v[64:67], v[168:171], v[200:203], v[64:67]
	v_mfma_f32_16x16x32_bf16 v[68:71], v[160:163], v[200:203], v[68:71]
	v_mfma_f32_16x16x32_bf16 v[68:71], v[156:159], v[196:199], v[68:71]
	v_mfma_f32_16x16x32_bf16 v[80:83], v[148:151], v[196:199], v[80:83]
	v_mfma_f32_16x16x32_bf16 v[80:83], v[152:155], v[200:203], v[80:83]
	v_mfma_f32_16x16x32_bf16 v[88:91], v[144:147], v[200:203], v[88:91]
	v_mfma_f32_16x16x32_bf16 v[88:91], v[140:143], v[196:199], v[88:91]
	s_barrier
	s_add_i32 s63, s50, s37
	v_lshl_add_u64 v[204:205], s[28:29], 0, v[128:129]
	s_mov_b32 m0, s63
	ds_read_b128 v[172:175], v224 offset:16384
	ds_read_b128 v[176:179], v224 offset:17408
	ds_read_b128 v[180:183], v224 offset:18432
	ds_read_b128 v[184:187], v224 offset:19456
	ds_read_b128 v[188:191], v224 offset:20480
	ds_read_b128 v[192:195], v224 offset:21504
	ds_read_b128 v[196:199], v224 offset:22528
	ds_read_b128 v[200:203], v224 offset:23552
	global_load_lds_dwordx4 v[204:205], off
	s_add_i32 m0, s63, 0x2000
	s_add_u32 s64, s28, 0x4000
	v_lshl_add_u64 v[204:205], s[28:29], 0, v[130:131]
	s_addc_u32 s65, s29, 0
	s_add_i32 s63, s51, s37
	global_load_lds_dwordx4 v[204:205], off
	s_mov_b32 m0, s63
	v_lshl_add_u64 v[204:205], s[64:65], 0, v[128:129]
	global_load_lds_dwordx4 v[204:205], off
	s_add_i32 m0, s63, 0x2000
	v_lshl_add_u64 v[204:205], s[64:65], 0, v[130:131]
	global_load_lds_dwordx4 v[204:205], off
	s_mov_b32 m0, s38
	v_lshl_add_u64 v[204:205], s[30:31], 0, v[128:129]
	global_load_lds_dwordx4 v[204:205], off
	s_mov_b32 m0, s39
	v_lshl_add_u64 v[204:205], s[30:31], 0, v[130:131]
	global_load_lds_dwordx4 v[204:205], off
	s_waitcnt vmcnt(8)
	s_waitcnt lgkmcnt(0)
	s_barrier
	s_waitcnt lgkmcnt(0)
	v_mfma_f32_16x16x32_bf16 v[60:63], v[140:143], v[172:175], v[60:63]
	v_mfma_f32_16x16x32_bf16 v[60:63], v[144:147], v[176:179], v[60:63]
	v_mfma_f32_16x16x32_bf16 v[56:59], v[152:155], v[176:179], v[56:59]
	v_mfma_f32_16x16x32_bf16 v[56:59], v[148:151], v[172:175], v[56:59]
	v_mfma_f32_16x16x32_bf16 v[44:47], v[156:159], v[172:175], v[44:47]
	v_mfma_f32_16x16x32_bf16 v[44:47], v[160:163], v[176:179], v[44:47]
	v_mfma_f32_16x16x32_bf16 v[36:39], v[168:171], v[176:179], v[36:39]
	v_mfma_f32_16x16x32_bf16 v[36:39], v[164:167], v[172:175], v[36:39]
	v_mfma_f32_16x16x32_bf16 v[20:23], v[164:167], v[180:183], v[20:23]
	v_mfma_f32_16x16x32_bf16 v[20:23], v[168:171], v[184:187], v[20:23]
	v_mfma_f32_16x16x32_bf16 v[28:31], v[160:163], v[184:187], v[28:31]
	v_mfma_f32_16x16x32_bf16 v[28:31], v[156:159], v[180:183], v[28:31]
	v_mfma_f32_16x16x32_bf16 v[48:51], v[148:151], v[180:183], v[48:51]
	v_mfma_f32_16x16x32_bf16 v[48:51], v[152:155], v[184:187], v[48:51]
	v_mfma_f32_16x16x32_bf16 v[52:55], v[144:147], v[184:187], v[52:55]
	v_mfma_f32_16x16x32_bf16 v[52:55], v[140:143], v[180:183], v[52:55]
	v_mfma_f32_16x16x32_bf16 v[40:43], v[140:143], v[188:191], v[40:43]
	v_mfma_f32_16x16x32_bf16 v[40:43], v[144:147], v[192:195], v[40:43]
	v_mfma_f32_16x16x32_bf16 v[32:35], v[152:155], v[192:195], v[32:35]
	v_mfma_f32_16x16x32_bf16 v[32:35], v[148:151], v[188:191], v[32:35]
	v_mfma_f32_16x16x32_bf16 v[12:15], v[156:159], v[188:191], v[12:15]
	v_mfma_f32_16x16x32_bf16 v[12:15], v[160:163], v[192:195], v[12:15]
	v_mfma_f32_16x16x32_bf16 v[8:11], v[168:171], v[192:195], v[8:11]
	v_mfma_f32_16x16x32_bf16 v[8:11], v[164:167], v[188:191], v[8:11]
	v_mfma_f32_16x16x32_bf16 v[0:3], v[164:167], v[196:199], v[0:3]
	v_mfma_f32_16x16x32_bf16 v[0:3], v[168:171], v[200:203], v[0:3]
	v_mfma_f32_16x16x32_bf16 v[4:7], v[160:163], v[200:203], v[4:7]
	v_mfma_f32_16x16x32_bf16 v[4:7], v[156:159], v[196:199], v[4:7]
	v_mfma_f32_16x16x32_bf16 v[16:19], v[148:151], v[196:199], v[16:19]
	v_mfma_f32_16x16x32_bf16 v[16:19], v[152:155], v[200:203], v[16:19]
	v_mfma_f32_16x16x32_bf16 v[24:27], v[144:147], v[200:203], v[24:27]
	v_mfma_f32_16x16x32_bf16 v[24:27], v[140:143], v[196:199], v[24:27]
	s_barrier
	s_add_i32 s63, 0, 0x18000
	s_add_i32 s64, 0, 0x1c000
	v_add_u32_e32 v152, s63, v219
	v_add_u32_e32 v168, s64, v219
	ds_read_b128 v[140:143], v152
	ds_read_b128 v[144:147], v152 offset:1024
	ds_read_b128 v[148:151], v152 offset:2048
	ds_read_b128 v[152:155], v152 offset:3072
	ds_read_b128 v[156:159], v168
	ds_read_b128 v[160:163], v168 offset:1024
	ds_read_b128 v[164:167], v168 offset:2048
	ds_read_b128 v[168:171], v168 offset:3072
	s_add_u32 s30, s30, 0x4000
	s_addc_u32 s31, s31, 0
	s_mov_b32 m0, s40
	v_lshl_add_u64 v[204:205], s[30:31], 0, v[128:129]
	ds_read_b128 v[172:175], v224 offset:32768
	ds_read_b128 v[176:179], v224 offset:33792
	ds_read_b128 v[180:183], v224 offset:34816
	ds_read_b128 v[184:187], v224 offset:35840
	ds_read_b128 v[188:191], v224 offset:36864
	ds_read_b128 v[192:195], v224 offset:37888
	ds_read_b128 v[196:199], v224 offset:38912
	ds_read_b128 v[200:203], v224 offset:39936
	global_load_lds_dwordx4 v[204:205], off
	s_mov_b32 m0, s41
	v_lshl_add_u64 v[204:205], s[30:31], 0, v[130:131]
	global_load_lds_dwordx4 v[204:205], off
	s_waitcnt vmcnt(8)
	s_waitcnt lgkmcnt(0)
	s_barrier
	s_waitcnt lgkmcnt(0)
	v_mfma_f32_16x16x32_bf16 v[124:127], v[140:143], v[172:175], v[124:127]
	v_mfma_f32_16x16x32_bf16 v[124:127], v[144:147], v[176:179], v[124:127]
	v_mfma_f32_16x16x32_bf16 v[120:123], v[152:155], v[176:179], v[120:123]
	v_mfma_f32_16x16x32_bf16 v[120:123], v[148:151], v[172:175], v[120:123]
	v_mfma_f32_16x16x32_bf16 v[108:111], v[156:159], v[172:175], v[108:111]
	v_mfma_f32_16x16x32_bf16 v[108:111], v[160:163], v[176:179], v[108:111]
	v_mfma_f32_16x16x32_bf16 v[100:103], v[168:171], v[176:179], v[100:103]
	v_mfma_f32_16x16x32_bf16 v[100:103], v[164:167], v[172:175], v[100:103]
	v_mfma_f32_16x16x32_bf16 v[84:87], v[164:167], v[180:183], v[84:87]
	v_mfma_f32_16x16x32_bf16 v[84:87], v[168:171], v[184:187], v[84:87]
	v_mfma_f32_16x16x32_bf16 v[92:95], v[160:163], v[184:187], v[92:95]
	v_mfma_f32_16x16x32_bf16 v[92:95], v[156:159], v[180:183], v[92:95]
	v_mfma_f32_16x16x32_bf16 v[112:115], v[148:151], v[180:183], v[112:115]
	v_mfma_f32_16x16x32_bf16 v[112:115], v[152:155], v[184:187], v[112:115]
	v_mfma_f32_16x16x32_bf16 v[116:119], v[144:147], v[184:187], v[116:119]
	v_mfma_f32_16x16x32_bf16 v[116:119], v[140:143], v[180:183], v[116:119]
	v_mfma_f32_16x16x32_bf16 v[104:107], v[140:143], v[188:191], v[104:107]
	v_mfma_f32_16x16x32_bf16 v[104:107], v[144:147], v[192:195], v[104:107]
	v_mfma_f32_16x16x32_bf16 v[96:99], v[152:155], v[192:195], v[96:99]
	v_mfma_f32_16x16x32_bf16 v[96:99], v[148:151], v[188:191], v[96:99]
	v_mfma_f32_16x16x32_bf16 v[76:79], v[156:159], v[188:191], v[76:79]
	v_mfma_f32_16x16x32_bf16 v[76:79], v[160:163], v[192:195], v[76:79]
	v_mfma_f32_16x16x32_bf16 v[72:75], v[168:171], v[192:195], v[72:75]
	v_mfma_f32_16x16x32_bf16 v[72:75], v[164:167], v[188:191], v[72:75]
	v_mfma_f32_16x16x32_bf16 v[64:67], v[164:167], v[196:199], v[64:67]
	v_mfma_f32_16x16x32_bf16 v[64:67], v[168:171], v[200:203], v[64:67]
	v_mfma_f32_16x16x32_bf16 v[68:71], v[160:163], v[200:203], v[68:71]
	v_mfma_f32_16x16x32_bf16 v[68:71], v[156:159], v[196:199], v[68:71]
	v_mfma_f32_16x16x32_bf16 v[80:83], v[148:151], v[196:199], v[80:83]
	v_mfma_f32_16x16x32_bf16 v[80:83], v[152:155], v[200:203], v[80:83]
	v_mfma_f32_16x16x32_bf16 v[88:91], v[144:147], v[200:203], v[88:91]
	v_mfma_f32_16x16x32_bf16 v[88:91], v[140:143], v[196:199], v[88:91]
	s_barrier
	s_add_u32 s30, s28, 0x8000
	s_addc_u32 s31, s29, 0
	s_add_i32 s63, s63, s37
	v_lshl_add_u64 v[204:205], s[30:31], 0, v[128:129]
	s_mov_b32 m0, s63
	ds_read_b128 v[172:175], v224 offset:49152
	ds_read_b128 v[176:179], v224 offset:50176
	ds_read_b128 v[180:183], v224 offset:51200
	ds_read_b128 v[184:187], v224 offset:52224
	ds_read_b128 v[188:191], v224 offset:53248
	ds_read_b128 v[192:195], v224 offset:54272
	ds_read_b128 v[196:199], v224 offset:55296
	ds_read_b128 v[200:203], v224 offset:56320
	global_load_lds_dwordx4 v[204:205], off
	s_add_i32 m0, s63, 0x2000
	s_add_u32 s28, s28, 0xc000
	v_lshl_add_u64 v[204:205], s[30:31], 0, v[130:131]
	s_addc_u32 s29, s29, 0
	s_add_i32 s30, s64, s37
	global_load_lds_dwordx4 v[204:205], off
	s_mov_b32 m0, s30
	v_lshl_add_u64 v[204:205], s[28:29], 0, v[128:129]
	global_load_lds_dwordx4 v[204:205], off
	s_add_i32 m0, s30, 0x2000
	v_lshl_add_u64 v[204:205], s[28:29], 0, v[130:131]
	global_load_lds_dwordx4 v[204:205], off
	s_mov_b32 m0, s44
	v_lshl_add_u64 v[204:205], s[26:27], 0, v[128:129]
	global_load_lds_dwordx4 v[204:205], off
	s_mov_b32 m0, s45
	v_lshl_add_u64 v[204:205], s[26:27], 0, v[130:131]
	global_load_lds_dwordx4 v[204:205], off
	s_waitcnt vmcnt(8)
	s_waitcnt lgkmcnt(0)
	s_barrier
	s_waitcnt lgkmcnt(0)
	v_mfma_f32_16x16x32_bf16 v[60:63], v[140:143], v[172:175], v[60:63]
	v_mfma_f32_16x16x32_bf16 v[60:63], v[144:147], v[176:179], v[60:63]
	v_mfma_f32_16x16x32_bf16 v[56:59], v[152:155], v[176:179], v[56:59]
	v_mfma_f32_16x16x32_bf16 v[56:59], v[148:151], v[172:175], v[56:59]
	v_mfma_f32_16x16x32_bf16 v[44:47], v[156:159], v[172:175], v[44:47]
	v_mfma_f32_16x16x32_bf16 v[44:47], v[160:163], v[176:179], v[44:47]
	v_mfma_f32_16x16x32_bf16 v[36:39], v[168:171], v[176:179], v[36:39]
	v_mfma_f32_16x16x32_bf16 v[36:39], v[164:167], v[172:175], v[36:39]
	v_mfma_f32_16x16x32_bf16 v[20:23], v[164:167], v[180:183], v[20:23]
	v_mfma_f32_16x16x32_bf16 v[20:23], v[168:171], v[184:187], v[20:23]
	v_mfma_f32_16x16x32_bf16 v[28:31], v[160:163], v[184:187], v[28:31]
	v_mfma_f32_16x16x32_bf16 v[28:31], v[156:159], v[180:183], v[28:31]
	v_mfma_f32_16x16x32_bf16 v[48:51], v[148:151], v[180:183], v[48:51]
	v_mfma_f32_16x16x32_bf16 v[48:51], v[152:155], v[184:187], v[48:51]
	v_mfma_f32_16x16x32_bf16 v[52:55], v[144:147], v[184:187], v[52:55]
	v_mfma_f32_16x16x32_bf16 v[52:55], v[140:143], v[180:183], v[52:55]
	v_mfma_f32_16x16x32_bf16 v[40:43], v[140:143], v[188:191], v[40:43]
	v_mfma_f32_16x16x32_bf16 v[40:43], v[144:147], v[192:195], v[40:43]
	v_mfma_f32_16x16x32_bf16 v[32:35], v[152:155], v[192:195], v[32:35]
	v_mfma_f32_16x16x32_bf16 v[32:35], v[148:151], v[188:191], v[32:35]
	v_mfma_f32_16x16x32_bf16 v[12:15], v[156:159], v[188:191], v[12:15]
	v_mfma_f32_16x16x32_bf16 v[12:15], v[160:163], v[192:195], v[12:15]
	v_mfma_f32_16x16x32_bf16 v[8:11], v[168:171], v[192:195], v[8:11]
	v_mfma_f32_16x16x32_bf16 v[8:11], v[164:167], v[188:191], v[8:11]
	v_mfma_f32_16x16x32_bf16 v[0:3], v[164:167], v[196:199], v[0:3]
	v_mfma_f32_16x16x32_bf16 v[0:3], v[168:171], v[200:203], v[0:3]
	v_mfma_f32_16x16x32_bf16 v[4:7], v[160:163], v[200:203], v[4:7]
	v_mfma_f32_16x16x32_bf16 v[4:7], v[156:159], v[196:199], v[4:7]
	v_mfma_f32_16x16x32_bf16 v[16:19], v[148:151], v[196:199], v[16:19]
	v_mfma_f32_16x16x32_bf16 v[16:19], v[152:155], v[200:203], v[16:19]
	v_mfma_f32_16x16x32_bf16 v[24:27], v[144:147], v[200:203], v[24:27]
	v_mfma_f32_16x16x32_bf16 v[24:27], v[140:143], v[196:199], v[24:27]
	s_add_u32 s24, s24, 0x10000
	s_addc_u32 s25, s25, 0
	s_add_u32 s60, s60, 0x10000
	s_addc_u32 s61, s61, 0
	s_cmp_ge_i32 s62, s43
	s_mov_b32 s26, s62
	s_barrier
	s_cbranch_scc0 .LBB0_1056
	v_pk_mul_f32 v[198:199], v[126:127], 0.5 op_sel_hi:[1,0]
	v_pk_mul_f32 v[200:201], v[124:125], 0.5 op_sel_hi:[1,0]
	v_pk_mul_f32 v[202:203], v[122:123], 0.5 op_sel_hi:[1,0]
	v_pk_mul_f32 v[204:205], v[120:121], 0.5 op_sel_hi:[1,0]
	v_pk_mul_f32 v[208:209], v[110:111], 0.5 op_sel_hi:[1,0]
	v_pk_mul_f32 v[206:207], v[108:109], 0.5 op_sel_hi:[1,0]
	v_pk_mul_f32 v[196:197], v[102:103], 0.5 op_sel_hi:[1,0]
	v_pk_mul_f32 v[194:195], v[100:101], 0.5 op_sel_hi:[1,0]
	v_pk_mul_f32 v[192:193], v[118:119], 0.5 op_sel_hi:[1,0]
	v_pk_mul_f32 v[190:191], v[116:117], 0.5 op_sel_hi:[1,0]
	v_pk_mul_f32 v[188:189], v[114:115], 0.5 op_sel_hi:[1,0]
	v_pk_mul_f32 v[186:187], v[112:113], 0.5 op_sel_hi:[1,0]
	v_pk_mul_f32 v[184:185], v[94:95], 0.5 op_sel_hi:[1,0]
	v_pk_mul_f32 v[182:183], v[92:93], 0.5 op_sel_hi:[1,0]
	v_pk_mul_f32 v[180:181], v[86:87], 0.5 op_sel_hi:[1,0]
	v_pk_mul_f32 v[178:179], v[84:85], 0.5 op_sel_hi:[1,0]
	v_pk_mul_f32 v[176:177], v[106:107], 0.5 op_sel_hi:[1,0]
	v_pk_mul_f32 v[174:175], v[104:105], 0.5 op_sel_hi:[1,0]
	v_pk_mul_f32 v[172:173], v[98:99], 0.5 op_sel_hi:[1,0]
	v_pk_mul_f32 v[170:171], v[96:97], 0.5 op_sel_hi:[1,0]
	v_pk_mul_f32 v[168:169], v[78:79], 0.5 op_sel_hi:[1,0]
	v_pk_mul_f32 v[166:167], v[76:77], 0.5 op_sel_hi:[1,0]
	v_pk_mul_f32 v[164:165], v[74:75], 0.5 op_sel_hi:[1,0]
	v_pk_mul_f32 v[162:163], v[72:73], 0.5 op_sel_hi:[1,0]
	v_pk_mul_f32 v[160:161], v[90:91], 0.5 op_sel_hi:[1,0]
	v_pk_mul_f32 v[158:159], v[88:89], 0.5 op_sel_hi:[1,0]
	v_pk_mul_f32 v[156:157], v[82:83], 0.5 op_sel_hi:[1,0]
	v_pk_mul_f32 v[154:155], v[80:81], 0.5 op_sel_hi:[1,0]
	v_pk_mul_f32 v[152:153], v[70:71], 0.5 op_sel_hi:[1,0]
	v_pk_mul_f32 v[150:151], v[68:69], 0.5 op_sel_hi:[1,0]
	v_pk_mul_f32 v[148:149], v[66:67], 0.5 op_sel_hi:[1,0]
	v_pk_mul_f32 v[146:147], v[64:65], 0.5 op_sel_hi:[1,0]
	v_pk_mul_f32 v[142:143], v[62:63], 0.5 op_sel_hi:[1,0]
	v_pk_mul_f32 v[140:141], v[60:61], 0.5 op_sel_hi:[1,0]
	v_pk_mul_f32 v[126:127], v[58:59], 0.5 op_sel_hi:[1,0]
	v_pk_mul_f32 v[124:125], v[56:57], 0.5 op_sel_hi:[1,0]
	v_pk_mul_f32 v[122:123], v[46:47], 0.5 op_sel_hi:[1,0]
	v_pk_mul_f32 v[120:121], v[44:45], 0.5 op_sel_hi:[1,0]
	v_pk_mul_f32 v[118:119], v[38:39], 0.5 op_sel_hi:[1,0]
	v_pk_mul_f32 v[116:117], v[36:37], 0.5 op_sel_hi:[1,0]
	v_pk_mul_f32 v[114:115], v[54:55], 0.5 op_sel_hi:[1,0]
	v_pk_mul_f32 v[112:113], v[52:53], 0.5 op_sel_hi:[1,0]
	v_pk_mul_f32 v[110:111], v[50:51], 0.5 op_sel_hi:[1,0]
	v_pk_mul_f32 v[108:109], v[48:49], 0.5 op_sel_hi:[1,0]
	v_pk_mul_f32 v[106:107], v[30:31], 0.5 op_sel_hi:[1,0]
	v_pk_mul_f32 v[104:105], v[28:29], 0.5 op_sel_hi:[1,0]
	v_pk_mul_f32 v[102:103], v[22:23], 0.5 op_sel_hi:[1,0]
	v_pk_mul_f32 v[100:101], v[20:21], 0.5 op_sel_hi:[1,0]
	v_pk_mul_f32 v[98:99], v[42:43], 0.5 op_sel_hi:[1,0]
	v_pk_mul_f32 v[96:97], v[40:41], 0.5 op_sel_hi:[1,0]
	v_pk_mul_f32 v[94:95], v[34:35], 0.5 op_sel_hi:[1,0]
	v_pk_mul_f32 v[92:93], v[32:33], 0.5 op_sel_hi:[1,0]
	v_pk_mul_f32 v[90:91], v[14:15], 0.5 op_sel_hi:[1,0]
	v_pk_mul_f32 v[88:89], v[12:13], 0.5 op_sel_hi:[1,0]
	v_pk_mul_f32 v[86:87], v[10:11], 0.5 op_sel_hi:[1,0]
	v_pk_mul_f32 v[84:85], v[8:9], 0.5 op_sel_hi:[1,0]
	v_pk_mul_f32 v[82:83], v[26:27], 0.5 op_sel_hi:[1,0]
	v_pk_mul_f32 v[80:81], v[24:25], 0.5 op_sel_hi:[1,0]
	v_pk_mul_f32 v[78:79], v[18:19], 0.5 op_sel_hi:[1,0]
	v_pk_mul_f32 v[76:77], v[16:17], 0.5 op_sel_hi:[1,0]
	v_pk_mul_f32 v[74:75], v[6:7], 0.5 op_sel_hi:[1,0]
	v_pk_mul_f32 v[72:73], v[4:5], 0.5 op_sel_hi:[1,0]
	v_pk_mul_f32 v[70:71], v[2:3], 0.5 op_sel_hi:[1,0]
	v_pk_mul_f32 v[68:69], v[0:1], 0.5 op_sel_hi:[1,0]

.LBB0_1159:
	ds_read_b128 v[128:131], v205
	ds_read_b128 v[132:135], v205 offset:1024
	ds_read_b128 v[136:139], v205 offset:2048
	ds_read_b128 v[140:143], v205 offset:3072
	ds_read_b128 v[144:147], v206
	ds_read_b128 v[160:163], v206 offset:1024
	ds_read_b128 v[164:167], v206 offset:2048
	ds_read_b128 v[168:171], v206 offset:3072
	s_add_i32 s41, s6, 2
	s_add_u32 s68, s0, 0x80
	s_addc_u32 s7, s1, 0
	s_cmp_eq_u32 s57, s6
	s_cselect_b32 s6, s34, s68
	s_cselect_b32 s7, s35, s7
	s_cselect_b32 s69, s37, s39
	s_cselect_b32 s68, s36, s38
	v_lshl_add_u64 v[200:201], s[0:1], 0, v[152:153]
	s_add_i32 m0, s47, 0xc000
	ds_read_b128 v[172:175], v207
	ds_read_b128 v[176:179], v207 offset:1024
	ds_read_b128 v[180:183], v207 offset:2048
	ds_read_b128 v[184:187], v207 offset:3072
	ds_read_b128 v[188:191], v207 offset:4096
	ds_read_b128 v[192:195], v207 offset:5120
	ds_read_b128 v[196:199], v207 offset:6144
	ds_read_b128 v[212:215], v207 offset:7168
	global_load_lds_dwordx4 v[200:201], off
	s_add_i32 m0, s47, 0xe000
	v_lshl_add_u64 v[200:201], s[0:1], 0, v[154:155]
	global_load_lds_dwordx4 v[200:201], off
	s_waitcnt vmcnt(8)
	s_waitcnt lgkmcnt(0)
	s_barrier
	s_waitcnt lgkmcnt(0)
	v_mfma_f32_16x16x32_bf16 v[124:127], v[128:131], v[172:175], v[124:127]
	v_mfma_f32_16x16x32_bf16 v[124:127], v[132:135], v[176:179], v[124:127]
	v_mfma_f32_16x16x32_bf16 v[120:123], v[140:143], v[176:179], v[120:123]
	v_mfma_f32_16x16x32_bf16 v[120:123], v[136:139], v[172:175], v[120:123]
	v_mfma_f32_16x16x32_bf16 v[116:119], v[144:147], v[172:175], v[116:119]
	v_mfma_f32_16x16x32_bf16 v[116:119], v[160:163], v[176:179], v[116:119]
	v_mfma_f32_16x16x32_bf16 v[112:115], v[168:171], v[176:179], v[112:115]
	v_mfma_f32_16x16x32_bf16 v[112:115], v[164:167], v[172:175], v[112:115]
	v_mfma_f32_16x16x32_bf16 v[96:99], v[164:167], v[180:183], v[96:99]
	v_mfma_f32_16x16x32_bf16 v[96:99], v[168:171], v[184:187], v[96:99]
	v_mfma_f32_16x16x32_bf16 v[100:103], v[160:163], v[184:187], v[100:103]
	v_mfma_f32_16x16x32_bf16 v[100:103], v[144:147], v[180:183], v[100:103]
	v_mfma_f32_16x16x32_bf16 v[104:107], v[136:139], v[180:183], v[104:107]
	v_mfma_f32_16x16x32_bf16 v[104:107], v[140:143], v[184:187], v[104:107]
	v_mfma_f32_16x16x32_bf16 v[108:111], v[132:135], v[184:187], v[108:111]
	v_mfma_f32_16x16x32_bf16 v[108:111], v[128:131], v[180:183], v[108:111]
	v_mfma_f32_16x16x32_bf16 v[92:95], v[128:131], v[188:191], v[92:95]
	v_mfma_f32_16x16x32_bf16 v[92:95], v[132:135], v[192:195], v[92:95]
	v_mfma_f32_16x16x32_bf16 v[88:91], v[140:143], v[192:195], v[88:91]
	v_mfma_f32_16x16x32_bf16 v[88:91], v[136:139], v[188:191], v[88:91]
	v_mfma_f32_16x16x32_bf16 v[84:87], v[144:147], v[188:191], v[84:87]
	v_mfma_f32_16x16x32_bf16 v[84:87], v[160:163], v[192:195], v[84:87]
	v_mfma_f32_16x16x32_bf16 v[80:83], v[168:171], v[192:195], v[80:83]
	v_mfma_f32_16x16x32_bf16 v[80:83], v[164:167], v[188:191], v[80:83]
	v_mfma_f32_16x16x32_bf16 v[64:67], v[164:167], v[196:199], v[64:67]
	v_mfma_f32_16x16x32_bf16 v[64:67], v[168:171], v[212:215], v[64:67]
	v_mfma_f32_16x16x32_bf16 v[68:71], v[160:163], v[212:215], v[68:71]
	v_mfma_f32_16x16x32_bf16 v[68:71], v[144:147], v[196:199], v[68:71]
	v_mfma_f32_16x16x32_bf16 v[72:75], v[136:139], v[196:199], v[72:75]
	v_mfma_f32_16x16x32_bf16 v[72:75], v[140:143], v[212:215], v[72:75]
	v_mfma_f32_16x16x32_bf16 v[76:79], v[132:135], v[212:215], v[76:79]
	v_mfma_f32_16x16x32_bf16 v[76:79], v[128:131], v[196:199], v[76:79]
	s_barrier
	s_add_i32 s70, s60, s46
	v_lshl_add_u64 v[200:201], s[68:69], 0, v[148:149]
	s_mov_b32 m0, s70
	ds_read_b128 v[172:175], v207 offset:16384
	ds_read_b128 v[176:179], v207 offset:17408
	ds_read_b128 v[180:183], v207 offset:18432
	ds_read_b128 v[184:187], v207 offset:19456
	ds_read_b128 v[188:191], v207 offset:20480
	ds_read_b128 v[192:195], v207 offset:21504
	ds_read_b128 v[196:199], v207 offset:22528
	ds_read_b128 v[212:215], v207 offset:23552
	global_load_lds_dwordx4 v[200:201], off
	s_add_i32 m0, s70, 0x2000
	v_lshl_add_u64 v[216:217], s[68:69], 0, v[150:151]
	s_add_u32 s68, s68, s10
	s_addc_u32 s69, s69, s11
	s_add_i32 s70, s61, s46
	global_load_lds_dwordx4 v[216:217], off
	v_lshl_add_u64 v[218:219], s[68:69], 0, v[148:149]
	s_mov_b32 m0, s70
	v_lshl_add_u64 v[220:221], s[68:69], 0, v[150:151]
	global_load_lds_dwordx4 v[218:219], off
	s_add_i32 m0, s70, 0x2000
	v_lshl_add_u64 v[222:223], s[6:7], 0, v[148:149]
	global_load_lds_dwordx4 v[220:221], off
	s_mov_b32 m0, s47
	v_lshl_add_u64 v[224:225], s[6:7], 0, v[150:151]
	global_load_lds_dwordx4 v[222:223], off
	s_mov_b32 m0, s48
	s_nop 0
	global_load_lds_dwordx4 v[224:225], off
	s_waitcnt vmcnt(8)
	s_waitcnt lgkmcnt(0)
	s_barrier
	s_waitcnt lgkmcnt(0)
	v_mfma_f32_16x16x32_bf16 v[60:63], v[128:131], v[172:175], v[60:63]
	v_mfma_f32_16x16x32_bf16 v[60:63], v[132:135], v[176:179], v[60:63]
	v_mfma_f32_16x16x32_bf16 v[56:59], v[140:143], v[176:179], v[56:59]
	v_mfma_f32_16x16x32_bf16 v[56:59], v[136:139], v[172:175], v[56:59]
	v_mfma_f32_16x16x32_bf16 v[52:55], v[144:147], v[172:175], v[52:55]
	v_mfma_f32_16x16x32_bf16 v[52:55], v[160:163], v[176:179], v[52:55]
	v_mfma_f32_16x16x32_bf16 v[48:51], v[168:171], v[176:179], v[48:51]
	v_mfma_f32_16x16x32_bf16 v[48:51], v[164:167], v[172:175], v[48:51]
	v_mfma_f32_16x16x32_bf16 v[32:35], v[164:167], v[180:183], v[32:35]
	v_mfma_f32_16x16x32_bf16 v[32:35], v[168:171], v[184:187], v[32:35]
	v_mfma_f32_16x16x32_bf16 v[36:39], v[160:163], v[184:187], v[36:39]
	v_mfma_f32_16x16x32_bf16 v[36:39], v[144:147], v[180:183], v[36:39]
	v_mfma_f32_16x16x32_bf16 v[40:43], v[136:139], v[180:183], v[40:43]
	v_mfma_f32_16x16x32_bf16 v[40:43], v[140:143], v[184:187], v[40:43]
	v_mfma_f32_16x16x32_bf16 v[44:47], v[132:135], v[184:187], v[44:47]
	v_mfma_f32_16x16x32_bf16 v[44:47], v[128:131], v[180:183], v[44:47]
	v_mfma_f32_16x16x32_bf16 v[28:31], v[128:131], v[188:191], v[28:31]
	v_mfma_f32_16x16x32_bf16 v[28:31], v[132:135], v[192:195], v[28:31]
	v_mfma_f32_16x16x32_bf16 v[24:27], v[140:143], v[192:195], v[24:27]
	v_mfma_f32_16x16x32_bf16 v[24:27], v[136:139], v[188:191], v[24:27]
	v_mfma_f32_16x16x32_bf16 v[20:23], v[144:147], v[188:191], v[20:23]
	v_mfma_f32_16x16x32_bf16 v[20:23], v[160:163], v[192:195], v[20:23]
	v_mfma_f32_16x16x32_bf16 v[16:19], v[168:171], v[192:195], v[16:19]
	v_mfma_f32_16x16x32_bf16 v[16:19], v[164:167], v[188:191], v[16:19]
	v_mfma_f32_16x16x32_bf16 v[0:3], v[164:167], v[196:199], v[0:3]
	v_mfma_f32_16x16x32_bf16 v[0:3], v[168:171], v[212:215], v[0:3]
	v_mfma_f32_16x16x32_bf16 v[4:7], v[160:163], v[212:215], v[4:7]
	v_mfma_f32_16x16x32_bf16 v[4:7], v[144:147], v[196:199], v[4:7]
	v_mfma_f32_16x16x32_bf16 v[8:11], v[136:139], v[196:199], v[8:11]
	v_mfma_f32_16x16x32_bf16 v[8:11], v[140:143], v[212:215], v[8:11]
	v_mfma_f32_16x16x32_bf16 v[12:15], v[132:135], v[212:215], v[12:15]
	v_mfma_f32_16x16x32_bf16 v[12:15], v[128:131], v[196:199], v[12:15]
	s_barrier
	s_add_i32 s68, 0, 0x18000
	s_add_i32 s69, 0, 0x1c000
	v_add_u32_e32 v140, s68, v203
	v_add_u32_e32 v168, s69, v203
	ds_read_b128 v[128:131], v140
	ds_read_b128 v[132:135], v140 offset:1024
	ds_read_b128 v[136:139], v140 offset:2048
	ds_read_b128 v[140:143], v140 offset:3072
	ds_read_b128 v[144:147], v168
	ds_read_b128 v[160:163], v168 offset:1024
	ds_read_b128 v[164:167], v168 offset:2048
	ds_read_b128 v[168:171], v168 offset:3072
	s_add_u32 s6, s6, s10
	s_addc_u32 s7, s7, s11
	s_mov_b32 m0, s49
	v_lshl_add_u64 v[226:227], s[6:7], 0, v[148:149]
	ds_read_b128 v[172:175], v207 offset:32768
	ds_read_b128 v[176:179], v207 offset:33792
	ds_read_b128 v[180:183], v207 offset:34816
	ds_read_b128 v[184:187], v207 offset:35840
	ds_read_b128 v[188:191], v207 offset:36864
	ds_read_b128 v[192:195], v207 offset:37888
	ds_read_b128 v[196:199], v207 offset:38912
	ds_read_b128 v[212:215], v207 offset:39936
	global_load_lds_dwordx4 v[226:227], off
	s_mov_b32 m0, s50
	v_lshl_add_u64 v[226:227], s[6:7], 0, v[150:151]
	global_load_lds_dwordx4 v[226:227], off
	s_waitcnt vmcnt(8)
	s_waitcnt lgkmcnt(0)
	s_barrier
	s_waitcnt lgkmcnt(0)
	v_mfma_f32_16x16x32_bf16 v[124:127], v[128:131], v[172:175], v[124:127]
	v_mfma_f32_16x16x32_bf16 v[124:127], v[132:135], v[176:179], v[124:127]
	v_mfma_f32_16x16x32_bf16 v[120:123], v[140:143], v[176:179], v[120:123]
	v_mfma_f32_16x16x32_bf16 v[120:123], v[136:139], v[172:175], v[120:123]
	v_mfma_f32_16x16x32_bf16 v[116:119], v[144:147], v[172:175], v[116:119]
	v_mfma_f32_16x16x32_bf16 v[116:119], v[160:163], v[176:179], v[116:119]
	v_mfma_f32_16x16x32_bf16 v[112:115], v[168:171], v[176:179], v[112:115]
	v_mfma_f32_16x16x32_bf16 v[112:115], v[164:167], v[172:175], v[112:115]
	v_mfma_f32_16x16x32_bf16 v[96:99], v[164:167], v[180:183], v[96:99]
	v_mfma_f32_16x16x32_bf16 v[96:99], v[168:171], v[184:187], v[96:99]
	v_mfma_f32_16x16x32_bf16 v[100:103], v[160:163], v[184:187], v[100:103]
	v_mfma_f32_16x16x32_bf16 v[100:103], v[144:147], v[180:183], v[100:103]
	v_mfma_f32_16x16x32_bf16 v[104:107], v[136:139], v[180:183], v[104:107]
	v_mfma_f32_16x16x32_bf16 v[104:107], v[140:143], v[184:187], v[104:107]
	v_mfma_f32_16x16x32_bf16 v[108:111], v[132:135], v[184:187], v[108:111]
	v_mfma_f32_16x16x32_bf16 v[108:111], v[128:131], v[180:183], v[108:111]
	v_mfma_f32_16x16x32_bf16 v[92:95], v[128:131], v[188:191], v[92:95]
	v_mfma_f32_16x16x32_bf16 v[92:95], v[132:135], v[192:195], v[92:95]
	v_mfma_f32_16x16x32_bf16 v[88:91], v[140:143], v[192:195], v[88:91]
	v_mfma_f32_16x16x32_bf16 v[88:91], v[136:139], v[188:191], v[88:91]
	v_mfma_f32_16x16x32_bf16 v[84:87], v[144:147], v[188:191], v[84:87]
	v_mfma_f32_16x16x32_bf16 v[84:87], v[160:163], v[192:195], v[84:87]
	v_mfma_f32_16x16x32_bf16 v[80:83], v[168:171], v[192:195], v[80:83]
	v_mfma_f32_16x16x32_bf16 v[80:83], v[164:167], v[188:191], v[80:83]
	v_mfma_f32_16x16x32_bf16 v[64:67], v[164:167], v[196:199], v[64:67]
	v_mfma_f32_16x16x32_bf16 v[64:67], v[168:171], v[212:215], v[64:67]
	v_mfma_f32_16x16x32_bf16 v[68:71], v[160:163], v[212:215], v[68:71]
	v_mfma_f32_16x16x32_bf16 v[68:71], v[144:147], v[196:199], v[68:71]
	v_mfma_f32_16x16x32_bf16 v[72:75], v[136:139], v[196:199], v[72:75]
	v_mfma_f32_16x16x32_bf16 v[72:75], v[140:143], v[212:215], v[72:75]
	v_mfma_f32_16x16x32_bf16 v[76:79], v[132:135], v[212:215], v[76:79]
	v_mfma_f32_16x16x32_bf16 v[76:79], v[128:131], v[196:199], v[76:79]
	s_barrier
	s_add_i32 s6, s68, s46
	v_lshl_add_u64 v[200:201], v[200:201], 0, s[20:21]
	s_mov_b32 m0, s6
	ds_read_b128 v[172:175], v207 offset:49152
	ds_read_b128 v[176:179], v207 offset:50176
	ds_read_b128 v[180:183], v207 offset:51200
	ds_read_b128 v[184:187], v207 offset:52224
	ds_read_b128 v[188:191], v207 offset:53248
	ds_read_b128 v[192:195], v207 offset:54272
	ds_read_b128 v[196:199], v207 offset:55296
	ds_read_b128 v[212:215], v207 offset:56320
	global_load_lds_dwordx4 v[200:201], off
	v_lshl_add_u64 v[200:201], v[216:217], 0, s[20:21]
	s_add_i32 m0, s6, 0x2000
	s_add_i32 s6, s69, s46
	global_load_lds_dwordx4 v[200:201], off
	s_mov_b32 m0, s6
	v_lshl_add_u64 v[200:201], v[218:219], 0, s[20:21]
	global_load_lds_dwordx4 v[200:201], off
	s_add_i32 m0, s6, 0x2000
	v_lshl_add_u64 v[200:201], v[220:221], 0, s[20:21]
	global_load_lds_dwordx4 v[200:201], off
	s_mov_b32 m0, s54
	v_lshl_add_u64 v[200:201], v[222:223], 0, s[20:21]
	global_load_lds_dwordx4 v[200:201], off
	s_mov_b32 m0, s55
	v_lshl_add_u64 v[200:201], v[224:225], 0, s[20:21]
	global_load_lds_dwordx4 v[200:201], off
	s_waitcnt vmcnt(8)
	s_waitcnt lgkmcnt(0)
	s_barrier
	s_waitcnt lgkmcnt(0)
	v_mfma_f32_16x16x32_bf16 v[60:63], v[128:131], v[172:175], v[60:63]
	v_mfma_f32_16x16x32_bf16 v[60:63], v[132:135], v[176:179], v[60:63]
	v_mfma_f32_16x16x32_bf16 v[56:59], v[140:143], v[176:179], v[56:59]
	v_mfma_f32_16x16x32_bf16 v[56:59], v[136:139], v[172:175], v[56:59]
	v_mfma_f32_16x16x32_bf16 v[52:55], v[144:147], v[172:175], v[52:55]
	v_mfma_f32_16x16x32_bf16 v[52:55], v[160:163], v[176:179], v[52:55]
	v_mfma_f32_16x16x32_bf16 v[48:51], v[168:171], v[176:179], v[48:51]
	v_mfma_f32_16x16x32_bf16 v[48:51], v[164:167], v[172:175], v[48:51]
	v_mfma_f32_16x16x32_bf16 v[32:35], v[164:167], v[180:183], v[32:35]
	v_mfma_f32_16x16x32_bf16 v[32:35], v[168:171], v[184:187], v[32:35]
	v_mfma_f32_16x16x32_bf16 v[36:39], v[160:163], v[184:187], v[36:39]
	v_mfma_f32_16x16x32_bf16 v[36:39], v[144:147], v[180:183], v[36:39]
	v_mfma_f32_16x16x32_bf16 v[40:43], v[136:139], v[180:183], v[40:43]
	v_mfma_f32_16x16x32_bf16 v[40:43], v[140:143], v[184:187], v[40:43]
	v_mfma_f32_16x16x32_bf16 v[44:47], v[132:135], v[184:187], v[44:47]
	v_mfma_f32_16x16x32_bf16 v[44:47], v[128:131], v[180:183], v[44:47]
	v_mfma_f32_16x16x32_bf16 v[28:31], v[128:131], v[188:191], v[28:31]
	v_mfma_f32_16x16x32_bf16 v[28:31], v[132:135], v[192:195], v[28:31]
	v_mfma_f32_16x16x32_bf16 v[24:27], v[140:143], v[192:195], v[24:27]
	v_mfma_f32_16x16x32_bf16 v[24:27], v[136:139], v[188:191], v[24:27]
	v_mfma_f32_16x16x32_bf16 v[20:23], v[144:147], v[188:191], v[20:23]
	v_mfma_f32_16x16x32_bf16 v[20:23], v[160:163], v[192:195], v[20:23]
	v_mfma_f32_16x16x32_bf16 v[16:19], v[168:171], v[192:195], v[16:19]
	v_mfma_f32_16x16x32_bf16 v[16:19], v[164:167], v[188:191], v[16:19]
	v_mfma_f32_16x16x32_bf16 v[0:3], v[164:167], v[196:199], v[0:3]
	v_mfma_f32_16x16x32_bf16 v[0:3], v[168:171], v[212:215], v[0:3]
	v_mfma_f32_16x16x32_bf16 v[4:7], v[160:163], v[212:215], v[4:7]
	v_mfma_f32_16x16x32_bf16 v[4:7], v[144:147], v[196:199], v[4:7]
	v_mfma_f32_16x16x32_bf16 v[8:11], v[136:139], v[196:199], v[8:11]
	v_mfma_f32_16x16x32_bf16 v[8:11], v[140:143], v[212:215], v[8:11]
	v_mfma_f32_16x16x32_bf16 v[12:15], v[132:135], v[212:215], v[12:15]
	v_mfma_f32_16x16x32_bf16 v[12:15], v[128:131], v[196:199], v[12:15]
	s_add_u32 s0, s0, 0x100
	s_addc_u32 s1, s1, 0
	s_add_u32 s38, s38, 0x100
	s_addc_u32 s39, s39, 0
	s_cmp_ge_i32 s41, s56
	s_mov_b32 s6, s41
	s_barrier
	s_cbranch_scc0 .LBB0_1159
